# SGU group loop: epilogue u/g_c lines touched at the head of each group iteration (L2 prefetch)
# baseline (speedup 1.0000x reference)
; __device__ __forceinline__ unsigned pk2(float lo, float hi) { f32x2 v = {lo, hi}; bf16x2_t b = __builtin_convertvector(v, bf16x2_t); return __builtin_bit_cast(unsigned, b); }
; #define MFMA32(a, b, c) __builtin_amdgcn_mfma_f32_32x32x16_bf16((a), (b), (c), 0, 0, 0)
; __device__ __forceinline__ void unpack8(const u32x4 w, float* v) { v[0] = bflo(w.x); v[1] = bfhi(w.x); v[2] = bflo(w.y); v[3] = bfhi(w.y); v[4] = bflo(w.z); v[5] = bfhi(w.z); v[6] = bflo(w.w); v[7] = bfhi(w.w); }
; template <int tbA, int tbB> ...
;     for (int gi = 0; gi < 4; ++gi) {
;         const int g = gh * 4 + gi;
;         const int ch = g * 128 + cb * 32 + r;
;         const float gg = lng[ch], bb = lnb[ch];
;         const bf16_t* ap = VCT + (size_t)ch * PT + tok0 + 8 * hh;
;         const bf16_t* wp = Wbf + (size_t)g * 16384 + 8 * hh;
;         constexpr int NSB = (tbB + 1) * 2, NSA = (tbA + 1) * 2;
;         int so = 0; asm volatile("" : "+v"(so));
;         u32x4 raw[NSB]; bf16x8 wB[NSB], wA[NSA];
; #pragma unroll
;         for (int k = 0; k < NSB; ++k) { raw[k] = *(const u32x4*)(ap + 16 * k); wB[k] = *(const bf16x8*)(wp + (size_t)(tbB * 32 + r) * 128 + 16 * k); }
; #pragma unroll
;         for (int k = 0; k < NSA; ++k) wA[k] = *(const bf16x8*)(wp + (size_t)(tbA * 32 + r) * 128 + 16 * k);
;         f32x16 accA, accB;
; #pragma unroll
;         for (int i = 0; i < 16; ++i) { accA[i] = 0.f; accB[i] = 0.f; }
; #pragma unroll
;         for (int k = 0; k < NSB; ++k) {
;             float v[8]; unpack8(raw[k], v);
; #pragma unroll
;             for (int jj = 0; jj < 8; ++jj) { const float mean = stat[(16 * k + 8 * hh + jj) * 2 + so], rstd = stat[(16 * k + 8 * hh + jj) * 2 + 1 + so]; v[jj] = (v[jj] - mean) * rstd * gg + bb; }
;             u32x4 af; af.x = pk2(v[0], v[1]); af.y = pk2(v[2], v[3]); af.z = pk2(v[4], v[5]); af.w = pk2(v[6], v[7]);
;             accB = MFMA32(__builtin_bit_cast(bf16x8, af), wB[k], accB);
;     ...
;                 const int t = (lane >> 2) + 16 * i, ck = lane & 3;
;                 const size_t a = (size_t)(tok0 + tb * 32 + t) * DH + g * 128 + cb * 32 + ck * 8;
;                 const u32x4 uu = *(const u32x4*)(U + a), gc = *(const u32x4*)(GC + a);
.LBB0_229:
	v_lshl_add_u64 v[8:9], v[52:53], 0, v[148:149]
	v_mov_b32_e32 v14, v133
	global_load_dword v60, v[56:57], off
	global_load_dword v62, v[54:55], off
	global_load_dwordx4 v[0:3], v[8:9], off offset:-96
	v_lshl_add_u64 v[10:11], v[58:59], 0, v[148:149]
	v_add_co_u32_e32 v12, vcc, s95, v10
	v_lshl_add_u32 v74, v14, 2, v158
	s_nop 0
	v_addc_co_u32_e32 v13, vcc, 0, v11, vcc
	v_add_co_u32_e32 v20, vcc, s96, v10
	global_load_dwordx4 v[4:7], v[12:13], off
	global_load_dwordx4 v[68:71], v[8:9], off offset:-64
	global_load_dwordx4 v[76:79], v[12:13], off offset:32
	global_load_dwordx4 v[80:83], v[8:9], off offset:-32
	global_load_dwordx4 v[84:87], v[12:13], off offset:64
	global_load_dwordx4 v[88:91], v[8:9], off
	global_load_dwordx4 v[92:95], v[12:13], off offset:96
	global_load_dwordx4 v[44:47], v[8:9], off offset:32
	global_load_dwordx4 v[40:43], v[12:13], off offset:128
	global_load_dwordx4 v[36:39], v[8:9], off offset:64
	global_load_dwordx4 v[32:35], v[12:13], off offset:160
	v_addc_co_u32_e32 v21, vcc, 0, v11, vcc
	v_add_u32_e32 v12, 0x2000, v74
	global_load_dwordx4 v[96:99], v[20:21], off offset:32
	global_load_dwordx4 v[100:103], v[20:21], off offset:64
	global_load_dwordx4 v[104:107], v[20:21], off offset:96
	v_add_u32_e32 v110, 0x2080, v74
	v_lshl_add_u64 v[58:59], v[58:59], 0, s[58:59]
	v_lshl_add_u64 v[52:53], v[52:53], 0, s[60:61]
	v_lshl_add_u64 v[54:55], v[54:55], 0, s[62:63]
	v_lshl_add_u64 v[56:57], v[56:57], 0, s[62:63]
	v_add_u32_e32 v120, s8, v66
	v_add_u32_e32 v122, 0xfa008000, v120
	v_mov_b32_e32 v123, 0
	v_lshlrev_b64 v[122:123], 1, v[122:123]
	v_lshl_add_u64 v[124:125], s[30:31], 0, v[122:123]
	global_load_dword v126, v[124:125], off
	v_lshl_add_u64 v[124:125], s[34:35], 0, v[122:123]
	global_load_dword v126, v[124:125], off
	v_add_u32_e32 v122, 0xfa00c000, v120
	v_mov_b32_e32 v123, 0
	v_lshlrev_b64 v[122:123], 1, v[122:123]
	v_lshl_add_u64 v[124:125], s[30:31], 0, v[122:123]
	global_load_dword v126, v[124:125], off
	v_lshl_add_u64 v[124:125], s[34:35], 0, v[122:123]
	global_load_dword v126, v[124:125], off
	v_add_u32_e32 v122, 0xfa010000, v120
	v_mov_b32_e32 v123, 0
	v_lshlrev_b64 v[122:123], 1, v[122:123]
	v_lshl_add_u64 v[124:125], s[30:31], 0, v[122:123]
	global_load_dword v126, v[124:125], off
	v_lshl_add_u64 v[124:125], s[34:35], 0, v[122:123]
	global_load_dword v126, v[124:125], off
	v_add_u32_e32 v122, 0xfa014000, v120
	v_mov_b32_e32 v123, 0
	v_lshlrev_b64 v[122:123], 1, v[122:123]
	v_lshl_add_u64 v[124:125], s[30:31], 0, v[122:123]
	global_load_dword v126, v[124:125], off
	v_lshl_add_u64 v[124:125], s[34:35], 0, v[122:123]
	global_load_dword v126, v[124:125], off
	s_waitcnt vmcnt(20)
	v_lshlrev_b32_e32 v72, 16, v68
	v_lshlrev_b32_e32 v8, 16, v0
	v_and_b32_e32 v9, 0xffff0000, v0
	v_add_u32_e32 v0, 0x2008, v74
	ds_read2_b32 v[10:11], v0 offset1:1
	ds_read2_b32 v[12:13], v12 offset1:1
	v_lshlrev_b32_e32 v0, 16, v1
	v_and_b32_e32 v1, 0xffff0000, v1
	v_and_b32_e32 v73, 0xffff0000, v68
	s_waitcnt lgkmcnt(1)
	v_mov_b32_e32 v15, v10
	s_waitcnt lgkmcnt(0)
	v_mov_b32_e32 v14, v12
	v_pk_add_f32 v[8:9], v[8:9], v[14:15] neg_lo:[0,1] neg_hi:[0,1]
	v_mov_b32_e32 v10, v13
	v_pk_mul_f32 v[8:9], v[8:9], v[10:11]
	v_add_u32_e32 v12, 0x2010, v74
	v_add_u32_e32 v10, 0x2018, v74
	ds_read2_b32 v[10:11], v10 offset1:1
	ds_read2_b32 v[12:13], v12 offset1:1
	v_add_u32_e32 v68, 0x2088, v74
	v_pk_fma_f32 v[8:9], v[60:61], v[8:9], v[62:63] op_sel_hi:[0,1,0]
	s_waitcnt lgkmcnt(1)
	v_mov_b32_e32 v15, v10
	s_waitcnt lgkmcnt(0)
	v_mov_b32_e32 v14, v12
	v_pk_add_f32 v[0:1], v[0:1], v[14:15] neg_lo:[0,1] neg_hi:[0,1]
	v_mov_b32_e32 v10, v13
	v_pk_mul_f32 v[0:1], v[0:1], v[10:11]
	v_add_u32_e32 v14, 0x2020, v74
	v_lshlrev_b32_e32 v10, 16, v2
	v_and_b32_e32 v11, 0xffff0000, v2
	v_add_u32_e32 v2, 0x2028, v74
	ds_read2_b32 v[12:13], v2 offset1:1
	ds_read2_b32 v[14:15], v14 offset1:1
	v_lshlrev_b32_e32 v2, 16, v3
	v_and_b32_e32 v3, 0xffff0000, v3
	v_pk_fma_f32 v[0:1], v[60:61], v[0:1], v[62:63] op_sel_hi:[0,1,0]
	s_waitcnt lgkmcnt(1)
	v_mov_b32_e32 v17, v12
	s_waitcnt lgkmcnt(0)
	v_mov_b32_e32 v16, v14
	v_pk_add_f32 v[10:11], v[10:11], v[16:17] neg_lo:[0,1] neg_hi:[0,1]
	v_mov_b32_e32 v12, v15
	v_pk_mul_f32 v[10:11], v[10:11], v[12:13]
	v_add_u32_e32 v14, 0x2030, v74
	v_add_u32_e32 v12, 0x2038, v74
	ds_read2_b32 v[12:13], v12 offset1:1
	ds_read2_b32 v[14:15], v14 offset1:1
	global_load_dwordx4 v[20:23], v[20:21], off
	ds_read2_b32 v[108:109], v68 offset1:1
	ds_read2_b32 v[110:111], v110 offset1:1
	v_lshlrev_b32_e32 v68, 16, v69
	v_and_b32_e32 v69, 0xffff0000, v69
	s_waitcnt lgkmcnt(2)
	v_mov_b32_e32 v16, v14
	s_waitcnt lgkmcnt(1)
	v_mov_b32_e32 v113, v108
	s_waitcnt lgkmcnt(0)
	v_mov_b32_e32 v112, v110
	v_pk_add_f32 v[72:73], v[72:73], v[112:113] neg_lo:[0,1] neg_hi:[0,1]
	v_mov_b32_e32 v108, v111
	v_pk_mul_f32 v[72:73], v[72:73], v[108:109]
	v_add_u32_e32 v110, 0x2090, v74
	v_add_u32_e32 v108, 0x2098, v74
	ds_read2_b32 v[108:109], v108 offset1:1
	ds_read2_b32 v[110:111], v110 offset1:1
	v_mov_b32_e32 v17, v12
	v_pk_add_f32 v[2:3], v[2:3], v[16:17] neg_lo:[0,1] neg_hi:[0,1]
	v_mov_b32_e32 v12, v15
	s_waitcnt lgkmcnt(1)
	v_mov_b32_e32 v113, v108
	s_waitcnt lgkmcnt(0)
	v_mov_b32_e32 v112, v110
	v_pk_add_f32 v[68:69], v[68:69], v[112:113] neg_lo:[0,1] neg_hi:[0,1]
	v_mov_b32_e32 v108, v111
	v_pk_mul_f32 v[68:69], v[68:69], v[108:109]
	v_add_u32_e32 v112, 0x20a0, v74
	v_pk_fma_f32 v[108:109], v[60:61], v[68:69], v[62:63] op_sel_hi:[0,1,0]
	v_lshlrev_b32_e32 v68, 16, v70
	v_and_b32_e32 v69, 0xffff0000, v70
	v_add_u32_e32 v70, 0x20a8, v74
	ds_read2_b32 v[110:111], v70 offset1:1
	ds_read2_b32 v[112:113], v112 offset1:1
	v_pk_mul_f32 v[2:3], v[2:3], v[12:13]
	v_add_u32_e32 v70, 0x20b8, v74
	v_pk_fma_f32 v[10:11], v[60:61], v[10:11], v[62:63] op_sel_hi:[0,1,0]
	s_waitcnt lgkmcnt(1)
; __device__ __forceinline__ unsigned pk2(float lo, float hi) { f32x2 v = {lo, hi}; bf16x2_t b = __builtin_convertvector(v, bf16x2_t); return __builtin_bit_cast(unsigned, b); }
; #define MFMA32(a, b, c) __builtin_amdgcn_mfma_f32_32x32x16_bf16((a), (b), (c), 0, 0, 0)
; __device__ __forceinline__ void unpack8(const u32x4 w, float* v) { v[0] = bflo(w.x); v[1] = bfhi(w.x); v[2] = bflo(w.y); v[3] = bfhi(w.y); v[4] = bflo(w.z); v[5] = bfhi(w.z); v[6] = bflo(w.w); v[7] = bfhi(w.w); }
; template <int tbA, int tbB> ...
;     ...
;         for (int k = 0; k < NSB; ++k) {
;             float v[8]; unpack8(raw[k], v);
; #pragma unroll
;             for (int jj = 0; jj < 8; ++jj) { const float mean = stat[(16 * k + 8 * hh + jj) * 2 + so], rstd = stat[(16 * k + 8 * hh + jj) * 2 + 1 + so]; v[jj] = (v[jj] - mean) * rstd * gg + bb; }
;             u32x4 af; af.x = pk2(v[0], v[1]); af.y = pk2(v[2], v[3]); af.z = pk2(v[4], v[5]); af.w = pk2(v[6], v[7]);
;             accB = MFMA32(__builtin_bit_cast(bf16x8, af), wB[k], accB);
;             if (k < NSA) accA = MFMA32(__builtin_bit_cast(bf16x8, af), wA[k < NSA ? k : 0], accA);
	v_mov_b32_e32 v115, v110
	s_waitcnt lgkmcnt(0)
	v_mov_b32_e32 v114, v112
	v_pk_add_f32 v[68:69], v[68:69], v[114:115] neg_lo:[0,1] neg_hi:[0,1]
	v_mov_b32_e32 v110, v113
	v_pk_mul_f32 v[68:69], v[68:69], v[110:111]
	v_add_u32_e32 v112, 0x20b0, v74
	v_pk_fma_f32 v[2:3], v[60:61], v[2:3], v[62:63] op_sel_hi:[0,1,0]
	v_pk_fma_f32 v[110:111], v[60:61], v[68:69], v[62:63] op_sel_hi:[0,1,0]
	v_lshlrev_b32_e32 v68, 16, v71
	v_and_b32_e32 v69, 0xffff0000, v71
	ds_read2_b32 v[70:71], v70 offset1:1
	ds_read2_b32 v[112:113], v112 offset1:1
	v_cvt_pk_bf16_f32 v16, v8, v9
	v_cvt_pk_bf16_f32 v17, v0, v1
	v_cvt_pk_bf16_f32 v18, v10, v11
	v_cvt_pk_bf16_f32 v19, v2, v3
	s_waitcnt lgkmcnt(0)
	v_mov_b32_e32 v114, v112
	v_mov_b32_e32 v115, v70
	v_mfma_f32_32x32x16_bf16 v[0:15], v[16:19], v[4:7], 0
	v_add_f32_e64 v68, v68, -v114
	v_add_f32_e64 v69, v69, -v115
	v_mov_b32_e32 v70, v113
	v_mul_f32_e64 v68, v68, v70
	v_mul_f32_e64 v69, v69, v71
	v_pk_fma_f32 v[72:73], v[60:61], v[72:73], v[62:63] op_sel_hi:[0,1,0]
	v_pk_fma_f32 v[112:113], v[60:61], v[68:69], v[62:63] op_sel_hi:[0,1,0]
	v_cvt_pk_bf16_f32 v68, v72, v73
	v_cvt_pk_bf16_f32 v69, v108, v109
	v_cvt_pk_bf16_f32 v70, v110, v111
	v_cvt_pk_bf16_f32 v71, v112, v113
	v_add_u32_e32 v72, 0x2100, v74
	s_waitcnt vmcnt(0)
	v_mfma_f32_32x32x16_bf16 v[16:31], v[16:19], v[20:23], 0
	v_mfma_f32_32x32x16_bf16 v[0:15], v[68:71], v[76:79], v[0:15]
	v_mfma_f32_32x32x16_bf16 v[16:31], v[68:71], v[96:99], v[16:31]
	v_add_u32_e32 v70, 0x2108, v74
	ds_read2_b32 v[70:71], v70 offset1:1
	ds_read2_b32 v[72:73], v72 offset1:1
	v_lshlrev_b32_e32 v68, 16, v80
	v_and_b32_e32 v69, 0xffff0000, v80
	s_waitcnt lgkmcnt(1)
	v_mov_b32_e32 v77, v70
	s_waitcnt lgkmcnt(0)
	v_mov_b32_e32 v76, v72
	v_pk_add_f32 v[68:69], v[68:69], v[76:77] neg_lo:[0,1] neg_hi:[0,1]
	v_add_u32_e32 v76, 0x2110, v74
	v_add_u32_e32 v72, 0x2118, v74
	v_mov_b32_e32 v70, v73
	ds_read2_b32 v[72:73], v72 offset1:1
	ds_read2_b32 v[76:77], v76 offset1:1
	v_pk_mul_f32 v[68:69], v[68:69], v[70:71]
	v_lshlrev_b32_e32 v70, 16, v81
	v_and_b32_e32 v71, 0xffff0000, v81
	s_waitcnt lgkmcnt(1)
	v_mov_b32_e32 v79, v72
	s_waitcnt lgkmcnt(0)
	v_mov_b32_e32 v78, v76
	v_pk_add_f32 v[70:71], v[70:71], v[78:79] neg_lo:[0,1] neg_hi:[0,1]
	v_add_u32_e32 v78, 0x2120, v74
	v_add_u32_e32 v76, 0x2128, v74
	v_mov_b32_e32 v72, v77
	ds_read2_b32 v[76:77], v76 offset1:1
	ds_read2_b32 v[78:79], v78 offset1:1
	v_pk_mul_f32 v[70:71], v[70:71], v[72:73]
	v_lshlrev_b32_e32 v72, 16, v82
	v_and_b32_e32 v73, 0xffff0000, v82
	s_waitcnt lgkmcnt(1)
	v_mov_b32_e32 v81, v76
	s_waitcnt lgkmcnt(0)
	v_mov_b32_e32 v80, v78
	v_pk_add_f32 v[72:73], v[72:73], v[80:81] neg_lo:[0,1] neg_hi:[0,1]
	v_add_u32_e32 v80, 0x2130, v74
	v_add_u32_e32 v78, 0x2138, v74
	v_mov_b32_e32 v76, v79
	ds_read2_b32 v[78:79], v78 offset1:1
	ds_read2_b32 v[80:81], v80 offset1:1
	v_pk_mul_f32 v[72:73], v[72:73], v[76:77]
	v_lshlrev_b32_e32 v76, 16, v83
	v_and_b32_e32 v77, 0xffff0000, v83
	s_waitcnt lgkmcnt(1)
	v_mov_b32_e32 v83, v78
	s_waitcnt lgkmcnt(0)
	v_mov_b32_e32 v82, v80
	v_pk_add_f32 v[76:77], v[76:77], v[82:83] neg_lo:[0,1] neg_hi:[0,1]
	v_mov_b32_e32 v78, v81
	v_pk_mul_f32 v[76:77], v[76:77], v[78:79]
	v_pk_fma_f32 v[68:69], v[60:61], v[68:69], v[62:63] op_sel_hi:[0,1,0]
	v_pk_fma_f32 v[70:71], v[60:61], v[70:71], v[62:63] op_sel_hi:[0,1,0]
	v_pk_fma_f32 v[72:73], v[60:61], v[72:73], v[62:63] op_sel_hi:[0,1,0]
	v_pk_fma_f32 v[76:77], v[60:61], v[76:77], v[62:63] op_sel_hi:[0,1,0]
	v_cvt_pk_bf16_f32 v68, v68, v69
	v_cvt_pk_bf16_f32 v69, v70, v71
	v_cvt_pk_bf16_f32 v70, v72, v73
	v_cvt_pk_bf16_f32 v71, v76, v77
	v_add_u32_e32 v72, 0x2180, v74
	s_nop 0
	v_mfma_f32_32x32x16_bf16 v[0:15], v[68:71], v[84:87], v[0:15]
	v_mfma_f32_32x32x16_bf16 v[16:31], v[68:71], v[100:103], v[16:31]
	v_add_u32_e32 v70, 0x2188, v74
	ds_read2_b32 v[70:71], v70 offset1:1
	ds_read2_b32 v[72:73], v72 offset1:1
	v_lshlrev_b32_e32 v68, 16, v88
	v_and_b32_e32 v69, 0xffff0000, v88
	s_waitcnt lgkmcnt(1)
	v_mov_b32_e32 v77, v70
	s_waitcnt lgkmcnt(0)
	v_mov_b32_e32 v76, v72
	v_pk_add_f32 v[68:69], v[68:69], v[76:77] neg_lo:[0,1] neg_hi:[0,1]
	v_add_u32_e32 v76, 0x2190, v74
	v_add_u32_e32 v72, 0x2198, v74
	v_mov_b32_e32 v70, v73
	ds_read2_b32 v[72:73], v72 offset1:1
	ds_read2_b32 v[76:77], v76 offset1:1
	v_pk_mul_f32 v[68:69], v[68:69], v[70:71]
	v_lshlrev_b32_e32 v70, 16, v89
	v_and_b32_e32 v71, 0xffff0000, v89
	s_waitcnt lgkmcnt(1)
	v_mov_b32_e32 v79, v72
	s_waitcnt lgkmcnt(0)
	v_mov_b32_e32 v78, v76
	v_pk_add_f32 v[70:71], v[70:71], v[78:79] neg_lo:[0,1] neg_hi:[0,1]
	v_add_u32_e32 v78, 0x21a0, v74
	v_add_u32_e32 v76, 0x21a8, v74
	v_mov_b32_e32 v72, v77
	ds_read2_b32 v[76:77], v76 offset1:1
	ds_read2_b32 v[78:79], v78 offset1:1
	v_pk_mul_f32 v[70:71], v[70:71], v[72:73]
	v_lshlrev_b32_e32 v72, 16, v90
	v_and_b32_e32 v73, 0xffff0000, v90
	s_waitcnt lgkmcnt(1)
	v_mov_b32_e32 v81, v76
	s_waitcnt lgkmcnt(0)
	v_mov_b32_e32 v80, v78
	v_pk_add_f32 v[72:73], v[72:73], v[80:81] neg_lo:[0,1] neg_hi:[0,1]
	v_add_u32_e32 v80, 0x21b0, v74
	v_add_u32_e32 v78, 0x21b8, v74
	v_mov_b32_e32 v76, v79
	ds_read2_b32 v[78:79], v78 offset1:1
	ds_read2_b32 v[80:81], v80 offset1:1
	v_pk_mul_f32 v[72:73], v[72:73], v[76:77]
	v_lshlrev_b32_e32 v76, 16, v91
	v_and_b32_e32 v77, 0xffff0000, v91
	s_waitcnt lgkmcnt(1)
	v_mov_b32_e32 v83, v78
	s_waitcnt lgkmcnt(0)
; __device__ __forceinline__ unsigned pk2(float lo, float hi) { f32x2 v = {lo, hi}; bf16x2_t b = __builtin_convertvector(v, bf16x2_t); return __builtin_bit_cast(unsigned, b); }
; #define MFMA32(a, b, c) __builtin_amdgcn_mfma_f32_32x32x16_bf16((a), (b), (c), 0, 0, 0)
; __device__ __forceinline__ void unpack8(const u32x4 w, float* v) { v[0] = bflo(w.x); v[1] = bfhi(w.x); v[2] = bflo(w.y); v[3] = bfhi(w.y); v[4] = bflo(w.z); v[5] = bfhi(w.z); v[6] = bflo(w.w); v[7] = bfhi(w.w); }
; template <int tbA, int tbB> ...
;     ...
;         for (int k = 0; k < NSB; ++k) {
;             float v[8]; unpack8(raw[k], v);
; #pragma unroll
;             for (int jj = 0; jj < 8; ++jj) { const float mean = stat[(16 * k + 8 * hh + jj) * 2 + so], rstd = stat[(16 * k + 8 * hh + jj) * 2 + 1 + so]; v[jj] = (v[jj] - mean) * rstd * gg + bb; }
;             u32x4 af; af.x = pk2(v[0], v[1]); af.y = pk2(v[2], v[3]); af.z = pk2(v[4], v[5]); af.w = pk2(v[6], v[7]);
;             accB = MFMA32(__builtin_bit_cast(bf16x8, af), wB[k], accB);
;             if (k < NSA) accA = MFMA32(__builtin_bit_cast(bf16x8, af), wA[k < NSA ? k : 0], accA);
;         }
; #pragma unroll
;         for (int which = 0; which < 2; ++which) {
;             const int tb = which ? tbB : tbA; const f32x16& acc = which ? accB : accA;
;             const float sbv = spb[g * 128 + tb * 32 + r];
	v_mov_b32_e32 v82, v80
	v_pk_add_f32 v[76:77], v[76:77], v[82:83] neg_lo:[0,1] neg_hi:[0,1]
	v_mov_b32_e32 v78, v81
	v_pk_mul_f32 v[76:77], v[76:77], v[78:79]
	v_pk_fma_f32 v[68:69], v[60:61], v[68:69], v[62:63] op_sel_hi:[0,1,0]
	v_pk_fma_f32 v[70:71], v[60:61], v[70:71], v[62:63] op_sel_hi:[0,1,0]
	v_pk_fma_f32 v[72:73], v[60:61], v[72:73], v[62:63] op_sel_hi:[0,1,0]
	v_pk_fma_f32 v[76:77], v[60:61], v[76:77], v[62:63] op_sel_hi:[0,1,0]
	v_cvt_pk_bf16_f32 v68, v68, v69
	v_cvt_pk_bf16_f32 v69, v70, v71
	v_cvt_pk_bf16_f32 v70, v72, v73
	v_cvt_pk_bf16_f32 v71, v76, v77
	v_add_u32_e32 v72, 0x2200, v74
	s_nop 0
	v_mfma_f32_32x32x16_bf16 v[0:15], v[68:71], v[92:95], v[0:15]
	v_mfma_f32_32x32x16_bf16 v[16:31], v[68:71], v[104:107], v[16:31]
	v_lshlrev_b32_e32 v68, 16, v44
	v_and_b32_e32 v69, 0xffff0000, v44
	v_add_u32_e32 v44, 0x2208, v74
	ds_read2_b32 v[70:71], v44 offset1:1
	ds_read2_b32 v[72:73], v72 offset1:1
	v_lshlrev_b32_e32 v44, 16, v45
	v_and_b32_e32 v45, 0xffff0000, v45
	s_waitcnt lgkmcnt(1)
	v_mov_b32_e32 v77, v70
	s_waitcnt lgkmcnt(0)
	v_mov_b32_e32 v76, v72
	v_pk_add_f32 v[68:69], v[68:69], v[76:77] neg_lo:[0,1] neg_hi:[0,1]
	v_mov_b32_e32 v70, v73
	v_pk_mul_f32 v[68:69], v[68:69], v[70:71]
	v_add_u32_e32 v72, 0x2210, v74
	v_add_u32_e32 v70, 0x2218, v74
	ds_read2_b32 v[70:71], v70 offset1:1
	ds_read2_b32 v[72:73], v72 offset1:1
	v_pk_fma_f32 v[68:69], v[60:61], v[68:69], v[62:63] op_sel_hi:[0,1,0]
	s_waitcnt lgkmcnt(1)
	v_mov_b32_e32 v77, v70
	s_waitcnt lgkmcnt(0)
	v_mov_b32_e32 v76, v72
	v_pk_add_f32 v[44:45], v[44:45], v[76:77] neg_lo:[0,1] neg_hi:[0,1]
	v_mov_b32_e32 v70, v73
	v_pk_mul_f32 v[44:45], v[44:45], v[70:71]
	v_add_u32_e32 v76, 0x2220, v74
	v_pk_fma_f32 v[70:71], v[60:61], v[44:45], v[62:63] op_sel_hi:[0,1,0]
	v_lshlrev_b32_e32 v44, 16, v46
	v_and_b32_e32 v45, 0xffff0000, v46
	v_add_u32_e32 v46, 0x2228, v74
	ds_read2_b32 v[72:73], v46 offset1:1
	ds_read2_b32 v[76:77], v76 offset1:1
	v_add_u32_e32 v46, 0x2238, v74
	s_waitcnt lgkmcnt(1)
	v_mov_b32_e32 v79, v72
	s_waitcnt lgkmcnt(0)
	v_mov_b32_e32 v78, v76
	v_pk_add_f32 v[44:45], v[44:45], v[78:79] neg_lo:[0,1] neg_hi:[0,1]
	v_mov_b32_e32 v72, v77
	v_pk_mul_f32 v[44:45], v[44:45], v[72:73]
	v_add_u32_e32 v76, 0x2230, v74
	v_pk_fma_f32 v[72:73], v[60:61], v[44:45], v[62:63] op_sel_hi:[0,1,0]
	v_lshlrev_b32_e32 v44, 16, v47
	v_and_b32_e32 v45, 0xffff0000, v47
	ds_read2_b32 v[46:47], v46 offset1:1
	ds_read2_b32 v[76:77], v76 offset1:1
	s_waitcnt lgkmcnt(1)
	v_mov_b32_e32 v79, v46
	s_waitcnt lgkmcnt(0)
	v_mov_b32_e32 v78, v76
	v_pk_add_f32 v[44:45], v[44:45], v[78:79] neg_lo:[0,1] neg_hi:[0,1]
	v_mov_b32_e32 v46, v77
	v_pk_mul_f32 v[44:45], v[44:45], v[46:47]
	v_cvt_pk_bf16_f32 v46, v72, v73
	v_pk_fma_f32 v[76:77], v[60:61], v[44:45], v[62:63] op_sel_hi:[0,1,0]
	v_cvt_pk_bf16_f32 v44, v68, v69
	v_cvt_pk_bf16_f32 v45, v70, v71
	v_cvt_pk_bf16_f32 v47, v76, v77
	s_nop 1
	v_mfma_f32_32x32x16_bf16 v[0:15], v[44:47], v[40:43], v[0:15]
	v_add_u32_e32 v44, 0x2280, v74
	v_lshlrev_b32_e32 v40, 16, v36
	v_and_b32_e32 v41, 0xffff0000, v36
	v_add_u32_e32 v36, 0x2288, v74
	ds_read2_b32 v[42:43], v36 offset1:1
	ds_read2_b32 v[44:45], v44 offset1:1
	v_lshlrev_b32_e32 v36, 16, v37
	v_and_b32_e32 v37, 0xffff0000, v37
	s_waitcnt lgkmcnt(1)
	v_mov_b32_e32 v47, v42
	s_waitcnt lgkmcnt(0)
	v_mov_b32_e32 v46, v44
	v_pk_add_f32 v[40:41], v[40:41], v[46:47] neg_lo:[0,1] neg_hi:[0,1]
	v_mov_b32_e32 v42, v45
	v_pk_mul_f32 v[40:41], v[40:41], v[42:43]
	v_add_u32_e32 v44, 0x2290, v74
	v_add_u32_e32 v42, 0x2298, v74
	ds_read2_b32 v[42:43], v42 offset1:1
	ds_read2_b32 v[44:45], v44 offset1:1
	v_pk_fma_f32 v[40:41], v[60:61], v[40:41], v[62:63] op_sel_hi:[0,1,0]
	s_waitcnt lgkmcnt(1)
	v_mov_b32_e32 v47, v42
	s_waitcnt lgkmcnt(0)
	v_mov_b32_e32 v46, v44
	v_pk_add_f32 v[36:37], v[36:37], v[46:47] neg_lo:[0,1] neg_hi:[0,1]
	v_mov_b32_e32 v42, v45
	v_pk_mul_f32 v[36:37], v[36:37], v[42:43]
	v_add_u32_e32 v46, 0x22a0, v74
	v_pk_fma_f32 v[42:43], v[60:61], v[36:37], v[62:63] op_sel_hi:[0,1,0]
	v_lshlrev_b32_e32 v36, 16, v38
	v_and_b32_e32 v37, 0xffff0000, v38
	v_add_u32_e32 v38, 0x22a8, v74
	ds_read2_b32 v[44:45], v38 offset1:1
	ds_read2_b32 v[46:47], v46 offset1:1
	v_add_u32_e32 v38, 0x22b8, v74
	s_waitcnt lgkmcnt(1)
	v_mov_b32_e32 v69, v44
	s_waitcnt lgkmcnt(0)
	v_mov_b32_e32 v68, v46
	v_pk_add_f32 v[36:37], v[36:37], v[68:69] neg_lo:[0,1] neg_hi:[0,1]
	v_mov_b32_e32 v44, v47
	v_pk_mul_f32 v[36:37], v[36:37], v[44:45]
	v_add_u32_e32 v46, 0x22b0, v74
	v_pk_fma_f32 v[44:45], v[60:61], v[36:37], v[62:63] op_sel_hi:[0,1,0]
	v_lshlrev_b32_e32 v36, 16, v39
	v_and_b32_e32 v37, 0xffff0000, v39
	ds_read2_b32 v[38:39], v38 offset1:1
	ds_read2_b32 v[46:47], v46 offset1:1
	s_waitcnt lgkmcnt(1)
	v_mov_b32_e32 v69, v38
	s_waitcnt lgkmcnt(0)
	v_mov_b32_e32 v68, v46
	v_pk_add_f32 v[36:37], v[36:37], v[68:69] neg_lo:[0,1] neg_hi:[0,1]
	v_mov_b32_e32 v38, v47
	v_pk_mul_f32 v[36:37], v[36:37], v[38:39]
	v_cvt_pk_bf16_f32 v38, v44, v45
	v_pk_fma_f32 v[46:47], v[60:61], v[36:37], v[62:63] op_sel_hi:[0,1,0]
	v_cvt_pk_bf16_f32 v36, v40, v41
	v_cvt_pk_bf16_f32 v37, v42, v43
	v_cvt_pk_bf16_f32 v39, v46, v47
	s_nop 1
	v_mfma_f32_32x32x16_bf16 v[0:15], v[36:39], v[32:35], v[0:15]
	global_load_dword v32, v[50:51], off
	s_waitcnt vmcnt(0)
; #define LAS __attribute__((address_space(3)))
; __device__ __forceinline__ unsigned pk2(float lo, float hi) { f32x2 v = {lo, hi}; bf16x2_t b = __builtin_convertvector(v, bf16x2_t); return __builtin_bit_cast(unsigned, b); }
; __device__ __forceinline__ float bflo(unsigned u) { return __uint_as_float(u << 16); }
; __device__ __forceinline__ float bfhi(unsigned u) { return __uint_as_float(u & 0xffff0000u); }
; template <int tbA, int tbB> ...
;     ...
;         for (int which = 0; which < 2; ++which) {
;             const int tb = which ? tbB : tbA; const f32x16& acc = which ? accB : accA;
;             const float sbv = spb[g * 128 + tb * 32 + r];
; #pragma unroll
;             for (int q = 0; q < 4; ++q) {
;                 u32x2 w; w.x = pk2(acc[4 * q + 0] + sbv, acc[4 * q + 1] + sbv); w.y = pk2(acc[4 * q + 2] + sbv, acc[4 * q + 3] + sbv);
;                 *(LAS u32x2*)(stg + which * 2560 + r * 80 + (8 * q + 4 * hh) * 2) = w;
;             }
;         }
; #pragma unroll
;         for (int which = 0; which < 2; ++which) {
;             const int tb = which ? tbB : tbA;
; #pragma unroll
;             for (int i = 0; i < 2; ++i) {
;                 const int t = (lane >> 2) + 16 * i, ck = lane & 3;
;                 const size_t a = (size_t)(tok0 + tb * 32 + t) * DH + g * 128 + cb * 32 + ck * 8;
;                 const u32x4 uu = *(const u32x4*)(U + a), gc = *(const u32x4*)(GC + a);
;                 const u32x4 mv = *(const LAS u32x4*)(stg + which * 2560 + t * 80 + ck * 16);
;                 u32x4 o; o.x = pk2(bflo(uu.x) * bflo(mv.x) * bflo(gc.x), bfhi(uu.x) * bfhi(mv.x) * bfhi(gc.x)); o.y = pk2(bflo(uu.y) * bflo(mv.y) * bflo(gc.y), bfhi(uu.y) * bfhi(mv.y) * bfhi(gc.y));
;                 o.z = pk2(bflo(uu.z) * bflo(mv.z) * bflo(gc.z), bfhi(uu.z) * bfhi(mv.z) * bfhi(gc.z)); o.w = pk2(bflo(uu.w) * bflo(mv.w) * bflo(gc.w), bfhi(uu.w) * bfhi(mv.w) * bfhi(gc.w));
;                 *(u32x4*)(OC + a) = o;
;             }
	v_add_f32_e64 v16, v16, v32
	v_add_f32_e64 v17, v17, v32
	v_add_f32_e64 v18, v18, v32
	v_add_f32_e64 v19, v19, v32
	v_cvt_pk_bf16_f32 v16, v16, v17
	v_cvt_pk_bf16_f32 v17, v18, v19
	v_pk_add_f32 v[18:19], v[20:21], v[32:33] op_sel_hi:[1,0]
	v_pk_add_f32 v[20:21], v[22:23], v[32:33] op_sel_hi:[1,0]
	v_cvt_pk_bf16_f32 v18, v18, v19
	v_cvt_pk_bf16_f32 v19, v20, v21
	v_add_u32_e32 v22, 0x4000, v67
	ds_write2_b64 v22, v[16:17], v[18:19] offset1:2
	v_pk_add_f32 v[16:17], v[24:25], v[32:33] op_sel_hi:[1,0]
	v_pk_add_f32 v[18:19], v[26:27], v[32:33] op_sel_hi:[1,0]
	v_cvt_pk_bf16_f32 v16, v16, v17
	v_cvt_pk_bf16_f32 v17, v18, v19
	v_pk_add_f32 v[18:19], v[28:29], v[32:33] op_sel_hi:[1,0]
	v_pk_add_f32 v[20:21], v[30:31], v[32:33] op_sel_hi:[1,0]
	v_cvt_pk_bf16_f32 v18, v18, v19
	v_cvt_pk_bf16_f32 v19, v20, v21
	ds_write2_b64 v22, v[16:17], v[18:19] offset0:4 offset1:6
	global_load_dword v16, v[50:51], off offset:128
	v_add_u32_e32 v18, s8, v66
	v_add_u32_e32 v132, 0xfa008000, v18
	s_addk_i32 s8, 0x80
	v_lshl_add_u64 v[50:51], v[50:51], 0, s[62:63]
	s_cmpk_lg_i32 s8, 0x200
	s_waitcnt vmcnt(0)
	v_pk_add_f32 v[0:1], v[0:1], v[16:17] op_sel_hi:[1,0]
	v_pk_add_f32 v[2:3], v[2:3], v[16:17] op_sel_hi:[1,0]
	v_cvt_pk_bf16_f32 v0, v0, v1
	v_cvt_pk_bf16_f32 v1, v2, v3
	v_pk_add_f32 v[2:3], v[4:5], v[16:17] op_sel_hi:[1,0]
	v_pk_add_f32 v[4:5], v[6:7], v[16:17] op_sel_hi:[1,0]
	v_cvt_pk_bf16_f32 v2, v2, v3
	v_cvt_pk_bf16_f32 v3, v4, v5
	v_add_u32_e32 v6, 0x4800, v67
	ds_write2_b64 v6, v[0:1], v[2:3] offset0:64 offset1:66
	v_pk_add_f32 v[0:1], v[8:9], v[16:17] op_sel_hi:[1,0]
	v_pk_add_f32 v[2:3], v[10:11], v[16:17] op_sel_hi:[1,0]
	v_cvt_pk_bf16_f32 v0, v0, v1
	v_cvt_pk_bf16_f32 v1, v2, v3
	v_pk_add_f32 v[2:3], v[12:13], v[16:17] op_sel_hi:[1,0]
	v_pk_add_f32 v[4:5], v[14:15], v[16:17] op_sel_hi:[1,0]
	v_cvt_pk_bf16_f32 v2, v2, v3
	v_cvt_pk_bf16_f32 v3, v4, v5
	v_lshlrev_b64 v[12:13], 1, v[132:133]
	ds_write2_b64 v6, v[0:1], v[2:3] offset0:68 offset1:70
	v_lshl_add_u64 v[0:1], s[30:31], 0, v[12:13]
	global_load_dwordx4 v[0:3], v[0:1], off
	v_lshl_add_u64 v[4:5], s[34:35], 0, v[12:13]
	global_load_dwordx4 v[4:7], v[4:5], off
	ds_read_b128 v[8:11], v75 offset:16384
	v_add_u32_e32 v132, 0xfa00c000, v18
	s_waitcnt lgkmcnt(0)
	v_lshlrev_b32_e32 v16, 16, v8
	v_and_b32_e32 v17, 0xffff0000, v8
	v_lshlrev_b32_e32 v8, 16, v9
	v_and_b32_e32 v9, 0xffff0000, v9
	s_waitcnt vmcnt(1)
	v_lshlrev_b32_e32 v14, 16, v0
	v_and_b32_e32 v15, 0xffff0000, v0
	v_pk_mul_f32 v[14:15], v[14:15], v[16:17]
	s_waitcnt vmcnt(0)
	v_lshlrev_b32_e32 v16, 16, v4
	v_and_b32_e32 v17, 0xffff0000, v4
	v_pk_mul_f32 v[14:15], v[14:15], v[16:17]
	v_lshlrev_b32_e32 v4, 16, v5
	v_cvt_pk_bf16_f32 v0, v14, v15
	v_lshlrev_b32_e32 v14, 16, v1
	v_and_b32_e32 v15, 0xffff0000, v1
	v_pk_mul_f32 v[8:9], v[14:15], v[8:9]
	v_and_b32_e32 v5, 0xffff0000, v5
	v_pk_mul_f32 v[4:5], v[8:9], v[4:5]
	v_lshlrev_b32_e32 v8, 16, v10
	v_cvt_pk_bf16_f32 v1, v4, v5
	v_lshlrev_b32_e32 v4, 16, v2
	v_and_b32_e32 v5, 0xffff0000, v2
	v_and_b32_e32 v9, 0xffff0000, v10
	v_pk_mul_f32 v[4:5], v[4:5], v[8:9]
	v_lshlrev_b32_e32 v8, 16, v6
	v_and_b32_e32 v9, 0xffff0000, v6
	v_pk_mul_f32 v[4:5], v[4:5], v[8:9]
	v_lshlrev_b32_e32 v8, 16, v11
	v_cvt_pk_bf16_f32 v2, v4, v5
	v_lshlrev_b32_e32 v4, 16, v3
	v_and_b32_e32 v5, 0xffff0000, v3
	v_and_b32_e32 v9, 0xffff0000, v11
	v_pk_mul_f32 v[4:5], v[4:5], v[8:9]
	v_lshlrev_b32_e32 v6, 16, v7
	v_and_b32_e32 v7, 0xffff0000, v7
	v_pk_mul_f32 v[4:5], v[4:5], v[6:7]
	ds_read_b128 v[8:11], v75 offset:17664
	v_cvt_pk_bf16_f32 v3, v4, v5
	v_lshl_add_u64 v[4:5], s[36:37], 0, v[12:13]
	v_lshlrev_b64 v[12:13], 1, v[132:133]
	global_store_dwordx4 v[4:5], v[0:3], off
	v_lshl_add_u64 v[4:5], s[34:35], 0, v[12:13]
	global_load_dwordx4 v[4:7], v[4:5], off
	v_lshl_add_u64 v[0:1], s[30:31], 0, v[12:13]
	global_load_dwordx4 v[0:3], v[0:1], off
	s_waitcnt lgkmcnt(0)
	v_lshlrev_b32_e32 v16, 16, v8
	v_and_b32_e32 v17, 0xffff0000, v8
	v_lshlrev_b32_e32 v8, 16, v9
	v_and_b32_e32 v9, 0xffff0000, v9
	v_add_u32_e32 v132, 0xfa010000, v18
	s_waitcnt vmcnt(0)
; #define LAS __attribute__((address_space(3)))
; __device__ __forceinline__ unsigned pk2(float lo, float hi) { f32x2 v = {lo, hi}; bf16x2_t b = __builtin_convertvector(v, bf16x2_t); return __builtin_bit_cast(unsigned, b); }
; __device__ __forceinline__ float bflo(unsigned u) { return __uint_as_float(u << 16); }
; __device__ __forceinline__ float bfhi(unsigned u) { return __uint_as_float(u & 0xffff0000u); }
; template <int tbA, int tbB> ...
;     ...
;             for (int i = 0; i < 2; ++i) {
;                 const int t = (lane >> 2) + 16 * i, ck = lane & 3;
;                 const size_t a = (size_t)(tok0 + tb * 32 + t) * DH + g * 128 + cb * 32 + ck * 8;
;                 const u32x4 uu = *(const u32x4*)(U + a), gc = *(const u32x4*)(GC + a);
;                 const u32x4 mv = *(const LAS u32x4*)(stg + which * 2560 + t * 80 + ck * 16);
;                 u32x4 o; o.x = pk2(bflo(uu.x) * bflo(mv.x) * bflo(gc.x), bfhi(uu.x) * bfhi(mv.x) * bfhi(gc.x)); o.y = pk2(bflo(uu.y) * bflo(mv.y) * bflo(gc.y), bfhi(uu.y) * bfhi(mv.y) * bfhi(gc.y));
;                 o.z = pk2(bflo(uu.z) * bflo(mv.z) * bflo(gc.z), bfhi(uu.z) * bfhi(mv.z) * bfhi(gc.z)); o.w = pk2(bflo(uu.w) * bflo(mv.w) * bflo(gc.w), bfhi(uu.w) * bfhi(mv.w) * bfhi(gc.w));
;                 *(u32x4*)(OC + a) = o;
;             }
	v_lshlrev_b32_e32 v14, 16, v0
	v_and_b32_e32 v15, 0xffff0000, v0
	v_pk_mul_f32 v[14:15], v[14:15], v[16:17]
	v_lshlrev_b32_e32 v16, 16, v4
	v_and_b32_e32 v17, 0xffff0000, v4
	v_pk_mul_f32 v[14:15], v[14:15], v[16:17]
	v_lshlrev_b32_e32 v4, 16, v5
	v_cvt_pk_bf16_f32 v0, v14, v15
	v_lshlrev_b32_e32 v14, 16, v1
	v_and_b32_e32 v15, 0xffff0000, v1
	v_pk_mul_f32 v[8:9], v[14:15], v[8:9]
	v_and_b32_e32 v5, 0xffff0000, v5
	v_pk_mul_f32 v[4:5], v[8:9], v[4:5]
	v_lshlrev_b32_e32 v8, 16, v10
	v_cvt_pk_bf16_f32 v1, v4, v5
	v_lshlrev_b32_e32 v4, 16, v2
	v_and_b32_e32 v5, 0xffff0000, v2
	v_and_b32_e32 v9, 0xffff0000, v10
	v_pk_mul_f32 v[4:5], v[4:5], v[8:9]
	v_lshlrev_b32_e32 v8, 16, v6
	v_and_b32_e32 v9, 0xffff0000, v6
	v_pk_mul_f32 v[4:5], v[4:5], v[8:9]
	v_lshlrev_b32_e32 v8, 16, v11
	v_cvt_pk_bf16_f32 v2, v4, v5
	v_lshlrev_b32_e32 v4, 16, v3
	v_and_b32_e32 v5, 0xffff0000, v3
	v_and_b32_e32 v9, 0xffff0000, v11
	v_pk_mul_f32 v[4:5], v[4:5], v[8:9]
	v_lshlrev_b32_e32 v6, 16, v7
	v_and_b32_e32 v7, 0xffff0000, v7
	v_pk_mul_f32 v[4:5], v[4:5], v[6:7]
	ds_read_b128 v[8:11], v75 offset:18944
	v_cvt_pk_bf16_f32 v3, v4, v5
	v_lshl_add_u64 v[4:5], s[36:37], 0, v[12:13]
	v_lshlrev_b64 v[12:13], 1, v[132:133]
	global_store_dwordx4 v[4:5], v[0:3], off
	v_lshl_add_u64 v[4:5], s[34:35], 0, v[12:13]
	global_load_dwordx4 v[4:7], v[4:5], off
	v_lshl_add_u64 v[0:1], s[30:31], 0, v[12:13]
	global_load_dwordx4 v[0:3], v[0:1], off
	s_waitcnt lgkmcnt(0)
	v_lshlrev_b32_e32 v16, 16, v8
	v_and_b32_e32 v17, 0xffff0000, v8
	v_lshlrev_b32_e32 v8, 16, v9
	v_and_b32_e32 v9, 0xffff0000, v9
	v_add_u32_e32 v132, 0xfa014000, v18
	s_waitcnt vmcnt(0)
	v_lshlrev_b32_e32 v14, 16, v0
	v_and_b32_e32 v15, 0xffff0000, v0
	v_pk_mul_f32 v[14:15], v[14:15], v[16:17]
	v_lshlrev_b32_e32 v16, 16, v4
	v_and_b32_e32 v17, 0xffff0000, v4
	v_pk_mul_f32 v[14:15], v[14:15], v[16:17]
	v_lshlrev_b32_e32 v4, 16, v5
	v_cvt_pk_bf16_f32 v0, v14, v15
	v_lshlrev_b32_e32 v14, 16, v1
	v_and_b32_e32 v15, 0xffff0000, v1
	v_pk_mul_f32 v[8:9], v[14:15], v[8:9]
	v_and_b32_e32 v5, 0xffff0000, v5
	v_pk_mul_f32 v[4:5], v[8:9], v[4:5]
	v_lshlrev_b32_e32 v8, 16, v10
	v_cvt_pk_bf16_f32 v1, v4, v5
	v_lshlrev_b32_e32 v4, 16, v2
	v_and_b32_e32 v5, 0xffff0000, v2
	v_and_b32_e32 v9, 0xffff0000, v10
	v_pk_mul_f32 v[4:5], v[4:5], v[8:9]
	v_lshlrev_b32_e32 v8, 16, v6
	v_and_b32_e32 v9, 0xffff0000, v6
	v_pk_mul_f32 v[4:5], v[4:5], v[8:9]
	v_lshlrev_b32_e32 v8, 16, v11
	v_cvt_pk_bf16_f32 v2, v4, v5
	v_lshlrev_b32_e32 v4, 16, v3
	v_and_b32_e32 v5, 0xffff0000, v3
	v_and_b32_e32 v9, 0xffff0000, v11
	v_pk_mul_f32 v[4:5], v[4:5], v[8:9]
	v_lshlrev_b32_e32 v6, 16, v7
	v_and_b32_e32 v7, 0xffff0000, v7
	v_pk_mul_f32 v[4:5], v[4:5], v[6:7]
	ds_read_b128 v[8:11], v75 offset:20224
	v_cvt_pk_bf16_f32 v3, v4, v5
	v_lshl_add_u64 v[4:5], s[36:37], 0, v[12:13]
	v_lshlrev_b64 v[12:13], 1, v[132:133]
	global_store_dwordx4 v[4:5], v[0:3], off
	v_lshl_add_u64 v[4:5], s[34:35], 0, v[12:13]
	global_load_dwordx4 v[4:7], v[4:5], off
	v_lshl_add_u64 v[0:1], s[30:31], 0, v[12:13]
	global_load_dwordx4 v[0:3], v[0:1], off
	s_waitcnt lgkmcnt(0)
	v_lshlrev_b32_e32 v16, 16, v8
	v_and_b32_e32 v17, 0xffff0000, v8
	v_lshlrev_b32_e32 v8, 16, v9
	v_and_b32_e32 v9, 0xffff0000, v9
	s_waitcnt vmcnt(0)
	v_lshlrev_b32_e32 v14, 16, v0
	v_and_b32_e32 v15, 0xffff0000, v0
	v_pk_mul_f32 v[14:15], v[14:15], v[16:17]
	v_lshlrev_b32_e32 v16, 16, v4
	v_and_b32_e32 v17, 0xffff0000, v4
	v_pk_mul_f32 v[14:15], v[14:15], v[16:17]
	v_lshlrev_b32_e32 v4, 16, v5
	v_cvt_pk_bf16_f32 v0, v14, v15
	v_lshlrev_b32_e32 v14, 16, v1
	v_and_b32_e32 v15, 0xffff0000, v1
	v_pk_mul_f32 v[8:9], v[14:15], v[8:9]
	v_and_b32_e32 v5, 0xffff0000, v5
	v_pk_mul_f32 v[4:5], v[8:9], v[4:5]
	v_lshlrev_b32_e32 v8, 16, v10
	v_cvt_pk_bf16_f32 v1, v4, v5
	v_lshlrev_b32_e32 v4, 16, v2
	v_and_b32_e32 v5, 0xffff0000, v2
	v_and_b32_e32 v9, 0xffff0000, v10
	v_pk_mul_f32 v[4:5], v[4:5], v[8:9]
	v_lshlrev_b32_e32 v8, 16, v6
	v_and_b32_e32 v9, 0xffff0000, v6
	v_pk_mul_f32 v[4:5], v[4:5], v[8:9]
	v_lshlrev_b32_e32 v8, 16, v11
	v_cvt_pk_bf16_f32 v2, v4, v5
	v_lshlrev_b32_e32 v4, 16, v3
	v_and_b32_e32 v5, 0xffff0000, v3
	v_and_b32_e32 v9, 0xffff0000, v11
	v_pk_mul_f32 v[4:5], v[4:5], v[8:9]
	v_lshlrev_b32_e32 v6, 16, v7
	v_and_b32_e32 v7, 0xffff0000, v7
	v_pk_mul_f32 v[4:5], v[4:5], v[6:7]
	s_nop 0
	v_cvt_pk_bf16_f32 v3, v4, v5
	v_lshl_add_u64 v[4:5], s[36:37], 0, v[12:13]
	global_store_dwordx4 v[4:5], v[0:3], off
	s_cbranch_scc1 .LBB0_229
	s_mov_b64 s[8:9], 0

; __device__ __forceinline__ unsigned pk2(float lo, float hi) { f32x2 v = {lo, hi}; bf16x2_t b = __builtin_convertvector(v, bf16x2_t); return __builtin_bit_cast(unsigned, b); }
; #define MFMA32(a, b, c) __builtin_amdgcn_mfma_f32_32x32x16_bf16((a), (b), (c), 0, 0, 0)
; __device__ __forceinline__ void unpack8(const u32x4 w, float* v) { v[0] = bflo(w.x); v[1] = bfhi(w.x); v[2] = bflo(w.y); v[3] = bfhi(w.y); v[4] = bflo(w.z); v[5] = bfhi(w.z); v[6] = bflo(w.w); v[7] = bfhi(w.w); }
; template <int tbA, int tbB> ...
;     for (int gi = 0; gi < 4; ++gi) {
;         const int g = gh * 4 + gi;
;         const int ch = g * 128 + cb * 32 + r;
;         const float gg = lng[ch], bb = lnb[ch];
;         const bf16_t* ap = VCT + (size_t)ch * PT + tok0 + 8 * hh;
;         const bf16_t* wp = Wbf + (size_t)g * 16384 + 8 * hh;
;         constexpr int NSB = (tbB + 1) * 2, NSA = (tbA + 1) * 2;
;         int so = 0; asm volatile("" : "+v"(so));
;         u32x4 raw[NSB]; bf16x8 wB[NSB], wA[NSA];
; #pragma unroll
;         for (int k = 0; k < NSB; ++k) { raw[k] = *(const u32x4*)(ap + 16 * k); wB[k] = *(const bf16x8*)(wp + (size_t)(tbB * 32 + r) * 128 + 16 * k); }
; #pragma unroll
;         for (int k = 0; k < NSA; ++k) wA[k] = *(const bf16x8*)(wp + (size_t)(tbA * 32 + r) * 128 + 16 * k);
;         f32x16 accA, accB;
; #pragma unroll
;         for (int i = 0; i < 16; ++i) { accA[i] = 0.f; accB[i] = 0.f; }
; #pragma unroll
;         for (int k = 0; k < NSB; ++k) {
;             float v[8]; unpack8(raw[k], v);
; #pragma unroll
;             for (int jj = 0; jj < 8; ++jj) { const float mean = stat[(16 * k + 8 * hh + jj) * 2 + so], rstd = stat[(16 * k + 8 * hh + jj) * 2 + 1 + so]; v[jj] = (v[jj] - mean) * rstd * gg + bb; }
;             u32x4 af; af.x = pk2(v[0], v[1]); af.y = pk2(v[2], v[3]); af.z = pk2(v[4], v[5]); af.w = pk2(v[6], v[7]);
;             accB = MFMA32(__builtin_bit_cast(bf16x8, af), wB[k], accB);
;     ...
;                 const int t = (lane >> 2) + 16 * i, ck = lane & 3;
;                 const size_t a = (size_t)(tok0 + tb * 32 + t) * DH + g * 128 + cb * 32 + ck * 8;
;                 const u32x4 uu = *(const u32x4*)(U + a), gc = *(const u32x4*)(GC + a);
.LBB0_233:
	v_lshl_add_u64 v[8:9], v[68:69], 0, v[148:149]
	v_mov_b32_e32 v14, 0
	global_load_dword v74, v[72:73], off
	global_load_dword v76, v[70:71], off
	global_load_dwordx4 v[0:3], v[8:9], off offset:-128
	v_lshl_add_u64 v[10:11], v[64:65], 0, v[148:149]
	v_add_co_u32_e32 v12, vcc, s97, v10
	v_lshl_add_u32 v79, v14, 2, v158
	s_nop 0
	v_addc_co_u32_e32 v13, vcc, 0, v11, vcc
	v_add_co_u32_e32 v20, vcc, s93, v10
	global_load_dwordx4 v[4:7], v[12:13], off
	global_load_dwordx4 v[80:83], v[8:9], off offset:-96
	global_load_dwordx4 v[84:87], v[12:13], off offset:32
	global_load_dwordx4 v[88:91], v[8:9], off offset:-64
	global_load_dwordx4 v[92:95], v[12:13], off offset:64
	global_load_dwordx4 v[96:99], v[8:9], off offset:-32
	global_load_dwordx4 v[100:103], v[12:13], off offset:96
	global_load_dwordx4 v[60:63], v[8:9], off
	global_load_dwordx4 v[56:59], v[12:13], off offset:128
	global_load_dwordx4 v[52:55], v[8:9], off offset:32
	global_load_dwordx4 v[48:51], v[12:13], off offset:160
	global_load_dwordx4 v[44:47], v[8:9], off offset:64
	global_load_dwordx4 v[40:43], v[12:13], off offset:192
	global_load_dwordx4 v[36:39], v[8:9], off offset:96
	global_load_dwordx4 v[32:35], v[12:13], off offset:224
	v_addc_co_u32_e32 v21, vcc, 0, v11, vcc
	v_add_u32_e32 v12, 0x2000, v79
	global_load_dwordx4 v[104:107], v[20:21], off offset:32
	v_add_u32_e32 v112, 0x2080, v79
	v_lshl_add_u64 v[64:65], v[64:65], 0, s[58:59]
	v_lshl_add_u64 v[68:69], v[68:69], 0, s[60:61]
	v_lshl_add_u64 v[70:71], v[70:71], 0, s[62:63]
	v_lshl_add_u64 v[72:73], v[72:73], 0, s[62:63]
	v_add_u32_e32 v120, s8, v77
	v_add_u32_e32 v122, 0xfa000000, v120
	v_mov_b32_e32 v123, 0
	v_lshlrev_b64 v[122:123], 1, v[122:123]
	v_lshl_add_u64 v[124:125], s[30:31], 0, v[122:123]
	global_load_dword v126, v[124:125], off
	v_lshl_add_u64 v[124:125], s[34:35], 0, v[122:123]
	global_load_dword v126, v[124:125], off
	v_add_u32_e32 v122, 0xfa004000, v120
	v_mov_b32_e32 v123, 0
	v_lshlrev_b64 v[122:123], 1, v[122:123]
	v_lshl_add_u64 v[124:125], s[30:31], 0, v[122:123]
	global_load_dword v126, v[124:125], off
	v_lshl_add_u64 v[124:125], s[34:35], 0, v[122:123]
	global_load_dword v126, v[124:125], off
	v_add_u32_e32 v122, 0xfa018000, v120
	v_mov_b32_e32 v123, 0
	v_lshlrev_b64 v[122:123], 1, v[122:123]
	v_lshl_add_u64 v[124:125], s[30:31], 0, v[122:123]
	global_load_dword v126, v[124:125], off
	v_lshl_add_u64 v[124:125], s[34:35], 0, v[122:123]
	global_load_dword v126, v[124:125], off
	v_add_u32_e32 v122, 0xfa01c000, v120
	v_mov_b32_e32 v123, 0
	v_lshlrev_b64 v[122:123], 1, v[122:123]
	v_lshl_add_u64 v[124:125], s[30:31], 0, v[122:123]
	global_load_dword v126, v[124:125], off
	v_lshl_add_u64 v[124:125], s[34:35], 0, v[122:123]
	global_load_dword v126, v[124:125], off
	s_waitcnt vmcnt(22)
	v_lshlrev_b32_e32 v108, 16, v80
	v_and_b32_e32 v109, 0xffff0000, v80
	v_add_u32_e32 v80, 0x2088, v79
	v_lshlrev_b32_e32 v8, 16, v0
	v_and_b32_e32 v9, 0xffff0000, v0
	v_add_u32_e32 v0, 0x2008, v79
	ds_read2_b32 v[10:11], v0 offset1:1
	ds_read2_b32 v[12:13], v12 offset1:1
	v_lshlrev_b32_e32 v0, 16, v1
	v_and_b32_e32 v1, 0xffff0000, v1
	s_waitcnt lgkmcnt(1)
	v_mov_b32_e32 v15, v10
	s_waitcnt lgkmcnt(0)
	v_mov_b32_e32 v14, v12
	v_pk_add_f32 v[8:9], v[8:9], v[14:15] neg_lo:[0,1] neg_hi:[0,1]
	v_mov_b32_e32 v10, v13
	v_pk_mul_f32 v[8:9], v[8:9], v[10:11]
	v_add_u32_e32 v12, 0x2010, v79
	v_add_u32_e32 v10, 0x2018, v79
	ds_read2_b32 v[10:11], v10 offset1:1
	ds_read2_b32 v[12:13], v12 offset1:1
	v_pk_fma_f32 v[8:9], v[74:75], v[8:9], v[76:77] op_sel_hi:[0,1,0]
	s_waitcnt lgkmcnt(1)
	v_mov_b32_e32 v15, v10
	s_waitcnt lgkmcnt(0)
	v_mov_b32_e32 v14, v12
	v_pk_add_f32 v[0:1], v[0:1], v[14:15] neg_lo:[0,1] neg_hi:[0,1]
	v_mov_b32_e32 v10, v13
	v_pk_mul_f32 v[0:1], v[0:1], v[10:11]
	v_add_u32_e32 v14, 0x2020, v79
	v_lshlrev_b32_e32 v10, 16, v2
	v_and_b32_e32 v11, 0xffff0000, v2
	v_add_u32_e32 v2, 0x2028, v79
	ds_read2_b32 v[12:13], v2 offset1:1
	ds_read2_b32 v[14:15], v14 offset1:1
	v_lshlrev_b32_e32 v2, 16, v3
	v_and_b32_e32 v3, 0xffff0000, v3
	v_pk_fma_f32 v[0:1], v[74:75], v[0:1], v[76:77] op_sel_hi:[0,1,0]
	s_waitcnt lgkmcnt(1)
	v_mov_b32_e32 v17, v12
	s_waitcnt lgkmcnt(0)
	v_mov_b32_e32 v16, v14
	v_pk_add_f32 v[10:11], v[10:11], v[16:17] neg_lo:[0,1] neg_hi:[0,1]
	v_mov_b32_e32 v12, v15
	v_pk_mul_f32 v[10:11], v[10:11], v[12:13]
	v_add_u32_e32 v14, 0x2030, v79
	v_add_u32_e32 v12, 0x2038, v79
	ds_read2_b32 v[12:13], v12 offset1:1
	ds_read2_b32 v[14:15], v14 offset1:1
	global_load_dwordx4 v[20:23], v[20:21], off
	ds_read2_b32 v[110:111], v80 offset1:1
	ds_read2_b32 v[112:113], v112 offset1:1
	v_lshlrev_b32_e32 v80, 16, v81
	v_and_b32_e32 v81, 0xffff0000, v81
	s_waitcnt lgkmcnt(2)
	v_mov_b32_e32 v16, v14
	s_waitcnt lgkmcnt(1)
	v_mov_b32_e32 v115, v110
	s_waitcnt lgkmcnt(0)
	v_mov_b32_e32 v114, v112
	v_pk_add_f32 v[108:109], v[108:109], v[114:115] neg_lo:[0,1] neg_hi:[0,1]
	v_mov_b32_e32 v110, v113
	v_pk_mul_f32 v[108:109], v[108:109], v[110:111]
	v_add_u32_e32 v112, 0x2090, v79
	v_add_u32_e32 v110, 0x2098, v79
	ds_read2_b32 v[110:111], v110 offset1:1
	ds_read2_b32 v[112:113], v112 offset1:1
	v_mov_b32_e32 v17, v12
	v_pk_add_f32 v[2:3], v[2:3], v[16:17] neg_lo:[0,1] neg_hi:[0,1]
	v_mov_b32_e32 v12, v15
	s_waitcnt lgkmcnt(1)
	v_mov_b32_e32 v115, v110
	s_waitcnt lgkmcnt(0)
	v_mov_b32_e32 v114, v112
	v_pk_add_f32 v[80:81], v[80:81], v[114:115] neg_lo:[0,1] neg_hi:[0,1]
	v_mov_b32_e32 v110, v113
	v_pk_mul_f32 v[80:81], v[80:81], v[110:111]
	v_add_u32_e32 v114, 0x20a0, v79
	v_pk_fma_f32 v[110:111], v[74:75], v[80:81], v[76:77] op_sel_hi:[0,1,0]
	v_lshlrev_b32_e32 v80, 16, v82
	v_and_b32_e32 v81, 0xffff0000, v82
	v_add_u32_e32 v82, 0x20a8, v79
	ds_read2_b32 v[112:113], v82 offset1:1
	ds_read2_b32 v[114:115], v114 offset1:1
	v_pk_mul_f32 v[2:3], v[2:3], v[12:13]
	v_add_u32_e32 v82, 0x20b8, v79
	v_pk_fma_f32 v[10:11], v[74:75], v[10:11], v[76:77] op_sel_hi:[0,1,0]
	s_waitcnt lgkmcnt(1)
; __device__ __forceinline__ unsigned pk2(float lo, float hi) { f32x2 v = {lo, hi}; bf16x2_t b = __builtin_convertvector(v, bf16x2_t); return __builtin_bit_cast(unsigned, b); }
; #define MFMA32(a, b, c) __builtin_amdgcn_mfma_f32_32x32x16_bf16((a), (b), (c), 0, 0, 0)
; __device__ __forceinline__ void unpack8(const u32x4 w, float* v) { v[0] = bflo(w.x); v[1] = bfhi(w.x); v[2] = bflo(w.y); v[3] = bfhi(w.y); v[4] = bflo(w.z); v[5] = bfhi(w.z); v[6] = bflo(w.w); v[7] = bfhi(w.w); }
; template <int tbA, int tbB> ...
;     ...
;         for (int k = 0; k < NSB; ++k) {
;             float v[8]; unpack8(raw[k], v);
; #pragma unroll
;             for (int jj = 0; jj < 8; ++jj) { const float mean = stat[(16 * k + 8 * hh + jj) * 2 + so], rstd = stat[(16 * k + 8 * hh + jj) * 2 + 1 + so]; v[jj] = (v[jj] - mean) * rstd * gg + bb; }
;             u32x4 af; af.x = pk2(v[0], v[1]); af.y = pk2(v[2], v[3]); af.z = pk2(v[4], v[5]); af.w = pk2(v[6], v[7]);
;             accB = MFMA32(__builtin_bit_cast(bf16x8, af), wB[k], accB);
;             if (k < NSA) accA = MFMA32(__builtin_bit_cast(bf16x8, af), wA[k < NSA ? k : 0], accA);
	v_mov_b32_e32 v117, v112
	s_waitcnt lgkmcnt(0)
	v_mov_b32_e32 v116, v114
	v_pk_add_f32 v[80:81], v[80:81], v[116:117] neg_lo:[0,1] neg_hi:[0,1]
	v_mov_b32_e32 v112, v115
	v_pk_mul_f32 v[80:81], v[80:81], v[112:113]
	v_add_u32_e32 v114, 0x20b0, v79
	v_pk_fma_f32 v[2:3], v[74:75], v[2:3], v[76:77] op_sel_hi:[0,1,0]
	v_pk_fma_f32 v[112:113], v[74:75], v[80:81], v[76:77] op_sel_hi:[0,1,0]
	v_lshlrev_b32_e32 v80, 16, v83
	v_and_b32_e32 v81, 0xffff0000, v83
	ds_read2_b32 v[82:83], v82 offset1:1
	ds_read2_b32 v[114:115], v114 offset1:1
	v_cvt_pk_bf16_f32 v16, v8, v9
	v_cvt_pk_bf16_f32 v17, v0, v1
	v_cvt_pk_bf16_f32 v18, v10, v11
	v_cvt_pk_bf16_f32 v19, v2, v3
	s_waitcnt lgkmcnt(0)
	v_mov_b32_e32 v116, v114
	v_mov_b32_e32 v117, v82
	v_mfma_f32_32x32x16_bf16 v[0:15], v[16:19], v[4:7], 0
	v_add_f32_e64 v80, v80, -v116
	v_add_f32_e64 v81, v81, -v117
	v_mov_b32_e32 v82, v115
	v_mul_f32_e64 v80, v80, v82
	v_mul_f32_e64 v81, v81, v83
	v_pk_fma_f32 v[108:109], v[74:75], v[108:109], v[76:77] op_sel_hi:[0,1,0]
	v_pk_fma_f32 v[114:115], v[74:75], v[80:81], v[76:77] op_sel_hi:[0,1,0]
	v_cvt_pk_bf16_f32 v80, v108, v109
	v_cvt_pk_bf16_f32 v81, v110, v111
	v_cvt_pk_bf16_f32 v82, v112, v113
	v_cvt_pk_bf16_f32 v83, v114, v115
	s_waitcnt vmcnt(0)
	v_mfma_f32_32x32x16_bf16 v[16:31], v[16:19], v[20:23], 0
	v_mfma_f32_32x32x16_bf16 v[0:15], v[80:83], v[84:87], v[0:15]
	v_add_u32_e32 v84, 0x2100, v79
	v_mfma_f32_32x32x16_bf16 v[16:31], v[80:83], v[104:107], v[16:31]
	v_add_u32_e32 v82, 0x2108, v79
	ds_read2_b32 v[82:83], v82 offset1:1
	ds_read2_b32 v[84:85], v84 offset1:1
	v_lshlrev_b32_e32 v80, 16, v88
	v_and_b32_e32 v81, 0xffff0000, v88
	s_waitcnt lgkmcnt(1)
	v_mov_b32_e32 v87, v82
	s_waitcnt lgkmcnt(0)
	v_mov_b32_e32 v86, v84
	v_pk_add_f32 v[80:81], v[80:81], v[86:87] neg_lo:[0,1] neg_hi:[0,1]
	v_add_u32_e32 v86, 0x2110, v79
	v_add_u32_e32 v84, 0x2118, v79
	v_mov_b32_e32 v82, v85
	ds_read2_b32 v[84:85], v84 offset1:1
	ds_read2_b32 v[86:87], v86 offset1:1
	v_pk_mul_f32 v[80:81], v[80:81], v[82:83]
	v_lshlrev_b32_e32 v82, 16, v89
	v_and_b32_e32 v83, 0xffff0000, v89
	s_waitcnt lgkmcnt(1)
	v_mov_b32_e32 v89, v84
	s_waitcnt lgkmcnt(0)
	v_mov_b32_e32 v88, v86
	v_pk_add_f32 v[82:83], v[82:83], v[88:89] neg_lo:[0,1] neg_hi:[0,1]
	v_add_u32_e32 v88, 0x2120, v79
	v_add_u32_e32 v86, 0x2128, v79
	v_mov_b32_e32 v84, v87
	ds_read2_b32 v[86:87], v86 offset1:1
	ds_read2_b32 v[88:89], v88 offset1:1
	v_pk_mul_f32 v[82:83], v[82:83], v[84:85]
	v_lshlrev_b32_e32 v84, 16, v90
	v_and_b32_e32 v85, 0xffff0000, v90
	s_waitcnt lgkmcnt(1)
	v_mov_b32_e32 v105, v86
	s_waitcnt lgkmcnt(0)
	v_mov_b32_e32 v104, v88
	v_pk_add_f32 v[84:85], v[84:85], v[104:105] neg_lo:[0,1] neg_hi:[0,1]
	v_mov_b32_e32 v86, v89
	v_add_u32_e32 v90, 0x2130, v79
	v_add_u32_e32 v88, 0x2138, v79
	v_pk_mul_f32 v[84:85], v[84:85], v[86:87]
	v_lshlrev_b32_e32 v86, 16, v91
	v_and_b32_e32 v87, 0xffff0000, v91
	ds_read2_b32 v[88:89], v88 offset1:1
	ds_read2_b32 v[90:91], v90 offset1:1
	v_pk_fma_f32 v[80:81], v[74:75], v[80:81], v[76:77] op_sel_hi:[0,1,0]
	v_pk_fma_f32 v[82:83], v[74:75], v[82:83], v[76:77] op_sel_hi:[0,1,0]
	v_pk_fma_f32 v[84:85], v[74:75], v[84:85], v[76:77] op_sel_hi:[0,1,0]
	s_waitcnt lgkmcnt(1)
	v_mov_b32_e32 v105, v88
	s_waitcnt lgkmcnt(0)
	v_mov_b32_e32 v104, v90
	v_pk_add_f32 v[86:87], v[86:87], v[104:105] neg_lo:[0,1] neg_hi:[0,1]
	v_mov_b32_e32 v88, v91
	v_pk_mul_f32 v[86:87], v[86:87], v[88:89]
	v_cvt_pk_bf16_f32 v80, v80, v81
	v_pk_fma_f32 v[86:87], v[74:75], v[86:87], v[76:77] op_sel_hi:[0,1,0]
	v_cvt_pk_bf16_f32 v81, v82, v83
	v_cvt_pk_bf16_f32 v82, v84, v85
	v_cvt_pk_bf16_f32 v83, v86, v87
	v_add_u32_e32 v84, 0x2180, v79
	s_nop 0
	v_mfma_f32_32x32x16_bf16 v[0:15], v[80:83], v[92:95], v[0:15]
	v_add_u32_e32 v82, 0x2188, v79
	ds_read2_b32 v[82:83], v82 offset1:1
	ds_read2_b32 v[84:85], v84 offset1:1
	v_lshlrev_b32_e32 v80, 16, v96
	v_and_b32_e32 v81, 0xffff0000, v96
	s_waitcnt lgkmcnt(1)
	v_mov_b32_e32 v87, v82
	s_waitcnt lgkmcnt(0)
	v_mov_b32_e32 v86, v84
	v_pk_add_f32 v[80:81], v[80:81], v[86:87] neg_lo:[0,1] neg_hi:[0,1]
	v_add_u32_e32 v86, 0x2190, v79
	v_add_u32_e32 v84, 0x2198, v79
	v_mov_b32_e32 v82, v85
	ds_read2_b32 v[84:85], v84 offset1:1
	ds_read2_b32 v[86:87], v86 offset1:1
	v_pk_mul_f32 v[80:81], v[80:81], v[82:83]
	v_lshlrev_b32_e32 v82, 16, v97
	v_and_b32_e32 v83, 0xffff0000, v97
	s_waitcnt lgkmcnt(1)
	v_mov_b32_e32 v89, v84
	s_waitcnt lgkmcnt(0)
	v_mov_b32_e32 v88, v86
	v_pk_add_f32 v[82:83], v[82:83], v[88:89] neg_lo:[0,1] neg_hi:[0,1]
	v_add_u32_e32 v88, 0x21a0, v79
	v_add_u32_e32 v86, 0x21a8, v79
	v_mov_b32_e32 v84, v87
	ds_read2_b32 v[86:87], v86 offset1:1
	ds_read2_b32 v[88:89], v88 offset1:1
	v_pk_mul_f32 v[82:83], v[82:83], v[84:85]
	v_lshlrev_b32_e32 v84, 16, v98
	v_and_b32_e32 v85, 0xffff0000, v98
	s_waitcnt lgkmcnt(1)
	v_mov_b32_e32 v91, v86
	s_waitcnt lgkmcnt(0)
	v_mov_b32_e32 v90, v88
	v_pk_add_f32 v[84:85], v[84:85], v[90:91] neg_lo:[0,1] neg_hi:[0,1]
	v_add_u32_e32 v90, 0x21b0, v79
	v_add_u32_e32 v88, 0x21b8, v79
	v_mov_b32_e32 v86, v89
	ds_read2_b32 v[88:89], v88 offset1:1
	ds_read2_b32 v[90:91], v90 offset1:1
	v_pk_mul_f32 v[84:85], v[84:85], v[86:87]
	v_lshlrev_b32_e32 v86, 16, v99
	v_and_b32_e32 v87, 0xffff0000, v99
	s_waitcnt lgkmcnt(1)
	v_mov_b32_e32 v93, v88
	s_waitcnt lgkmcnt(0)
; __device__ __forceinline__ unsigned pk2(float lo, float hi) { f32x2 v = {lo, hi}; bf16x2_t b = __builtin_convertvector(v, bf16x2_t); return __builtin_bit_cast(unsigned, b); }
; #define MFMA32(a, b, c) __builtin_amdgcn_mfma_f32_32x32x16_bf16((a), (b), (c), 0, 0, 0)
; __device__ __forceinline__ void unpack8(const u32x4 w, float* v) { v[0] = bflo(w.x); v[1] = bfhi(w.x); v[2] = bflo(w.y); v[3] = bfhi(w.y); v[4] = bflo(w.z); v[5] = bfhi(w.z); v[6] = bflo(w.w); v[7] = bfhi(w.w); }
; template <int tbA, int tbB> ...
;     ...
;         for (int k = 0; k < NSB; ++k) {
;             float v[8]; unpack8(raw[k], v);
; #pragma unroll
;             for (int jj = 0; jj < 8; ++jj) { const float mean = stat[(16 * k + 8 * hh + jj) * 2 + so], rstd = stat[(16 * k + 8 * hh + jj) * 2 + 1 + so]; v[jj] = (v[jj] - mean) * rstd * gg + bb; }
;             u32x4 af; af.x = pk2(v[0], v[1]); af.y = pk2(v[2], v[3]); af.z = pk2(v[4], v[5]); af.w = pk2(v[6], v[7]);
;             accB = MFMA32(__builtin_bit_cast(bf16x8, af), wB[k], accB);
	v_mov_b32_e32 v92, v90
	v_pk_add_f32 v[86:87], v[86:87], v[92:93] neg_lo:[0,1] neg_hi:[0,1]
	v_mov_b32_e32 v88, v91
	v_pk_mul_f32 v[86:87], v[86:87], v[88:89]
	v_pk_fma_f32 v[80:81], v[74:75], v[80:81], v[76:77] op_sel_hi:[0,1,0]
	v_pk_fma_f32 v[82:83], v[74:75], v[82:83], v[76:77] op_sel_hi:[0,1,0]
	v_pk_fma_f32 v[84:85], v[74:75], v[84:85], v[76:77] op_sel_hi:[0,1,0]
	v_pk_fma_f32 v[86:87], v[74:75], v[86:87], v[76:77] op_sel_hi:[0,1,0]
	v_cvt_pk_bf16_f32 v80, v80, v81
	v_cvt_pk_bf16_f32 v81, v82, v83
	v_cvt_pk_bf16_f32 v82, v84, v85
	v_cvt_pk_bf16_f32 v83, v86, v87
	v_add_u32_e32 v84, 0x2200, v79
	s_nop 0
	v_mfma_f32_32x32x16_bf16 v[0:15], v[80:83], v[100:103], v[0:15]
	v_lshlrev_b32_e32 v80, 16, v60
	v_and_b32_e32 v81, 0xffff0000, v60
	v_add_u32_e32 v60, 0x2208, v79
	ds_read2_b32 v[82:83], v60 offset1:1
	ds_read2_b32 v[84:85], v84 offset1:1
	v_lshlrev_b32_e32 v60, 16, v61
	v_and_b32_e32 v61, 0xffff0000, v61
	s_waitcnt lgkmcnt(1)
	v_mov_b32_e32 v87, v82
	s_waitcnt lgkmcnt(0)
	v_mov_b32_e32 v86, v84
	v_pk_add_f32 v[80:81], v[80:81], v[86:87] neg_lo:[0,1] neg_hi:[0,1]
	v_mov_b32_e32 v82, v85
	v_pk_mul_f32 v[80:81], v[80:81], v[82:83]
	v_add_u32_e32 v84, 0x2210, v79
	v_add_u32_e32 v82, 0x2218, v79
	ds_read2_b32 v[82:83], v82 offset1:1
	ds_read2_b32 v[84:85], v84 offset1:1
	v_pk_fma_f32 v[80:81], v[74:75], v[80:81], v[76:77] op_sel_hi:[0,1,0]
	s_waitcnt lgkmcnt(1)
	v_mov_b32_e32 v87, v82
	s_waitcnt lgkmcnt(0)
	v_mov_b32_e32 v86, v84
	v_pk_add_f32 v[60:61], v[60:61], v[86:87] neg_lo:[0,1] neg_hi:[0,1]
	v_mov_b32_e32 v82, v85
	v_pk_mul_f32 v[60:61], v[60:61], v[82:83]
	v_add_u32_e32 v86, 0x2220, v79
	v_pk_fma_f32 v[82:83], v[74:75], v[60:61], v[76:77] op_sel_hi:[0,1,0]
	v_lshlrev_b32_e32 v60, 16, v62
	v_and_b32_e32 v61, 0xffff0000, v62
	v_add_u32_e32 v62, 0x2228, v79
	ds_read2_b32 v[84:85], v62 offset1:1
	ds_read2_b32 v[86:87], v86 offset1:1
	v_add_u32_e32 v62, 0x2238, v79
	s_waitcnt lgkmcnt(1)
	v_mov_b32_e32 v89, v84
	s_waitcnt lgkmcnt(0)
	v_mov_b32_e32 v88, v86
	v_pk_add_f32 v[60:61], v[60:61], v[88:89] neg_lo:[0,1] neg_hi:[0,1]
	v_mov_b32_e32 v84, v87
	v_pk_mul_f32 v[60:61], v[60:61], v[84:85]
	v_add_u32_e32 v86, 0x2230, v79
	v_pk_fma_f32 v[84:85], v[74:75], v[60:61], v[76:77] op_sel_hi:[0,1,0]
	v_lshlrev_b32_e32 v60, 16, v63
	v_and_b32_e32 v61, 0xffff0000, v63
	ds_read2_b32 v[62:63], v62 offset1:1
	ds_read2_b32 v[86:87], v86 offset1:1
	s_waitcnt lgkmcnt(1)
	v_mov_b32_e32 v89, v62
	s_waitcnt lgkmcnt(0)
	v_mov_b32_e32 v88, v86
	v_pk_add_f32 v[60:61], v[60:61], v[88:89] neg_lo:[0,1] neg_hi:[0,1]
	v_mov_b32_e32 v62, v87
	v_pk_mul_f32 v[60:61], v[60:61], v[62:63]
	v_cvt_pk_bf16_f32 v62, v84, v85
	v_pk_fma_f32 v[86:87], v[74:75], v[60:61], v[76:77] op_sel_hi:[0,1,0]
	v_cvt_pk_bf16_f32 v60, v80, v81
	v_cvt_pk_bf16_f32 v61, v82, v83
	v_cvt_pk_bf16_f32 v63, v86, v87
	s_nop 1
	v_mfma_f32_32x32x16_bf16 v[0:15], v[60:63], v[56:59], v[0:15]
	v_add_u32_e32 v60, 0x2280, v79
	v_lshlrev_b32_e32 v56, 16, v52
	v_and_b32_e32 v57, 0xffff0000, v52
	v_add_u32_e32 v52, 0x2288, v79
	ds_read2_b32 v[58:59], v52 offset1:1
	ds_read2_b32 v[60:61], v60 offset1:1
	v_lshlrev_b32_e32 v52, 16, v53
	v_and_b32_e32 v53, 0xffff0000, v53
	s_waitcnt lgkmcnt(1)
	v_mov_b32_e32 v63, v58
	s_waitcnt lgkmcnt(0)
	v_mov_b32_e32 v62, v60
	v_pk_add_f32 v[56:57], v[56:57], v[62:63] neg_lo:[0,1] neg_hi:[0,1]
	v_mov_b32_e32 v58, v61
	v_pk_mul_f32 v[56:57], v[56:57], v[58:59]
	v_add_u32_e32 v60, 0x2290, v79
	v_add_u32_e32 v58, 0x2298, v79
	ds_read2_b32 v[58:59], v58 offset1:1
	ds_read2_b32 v[60:61], v60 offset1:1
	v_pk_fma_f32 v[56:57], v[74:75], v[56:57], v[76:77] op_sel_hi:[0,1,0]
	s_waitcnt lgkmcnt(1)
	v_mov_b32_e32 v63, v58
	s_waitcnt lgkmcnt(0)
	v_mov_b32_e32 v62, v60
	v_pk_add_f32 v[52:53], v[52:53], v[62:63] neg_lo:[0,1] neg_hi:[0,1]
	v_mov_b32_e32 v58, v61
	v_pk_mul_f32 v[52:53], v[52:53], v[58:59]
	v_add_u32_e32 v62, 0x22a0, v79
	v_pk_fma_f32 v[58:59], v[74:75], v[52:53], v[76:77] op_sel_hi:[0,1,0]
	v_lshlrev_b32_e32 v52, 16, v54
	v_and_b32_e32 v53, 0xffff0000, v54
	v_add_u32_e32 v54, 0x22a8, v79
	ds_read2_b32 v[60:61], v54 offset1:1
	ds_read2_b32 v[62:63], v62 offset1:1
	v_add_u32_e32 v54, 0x22b8, v79
	s_waitcnt lgkmcnt(1)
	v_mov_b32_e32 v81, v60
	s_waitcnt lgkmcnt(0)
	v_mov_b32_e32 v80, v62
	v_pk_add_f32 v[52:53], v[52:53], v[80:81] neg_lo:[0,1] neg_hi:[0,1]
	v_mov_b32_e32 v60, v63
	v_pk_mul_f32 v[52:53], v[52:53], v[60:61]
	v_add_u32_e32 v62, 0x22b0, v79
	v_pk_fma_f32 v[60:61], v[74:75], v[52:53], v[76:77] op_sel_hi:[0,1,0]
	v_lshlrev_b32_e32 v52, 16, v55
	v_and_b32_e32 v53, 0xffff0000, v55
	ds_read2_b32 v[54:55], v54 offset1:1
	ds_read2_b32 v[62:63], v62 offset1:1
	s_waitcnt lgkmcnt(1)
	v_mov_b32_e32 v81, v54
	s_waitcnt lgkmcnt(0)
	v_mov_b32_e32 v80, v62
	v_pk_add_f32 v[52:53], v[52:53], v[80:81] neg_lo:[0,1] neg_hi:[0,1]
	v_mov_b32_e32 v54, v63
	v_pk_mul_f32 v[52:53], v[52:53], v[54:55]
	v_cvt_pk_bf16_f32 v54, v60, v61
	v_pk_fma_f32 v[62:63], v[74:75], v[52:53], v[76:77] op_sel_hi:[0,1,0]
	v_cvt_pk_bf16_f32 v52, v56, v57
	v_cvt_pk_bf16_f32 v53, v58, v59
	v_cvt_pk_bf16_f32 v55, v62, v63
	s_nop 1
	v_mfma_f32_32x32x16_bf16 v[0:15], v[52:55], v[48:51], v[0:15]
	v_add_u32_e32 v52, 0x2300, v79
	v_lshlrev_b32_e32 v48, 16, v44
	v_and_b32_e32 v49, 0xffff0000, v44
	v_add_u32_e32 v44, 0x2308, v79
	ds_read2_b32 v[50:51], v44 offset1:1
	ds_read2_b32 v[52:53], v52 offset1:1
	v_lshlrev_b32_e32 v44, 16, v45
	v_and_b32_e32 v45, 0xffff0000, v45
	s_waitcnt lgkmcnt(1)
	v_mov_b32_e32 v55, v50
	s_waitcnt lgkmcnt(0)
; #define LAS __attribute__((address_space(3)))
; __device__ __forceinline__ unsigned pk2(float lo, float hi) { f32x2 v = {lo, hi}; bf16x2_t b = __builtin_convertvector(v, bf16x2_t); return __builtin_bit_cast(unsigned, b); }
; #define MFMA32(a, b, c) __builtin_amdgcn_mfma_f32_32x32x16_bf16((a), (b), (c), 0, 0, 0)
; __device__ __forceinline__ void unpack8(const u32x4 w, float* v) { v[0] = bflo(w.x); v[1] = bfhi(w.x); v[2] = bflo(w.y); v[3] = bfhi(w.y); v[4] = bflo(w.z); v[5] = bfhi(w.z); v[6] = bflo(w.w); v[7] = bfhi(w.w); }
; template <int tbA, int tbB> ...
;     ...
;         for (int k = 0; k < NSB; ++k) {
;             float v[8]; unpack8(raw[k], v);
; #pragma unroll
;             for (int jj = 0; jj < 8; ++jj) { const float mean = stat[(16 * k + 8 * hh + jj) * 2 + so], rstd = stat[(16 * k + 8 * hh + jj) * 2 + 1 + so]; v[jj] = (v[jj] - mean) * rstd * gg + bb; }
;             u32x4 af; af.x = pk2(v[0], v[1]); af.y = pk2(v[2], v[3]); af.z = pk2(v[4], v[5]); af.w = pk2(v[6], v[7]);
;             accB = MFMA32(__builtin_bit_cast(bf16x8, af), wB[k], accB);
;             if (k < NSA) accA = MFMA32(__builtin_bit_cast(bf16x8, af), wA[k < NSA ? k : 0], accA);
;         }
; #pragma unroll
;         for (int which = 0; which < 2; ++which) {
;             const int tb = which ? tbB : tbA; const f32x16& acc = which ? accB : accA;
;             const float sbv = spb[g * 128 + tb * 32 + r];
; #pragma unroll
;             for (int q = 0; q < 4; ++q) {
;                 u32x2 w; w.x = pk2(acc[4 * q + 0] + sbv, acc[4 * q + 1] + sbv); w.y = pk2(acc[4 * q + 2] + sbv, acc[4 * q + 3] + sbv);
;                 *(LAS u32x2*)(stg + which * 2560 + r * 80 + (8 * q + 4 * hh) * 2) = w;
;             }
;         }
; #pragma unroll
	v_mov_b32_e32 v54, v52
	v_pk_add_f32 v[48:49], v[48:49], v[54:55] neg_lo:[0,1] neg_hi:[0,1]
	v_mov_b32_e32 v50, v53
	v_pk_mul_f32 v[48:49], v[48:49], v[50:51]
	v_add_u32_e32 v52, 0x2310, v79
	v_add_u32_e32 v50, 0x2318, v79
	ds_read2_b32 v[50:51], v50 offset1:1
	ds_read2_b32 v[52:53], v52 offset1:1
	v_pk_fma_f32 v[48:49], v[74:75], v[48:49], v[76:77] op_sel_hi:[0,1,0]
	s_waitcnt lgkmcnt(1)
	v_mov_b32_e32 v55, v50
	s_waitcnt lgkmcnt(0)
	v_mov_b32_e32 v54, v52
	v_pk_add_f32 v[44:45], v[44:45], v[54:55] neg_lo:[0,1] neg_hi:[0,1]
	v_mov_b32_e32 v50, v53
	v_pk_mul_f32 v[44:45], v[44:45], v[50:51]
	v_add_u32_e32 v54, 0x2320, v79
	v_pk_fma_f32 v[50:51], v[74:75], v[44:45], v[76:77] op_sel_hi:[0,1,0]
	v_lshlrev_b32_e32 v44, 16, v46
	v_and_b32_e32 v45, 0xffff0000, v46
	v_add_u32_e32 v46, 0x2328, v79
	ds_read2_b32 v[52:53], v46 offset1:1
	ds_read2_b32 v[54:55], v54 offset1:1
	v_add_u32_e32 v46, 0x2338, v79
	s_waitcnt lgkmcnt(1)
	v_mov_b32_e32 v57, v52
	s_waitcnt lgkmcnt(0)
	v_mov_b32_e32 v56, v54
	v_pk_add_f32 v[44:45], v[44:45], v[56:57] neg_lo:[0,1] neg_hi:[0,1]
	v_mov_b32_e32 v52, v55
	v_pk_mul_f32 v[44:45], v[44:45], v[52:53]
	v_add_u32_e32 v54, 0x2330, v79
	v_pk_fma_f32 v[52:53], v[74:75], v[44:45], v[76:77] op_sel_hi:[0,1,0]
	v_lshlrev_b32_e32 v44, 16, v47
	v_and_b32_e32 v45, 0xffff0000, v47
	ds_read2_b32 v[46:47], v46 offset1:1
	ds_read2_b32 v[54:55], v54 offset1:1
	s_waitcnt lgkmcnt(1)
	v_mov_b32_e32 v57, v46
	s_waitcnt lgkmcnt(0)
	v_mov_b32_e32 v56, v54
	v_pk_add_f32 v[44:45], v[44:45], v[56:57] neg_lo:[0,1] neg_hi:[0,1]
	v_mov_b32_e32 v46, v55
	v_pk_mul_f32 v[44:45], v[44:45], v[46:47]
	v_cvt_pk_bf16_f32 v46, v52, v53
	v_pk_fma_f32 v[54:55], v[74:75], v[44:45], v[76:77] op_sel_hi:[0,1,0]
	v_cvt_pk_bf16_f32 v44, v48, v49
	v_cvt_pk_bf16_f32 v45, v50, v51
	v_cvt_pk_bf16_f32 v47, v54, v55
	s_nop 1
	v_mfma_f32_32x32x16_bf16 v[0:15], v[44:47], v[40:43], v[0:15]
	v_add_u32_e32 v44, 0x2380, v79
	v_lshlrev_b32_e32 v40, 16, v36
	v_and_b32_e32 v41, 0xffff0000, v36
	v_add_u32_e32 v36, 0x2388, v79
	ds_read2_b32 v[42:43], v36 offset1:1
	ds_read2_b32 v[44:45], v44 offset1:1
	v_lshlrev_b32_e32 v36, 16, v37
	v_and_b32_e32 v37, 0xffff0000, v37
	s_waitcnt lgkmcnt(1)
	v_mov_b32_e32 v47, v42
	s_waitcnt lgkmcnt(0)
	v_mov_b32_e32 v46, v44
	v_pk_add_f32 v[40:41], v[40:41], v[46:47] neg_lo:[0,1] neg_hi:[0,1]
	v_mov_b32_e32 v42, v45
	v_pk_mul_f32 v[40:41], v[40:41], v[42:43]
	v_add_u32_e32 v44, 0x2390, v79
	v_add_u32_e32 v42, 0x2398, v79
	ds_read2_b32 v[42:43], v42 offset1:1
	ds_read2_b32 v[44:45], v44 offset1:1
	v_pk_fma_f32 v[40:41], v[74:75], v[40:41], v[76:77] op_sel_hi:[0,1,0]
	s_waitcnt lgkmcnt(1)
	v_mov_b32_e32 v47, v42
	s_waitcnt lgkmcnt(0)
	v_mov_b32_e32 v46, v44
	v_pk_add_f32 v[36:37], v[36:37], v[46:47] neg_lo:[0,1] neg_hi:[0,1]
	v_mov_b32_e32 v42, v45
	v_pk_mul_f32 v[36:37], v[36:37], v[42:43]
	v_add_u32_e32 v46, 0x23a0, v79
	v_pk_fma_f32 v[42:43], v[74:75], v[36:37], v[76:77] op_sel_hi:[0,1,0]
	v_lshlrev_b32_e32 v36, 16, v38
	v_and_b32_e32 v37, 0xffff0000, v38
	v_add_u32_e32 v38, 0x23a8, v79
	ds_read2_b32 v[44:45], v38 offset1:1
	ds_read2_b32 v[46:47], v46 offset1:1
	v_add_u32_e32 v38, 0x23b8, v79
	s_waitcnt lgkmcnt(1)
	v_mov_b32_e32 v49, v44
	s_waitcnt lgkmcnt(0)
	v_mov_b32_e32 v48, v46
	v_pk_add_f32 v[36:37], v[36:37], v[48:49] neg_lo:[0,1] neg_hi:[0,1]
	v_mov_b32_e32 v44, v47
	v_pk_mul_f32 v[36:37], v[36:37], v[44:45]
	v_add_u32_e32 v46, 0x23b0, v79
	v_pk_fma_f32 v[44:45], v[74:75], v[36:37], v[76:77] op_sel_hi:[0,1,0]
	v_lshlrev_b32_e32 v36, 16, v39
	v_and_b32_e32 v37, 0xffff0000, v39
	ds_read2_b32 v[38:39], v38 offset1:1
	ds_read2_b32 v[46:47], v46 offset1:1
	s_waitcnt lgkmcnt(1)
	v_mov_b32_e32 v49, v38
	s_waitcnt lgkmcnt(0)
	v_mov_b32_e32 v48, v46
	v_pk_add_f32 v[36:37], v[36:37], v[48:49] neg_lo:[0,1] neg_hi:[0,1]
	v_mov_b32_e32 v38, v47
	v_pk_mul_f32 v[36:37], v[36:37], v[38:39]
	v_cvt_pk_bf16_f32 v38, v44, v45
	v_pk_fma_f32 v[46:47], v[74:75], v[36:37], v[76:77] op_sel_hi:[0,1,0]
	v_cvt_pk_bf16_f32 v36, v40, v41
	v_cvt_pk_bf16_f32 v37, v42, v43
	v_cvt_pk_bf16_f32 v39, v46, v47
	s_nop 1
	v_mfma_f32_32x32x16_bf16 v[0:15], v[36:39], v[32:35], v[0:15]
	global_load_dword v32, v[66:67], off offset:-384
	s_waitcnt vmcnt(0)
	v_add_f32_e64 v16, v16, v32
	v_add_f32_e64 v17, v17, v32
	v_add_f32_e64 v18, v18, v32
	v_add_f32_e64 v19, v19, v32
	v_cvt_pk_bf16_f32 v16, v16, v17
	v_cvt_pk_bf16_f32 v17, v18, v19
	v_pk_add_f32 v[18:19], v[20:21], v[32:33] op_sel_hi:[1,0]
	v_pk_add_f32 v[20:21], v[22:23], v[32:33] op_sel_hi:[1,0]
	v_cvt_pk_bf16_f32 v18, v18, v19
	v_cvt_pk_bf16_f32 v19, v20, v21
	v_add_u32_e32 v22, 0x4000, v78
	ds_write2_b64 v22, v[16:17], v[18:19] offset1:2
	v_pk_add_f32 v[16:17], v[24:25], v[32:33] op_sel_hi:[1,0]
	v_pk_add_f32 v[18:19], v[26:27], v[32:33] op_sel_hi:[1,0]
	v_cvt_pk_bf16_f32 v16, v16, v17
	v_cvt_pk_bf16_f32 v17, v18, v19
	v_pk_add_f32 v[18:19], v[28:29], v[32:33] op_sel_hi:[1,0]
	v_pk_add_f32 v[20:21], v[30:31], v[32:33] op_sel_hi:[1,0]
	v_cvt_pk_bf16_f32 v18, v18, v19
	v_cvt_pk_bf16_f32 v19, v20, v21
	ds_write2_b64 v22, v[16:17], v[18:19] offset0:4 offset1:6
	global_load_dword v16, v[66:67], off
	v_add_u32_e32 v18, s8, v77
	v_add_u32_e32 v132, 0xfa000000, v18
	s_addk_i32 s8, 0x80
	v_lshl_add_u64 v[66:67], v[66:67], 0, s[62:63]
	s_cmpk_eq_i32 s8, 0x200
	s_waitcnt vmcnt(0)
; #define LAS __attribute__((address_space(3)))
; __device__ __forceinline__ unsigned pk2(float lo, float hi) { f32x2 v = {lo, hi}; bf16x2_t b = __builtin_convertvector(v, bf16x2_t); return __builtin_bit_cast(unsigned, b); }
; __device__ __forceinline__ float bflo(unsigned u) { return __uint_as_float(u << 16); }
; __device__ __forceinline__ float bfhi(unsigned u) { return __uint_as_float(u & 0xffff0000u); }
; template <int tbA, int tbB> ...
;     ...
;             const float sbv = spb[g * 128 + tb * 32 + r];
; #pragma unroll
;             for (int q = 0; q < 4; ++q) {
;                 u32x2 w; w.x = pk2(acc[4 * q + 0] + sbv, acc[4 * q + 1] + sbv); w.y = pk2(acc[4 * q + 2] + sbv, acc[4 * q + 3] + sbv);
;                 *(LAS u32x2*)(stg + which * 2560 + r * 80 + (8 * q + 4 * hh) * 2) = w;
;             }
;         }
; #pragma unroll
;         for (int which = 0; which < 2; ++which) {
;             const int tb = which ? tbB : tbA;
; #pragma unroll
;             for (int i = 0; i < 2; ++i) {
;                 const int t = (lane >> 2) + 16 * i, ck = lane & 3;
;                 const size_t a = (size_t)(tok0 + tb * 32 + t) * DH + g * 128 + cb * 32 + ck * 8;
;                 const u32x4 uu = *(const u32x4*)(U + a), gc = *(const u32x4*)(GC + a);
;                 const u32x4 mv = *(const LAS u32x4*)(stg + which * 2560 + t * 80 + ck * 16);
;                 u32x4 o; o.x = pk2(bflo(uu.x) * bflo(mv.x) * bflo(gc.x), bfhi(uu.x) * bfhi(mv.x) * bfhi(gc.x)); o.y = pk2(bflo(uu.y) * bflo(mv.y) * bflo(gc.y), bfhi(uu.y) * bfhi(mv.y) * bfhi(gc.y));
;                 o.z = pk2(bflo(uu.z) * bflo(mv.z) * bflo(gc.z), bfhi(uu.z) * bfhi(mv.z) * bfhi(gc.z)); o.w = pk2(bflo(uu.w) * bflo(mv.w) * bflo(gc.w), bfhi(uu.w) * bfhi(mv.w) * bfhi(gc.w));
;                 *(u32x4*)(OC + a) = o;
;             }
	v_pk_add_f32 v[0:1], v[0:1], v[16:17] op_sel_hi:[1,0]
	v_pk_add_f32 v[2:3], v[2:3], v[16:17] op_sel_hi:[1,0]
	v_cvt_pk_bf16_f32 v0, v0, v1
	v_cvt_pk_bf16_f32 v1, v2, v3
	v_pk_add_f32 v[2:3], v[4:5], v[16:17] op_sel_hi:[1,0]
	v_pk_add_f32 v[4:5], v[6:7], v[16:17] op_sel_hi:[1,0]
	v_cvt_pk_bf16_f32 v2, v2, v3
	v_cvt_pk_bf16_f32 v3, v4, v5
	v_add_u32_e32 v6, 0x4800, v78
	ds_write2_b64 v6, v[0:1], v[2:3] offset0:64 offset1:66
	v_pk_add_f32 v[0:1], v[8:9], v[16:17] op_sel_hi:[1,0]
	v_pk_add_f32 v[2:3], v[10:11], v[16:17] op_sel_hi:[1,0]
	v_cvt_pk_bf16_f32 v0, v0, v1
	v_cvt_pk_bf16_f32 v1, v2, v3
	v_pk_add_f32 v[2:3], v[12:13], v[16:17] op_sel_hi:[1,0]
	v_pk_add_f32 v[4:5], v[14:15], v[16:17] op_sel_hi:[1,0]
	v_cvt_pk_bf16_f32 v2, v2, v3
	v_cvt_pk_bf16_f32 v3, v4, v5
	v_lshlrev_b64 v[12:13], 1, v[132:133]
	ds_write2_b64 v6, v[0:1], v[2:3] offset0:68 offset1:70
	v_lshl_add_u64 v[0:1], s[30:31], 0, v[12:13]
	global_load_dwordx4 v[0:3], v[0:1], off
	v_lshl_add_u64 v[4:5], s[34:35], 0, v[12:13]
	global_load_dwordx4 v[4:7], v[4:5], off
	ds_read_b128 v[8:11], v75 offset:16384
	v_add_u32_e32 v132, 0xfa004000, v18
	s_waitcnt lgkmcnt(0)
	v_lshlrev_b32_e32 v16, 16, v8
	v_and_b32_e32 v17, 0xffff0000, v8
	v_lshlrev_b32_e32 v8, 16, v9
	v_and_b32_e32 v9, 0xffff0000, v9
	s_waitcnt vmcnt(1)
	v_lshlrev_b32_e32 v14, 16, v0
	v_and_b32_e32 v15, 0xffff0000, v0
	v_pk_mul_f32 v[14:15], v[14:15], v[16:17]
	s_waitcnt vmcnt(0)
	v_lshlrev_b32_e32 v16, 16, v4
	v_and_b32_e32 v17, 0xffff0000, v4
	v_pk_mul_f32 v[14:15], v[14:15], v[16:17]
	v_lshlrev_b32_e32 v4, 16, v5
	v_cvt_pk_bf16_f32 v0, v14, v15
	v_lshlrev_b32_e32 v14, 16, v1
	v_and_b32_e32 v15, 0xffff0000, v1
	v_pk_mul_f32 v[8:9], v[14:15], v[8:9]
	v_and_b32_e32 v5, 0xffff0000, v5
	v_pk_mul_f32 v[4:5], v[8:9], v[4:5]
	v_lshlrev_b32_e32 v8, 16, v10
	v_cvt_pk_bf16_f32 v1, v4, v5
	v_lshlrev_b32_e32 v4, 16, v2
	v_and_b32_e32 v5, 0xffff0000, v2
	v_and_b32_e32 v9, 0xffff0000, v10
	v_pk_mul_f32 v[4:5], v[4:5], v[8:9]
	v_lshlrev_b32_e32 v8, 16, v6
	v_and_b32_e32 v9, 0xffff0000, v6
	v_pk_mul_f32 v[4:5], v[4:5], v[8:9]
	v_lshlrev_b32_e32 v8, 16, v11
	v_cvt_pk_bf16_f32 v2, v4, v5
	v_lshlrev_b32_e32 v4, 16, v3
	v_and_b32_e32 v5, 0xffff0000, v3
	v_and_b32_e32 v9, 0xffff0000, v11
	v_pk_mul_f32 v[4:5], v[4:5], v[8:9]
	v_lshlrev_b32_e32 v6, 16, v7
	v_and_b32_e32 v7, 0xffff0000, v7
	v_pk_mul_f32 v[4:5], v[4:5], v[6:7]
	ds_read_b128 v[8:11], v75 offset:17664
	v_cvt_pk_bf16_f32 v3, v4, v5
	v_lshl_add_u64 v[4:5], s[36:37], 0, v[12:13]
	v_lshlrev_b64 v[12:13], 1, v[132:133]
	global_store_dwordx4 v[4:5], v[0:3], off
	v_lshl_add_u64 v[4:5], s[34:35], 0, v[12:13]
	global_load_dwordx4 v[4:7], v[4:5], off
	v_lshl_add_u64 v[0:1], s[30:31], 0, v[12:13]
	global_load_dwordx4 v[0:3], v[0:1], off
	s_waitcnt lgkmcnt(0)
	v_lshlrev_b32_e32 v16, 16, v8
	v_and_b32_e32 v17, 0xffff0000, v8
	v_lshlrev_b32_e32 v8, 16, v9
	v_and_b32_e32 v9, 0xffff0000, v9
	v_add_u32_e32 v132, 0xfa018000, v18
	s_waitcnt vmcnt(0)
	v_lshlrev_b32_e32 v14, 16, v0
	v_and_b32_e32 v15, 0xffff0000, v0
	v_pk_mul_f32 v[14:15], v[14:15], v[16:17]
	v_lshlrev_b32_e32 v16, 16, v4
	v_and_b32_e32 v17, 0xffff0000, v4
	v_pk_mul_f32 v[14:15], v[14:15], v[16:17]
	v_lshlrev_b32_e32 v4, 16, v5
	v_cvt_pk_bf16_f32 v0, v14, v15
	v_lshlrev_b32_e32 v14, 16, v1
	v_and_b32_e32 v15, 0xffff0000, v1
	v_pk_mul_f32 v[8:9], v[14:15], v[8:9]
	v_and_b32_e32 v5, 0xffff0000, v5
	v_pk_mul_f32 v[4:5], v[8:9], v[4:5]
	v_lshlrev_b32_e32 v8, 16, v10
	v_cvt_pk_bf16_f32 v1, v4, v5
	v_lshlrev_b32_e32 v4, 16, v2
	v_and_b32_e32 v5, 0xffff0000, v2
	v_and_b32_e32 v9, 0xffff0000, v10
	v_pk_mul_f32 v[4:5], v[4:5], v[8:9]
	v_lshlrev_b32_e32 v8, 16, v6
	v_and_b32_e32 v9, 0xffff0000, v6
	v_pk_mul_f32 v[4:5], v[4:5], v[8:9]
	v_lshlrev_b32_e32 v8, 16, v11
	v_cvt_pk_bf16_f32 v2, v4, v5
	v_lshlrev_b32_e32 v4, 16, v3
	v_and_b32_e32 v5, 0xffff0000, v3
	v_and_b32_e32 v9, 0xffff0000, v11
	v_pk_mul_f32 v[4:5], v[4:5], v[8:9]
	v_lshlrev_b32_e32 v6, 16, v7
	v_and_b32_e32 v7, 0xffff0000, v7
	v_pk_mul_f32 v[4:5], v[4:5], v[6:7]
	ds_read_b128 v[8:11], v75 offset:18944
	v_cvt_pk_bf16_f32 v3, v4, v5
	v_lshl_add_u64 v[4:5], s[36:37], 0, v[12:13]
	v_lshlrev_b64 v[12:13], 1, v[132:133]
	global_store_dwordx4 v[4:5], v[0:3], off
	v_lshl_add_u64 v[4:5], s[34:35], 0, v[12:13]
	global_load_dwordx4 v[4:7], v[4:5], off
	v_lshl_add_u64 v[0:1], s[30:31], 0, v[12:13]
	global_load_dwordx4 v[0:3], v[0:1], off
	s_waitcnt lgkmcnt(0)
; #define LAS __attribute__((address_space(3)))
; __device__ __forceinline__ unsigned pk2(float lo, float hi) { f32x2 v = {lo, hi}; bf16x2_t b = __builtin_convertvector(v, bf16x2_t); return __builtin_bit_cast(unsigned, b); }
; __device__ __forceinline__ float bflo(unsigned u) { return __uint_as_float(u << 16); }
; __device__ __forceinline__ float bfhi(unsigned u) { return __uint_as_float(u & 0xffff0000u); }
; template <int tbA, int tbB> ...
;     ...
;             for (int i = 0; i < 2; ++i) {
;                 const int t = (lane >> 2) + 16 * i, ck = lane & 3;
;                 const size_t a = (size_t)(tok0 + tb * 32 + t) * DH + g * 128 + cb * 32 + ck * 8;
;                 const u32x4 uu = *(const u32x4*)(U + a), gc = *(const u32x4*)(GC + a);
;                 const u32x4 mv = *(const LAS u32x4*)(stg + which * 2560 + t * 80 + ck * 16);
;                 u32x4 o; o.x = pk2(bflo(uu.x) * bflo(mv.x) * bflo(gc.x), bfhi(uu.x) * bfhi(mv.x) * bfhi(gc.x)); o.y = pk2(bflo(uu.y) * bflo(mv.y) * bflo(gc.y), bfhi(uu.y) * bfhi(mv.y) * bfhi(gc.y));
;                 o.z = pk2(bflo(uu.z) * bflo(mv.z) * bflo(gc.z), bfhi(uu.z) * bfhi(mv.z) * bfhi(gc.z)); o.w = pk2(bflo(uu.w) * bflo(mv.w) * bflo(gc.w), bfhi(uu.w) * bfhi(mv.w) * bfhi(gc.w));
;                 *(u32x4*)(OC + a) = o;
;             }
	v_lshlrev_b32_e32 v16, 16, v8
	v_and_b32_e32 v17, 0xffff0000, v8
	v_lshlrev_b32_e32 v8, 16, v9
	v_and_b32_e32 v9, 0xffff0000, v9
	v_add_u32_e32 v132, 0xfa01c000, v18
	s_waitcnt vmcnt(0)
	v_lshlrev_b32_e32 v14, 16, v0
	v_and_b32_e32 v15, 0xffff0000, v0
	v_pk_mul_f32 v[14:15], v[14:15], v[16:17]
	v_lshlrev_b32_e32 v16, 16, v4
	v_and_b32_e32 v17, 0xffff0000, v4
	v_pk_mul_f32 v[14:15], v[14:15], v[16:17]
	v_lshlrev_b32_e32 v4, 16, v5
	v_cvt_pk_bf16_f32 v0, v14, v15
	v_lshlrev_b32_e32 v14, 16, v1
	v_and_b32_e32 v15, 0xffff0000, v1
	v_pk_mul_f32 v[8:9], v[14:15], v[8:9]
	v_and_b32_e32 v5, 0xffff0000, v5
	v_pk_mul_f32 v[4:5], v[8:9], v[4:5]
	v_lshlrev_b32_e32 v8, 16, v10
	v_cvt_pk_bf16_f32 v1, v4, v5
	v_lshlrev_b32_e32 v4, 16, v2
	v_and_b32_e32 v5, 0xffff0000, v2
	v_and_b32_e32 v9, 0xffff0000, v10
	v_pk_mul_f32 v[4:5], v[4:5], v[8:9]
	v_lshlrev_b32_e32 v8, 16, v6
	v_and_b32_e32 v9, 0xffff0000, v6
	v_pk_mul_f32 v[4:5], v[4:5], v[8:9]
	v_lshlrev_b32_e32 v8, 16, v11
	v_cvt_pk_bf16_f32 v2, v4, v5
	v_lshlrev_b32_e32 v4, 16, v3
	v_and_b32_e32 v5, 0xffff0000, v3
	v_and_b32_e32 v9, 0xffff0000, v11
	v_pk_mul_f32 v[4:5], v[4:5], v[8:9]
	v_lshlrev_b32_e32 v6, 16, v7
	v_and_b32_e32 v7, 0xffff0000, v7
	v_pk_mul_f32 v[4:5], v[4:5], v[6:7]
	ds_read_b128 v[8:11], v75 offset:20224
	v_cvt_pk_bf16_f32 v3, v4, v5
	v_lshl_add_u64 v[4:5], s[36:37], 0, v[12:13]
	v_lshlrev_b64 v[12:13], 1, v[132:133]
	global_store_dwordx4 v[4:5], v[0:3], off
	v_lshl_add_u64 v[4:5], s[34:35], 0, v[12:13]
	global_load_dwordx4 v[4:7], v[4:5], off
	v_lshl_add_u64 v[0:1], s[30:31], 0, v[12:13]
	global_load_dwordx4 v[0:3], v[0:1], off
	s_waitcnt lgkmcnt(0)
	v_lshlrev_b32_e32 v16, 16, v8
	v_and_b32_e32 v17, 0xffff0000, v8
	v_lshlrev_b32_e32 v8, 16, v9
	v_and_b32_e32 v9, 0xffff0000, v9
	s_waitcnt vmcnt(0)
	v_lshlrev_b32_e32 v14, 16, v0
	v_and_b32_e32 v15, 0xffff0000, v0
	v_pk_mul_f32 v[14:15], v[14:15], v[16:17]
	v_lshlrev_b32_e32 v16, 16, v4
	v_and_b32_e32 v17, 0xffff0000, v4
	v_pk_mul_f32 v[14:15], v[14:15], v[16:17]
	v_lshlrev_b32_e32 v4, 16, v5
	v_cvt_pk_bf16_f32 v0, v14, v15
	v_lshlrev_b32_e32 v14, 16, v1
	v_and_b32_e32 v15, 0xffff0000, v1
	v_pk_mul_f32 v[8:9], v[14:15], v[8:9]
	v_and_b32_e32 v5, 0xffff0000, v5
	v_pk_mul_f32 v[4:5], v[8:9], v[4:5]
	v_lshlrev_b32_e32 v8, 16, v10
	v_cvt_pk_bf16_f32 v1, v4, v5
	v_lshlrev_b32_e32 v4, 16, v2
	v_and_b32_e32 v5, 0xffff0000, v2
	v_and_b32_e32 v9, 0xffff0000, v10
	v_pk_mul_f32 v[4:5], v[4:5], v[8:9]
	v_lshlrev_b32_e32 v8, 16, v6
	v_and_b32_e32 v9, 0xffff0000, v6
	v_pk_mul_f32 v[4:5], v[4:5], v[8:9]
	v_lshlrev_b32_e32 v8, 16, v11
	v_cvt_pk_bf16_f32 v2, v4, v5
	v_lshlrev_b32_e32 v4, 16, v3
	v_and_b32_e32 v5, 0xffff0000, v3
	v_and_b32_e32 v9, 0xffff0000, v11
	v_pk_mul_f32 v[4:5], v[4:5], v[8:9]
	v_lshlrev_b32_e32 v6, 16, v7
	v_and_b32_e32 v7, 0xffff0000, v7
	v_pk_mul_f32 v[4:5], v[4:5], v[6:7]
	s_nop 0
	v_cvt_pk_bf16_f32 v3, v4, v5
	v_lshl_add_u64 v[4:5], s[36:37], 0, v[12:13]
	global_store_dwordx4 v[4:5], v[0:3], off
	s_cbranch_scc0 .LBB0_233

; __device__ __forceinline__ unsigned pk2(float lo, float hi) { f32x2 v = {lo, hi}; bf16x2_t b = __builtin_convertvector(v, bf16x2_t); return __builtin_bit_cast(unsigned, b); }
; #define MFMA32(a, b, c) __builtin_amdgcn_mfma_f32_32x32x16_bf16((a), (b), (c), 0, 0, 0)
; __device__ __forceinline__ void unpack8(const u32x4 w, float* v) { v[0] = bflo(w.x); v[1] = bfhi(w.x); v[2] = bflo(w.y); v[3] = bfhi(w.y); v[4] = bflo(w.z); v[5] = bfhi(w.z); v[6] = bflo(w.w); v[7] = bfhi(w.w); }
; template <int tbA, int tbB> ...
;     for (int gi = 0; gi < 4; ++gi) {
;         const int g = gh * 4 + gi;
;         const int ch = g * 128 + cb * 32 + r;
;         const float gg = lng[ch], bb = lnb[ch];
;         const bf16_t* ap = VCT + (size_t)ch * PT + tok0 + 8 * hh;
;         const bf16_t* wp = Wbf + (size_t)g * 16384 + 8 * hh;
;         constexpr int NSB = (tbB + 1) * 2, NSA = (tbA + 1) * 2;
;         int so = 0; asm volatile("" : "+v"(so));
;         u32x4 raw[NSB]; bf16x8 wB[NSB], wA[NSA];
; #pragma unroll
;         for (int k = 0; k < NSB; ++k) { raw[k] = *(const u32x4*)(ap + 16 * k); wB[k] = *(const bf16x8*)(wp + (size_t)(tbB * 32 + r) * 128 + 16 * k); }
; #pragma unroll
;         for (int k = 0; k < NSA; ++k) wA[k] = *(const bf16x8*)(wp + (size_t)(tbA * 32 + r) * 128 + 16 * k);
;         f32x16 accA, accB;
; #pragma unroll
;         for (int i = 0; i < 16; ++i) { accA[i] = 0.f; accB[i] = 0.f; }
; #pragma unroll
;         for (int k = 0; k < NSB; ++k) {
;             float v[8]; unpack8(raw[k], v);
; #pragma unroll
;             for (int jj = 0; jj < 8; ++jj) { const float mean = stat[(16 * k + 8 * hh + jj) * 2 + so], rstd = stat[(16 * k + 8 * hh + jj) * 2 + 1 + so]; v[jj] = (v[jj] - mean) * rstd * gg + bb; }
;             u32x4 af; af.x = pk2(v[0], v[1]); af.y = pk2(v[2], v[3]); af.z = pk2(v[4], v[5]); af.w = pk2(v[6], v[7]);
;             accB = MFMA32(__builtin_bit_cast(bf16x8, af), wB[k], accB);
;     ...
;                 const int t = (lane >> 2) + 16 * i, ck = lane & 3;
;                 const size_t a = (size_t)(tok0 + tb * 32 + t) * DH + g * 128 + cb * 32 + ck * 8;
;                 const u32x4 uu = *(const u32x4*)(U + a), gc = *(const u32x4*)(GC + a);
.LBB0_653:
	v_lshl_add_u64 v[8:9], v[52:53], 0, v[148:149]
	v_mov_b32_e32 v14, v133
	global_load_dword v60, v[56:57], off
	global_load_dword v62, v[54:55], off
	global_load_dwordx4 v[0:3], v[8:9], off offset:-96
	v_lshl_add_u64 v[10:11], v[58:59], 0, v[148:149]
	v_add_co_u32_e32 v12, vcc, s96, v10
	v_lshl_add_u32 v74, v14, 2, v158
	s_nop 0
	v_addc_co_u32_e32 v13, vcc, 0, v11, vcc
	v_add_co_u32_e32 v20, vcc, s97, v10
	global_load_dwordx4 v[4:7], v[12:13], off
	global_load_dwordx4 v[68:71], v[8:9], off offset:-64
	global_load_dwordx4 v[76:79], v[12:13], off offset:32
	global_load_dwordx4 v[80:83], v[8:9], off offset:-32
	global_load_dwordx4 v[84:87], v[12:13], off offset:64
	global_load_dwordx4 v[88:91], v[8:9], off
	global_load_dwordx4 v[92:95], v[12:13], off offset:96
	global_load_dwordx4 v[44:47], v[8:9], off offset:32
	global_load_dwordx4 v[40:43], v[12:13], off offset:128
	global_load_dwordx4 v[36:39], v[8:9], off offset:64
	global_load_dwordx4 v[32:35], v[12:13], off offset:160
	v_addc_co_u32_e32 v21, vcc, 0, v11, vcc
	v_add_u32_e32 v12, 0x2000, v74
	global_load_dwordx4 v[96:99], v[20:21], off offset:32
	global_load_dwordx4 v[100:103], v[20:21], off offset:64
	global_load_dwordx4 v[104:107], v[20:21], off offset:96
	v_add_u32_e32 v110, 0x2080, v74
	v_lshl_add_u64 v[58:59], v[58:59], 0, s[58:59]
	v_lshl_add_u64 v[52:53], v[52:53], 0, s[60:61]
	v_lshl_add_u64 v[54:55], v[54:55], 0, s[62:63]
	v_lshl_add_u64 v[56:57], v[56:57], 0, s[62:63]
	v_add_u32_e32 v120, s8, v66
	v_add_u32_e32 v122, 0xfa008000, v120
	v_mov_b32_e32 v123, 0
	v_lshlrev_b64 v[122:123], 1, v[122:123]
	v_lshl_add_u64 v[124:125], s[30:31], 0, v[122:123]
	global_load_dword v126, v[124:125], off
	v_lshl_add_u64 v[124:125], s[34:35], 0, v[122:123]
	global_load_dword v126, v[124:125], off
	v_add_u32_e32 v122, 0xfa00c000, v120
	v_mov_b32_e32 v123, 0
	v_lshlrev_b64 v[122:123], 1, v[122:123]
	v_lshl_add_u64 v[124:125], s[30:31], 0, v[122:123]
	global_load_dword v126, v[124:125], off
	v_lshl_add_u64 v[124:125], s[34:35], 0, v[122:123]
	global_load_dword v126, v[124:125], off
	v_add_u32_e32 v122, 0xfa010000, v120
	v_mov_b32_e32 v123, 0
	v_lshlrev_b64 v[122:123], 1, v[122:123]
	v_lshl_add_u64 v[124:125], s[30:31], 0, v[122:123]
	global_load_dword v126, v[124:125], off
	v_lshl_add_u64 v[124:125], s[34:35], 0, v[122:123]
	global_load_dword v126, v[124:125], off
	v_add_u32_e32 v122, 0xfa014000, v120
	v_mov_b32_e32 v123, 0
	v_lshlrev_b64 v[122:123], 1, v[122:123]
	v_lshl_add_u64 v[124:125], s[30:31], 0, v[122:123]
	global_load_dword v126, v[124:125], off
	v_lshl_add_u64 v[124:125], s[34:35], 0, v[122:123]
	global_load_dword v126, v[124:125], off
	s_waitcnt vmcnt(20)
	v_lshlrev_b32_e32 v72, 16, v68
	v_lshlrev_b32_e32 v8, 16, v0
	v_and_b32_e32 v9, 0xffff0000, v0
	v_add_u32_e32 v0, 0x2008, v74
	ds_read2_b32 v[10:11], v0 offset1:1
	ds_read2_b32 v[12:13], v12 offset1:1
	v_lshlrev_b32_e32 v0, 16, v1
	v_and_b32_e32 v1, 0xffff0000, v1
	v_and_b32_e32 v73, 0xffff0000, v68
	s_waitcnt lgkmcnt(1)
	v_mov_b32_e32 v15, v10
	s_waitcnt lgkmcnt(0)
	v_mov_b32_e32 v14, v12
	v_pk_add_f32 v[8:9], v[8:9], v[14:15] neg_lo:[0,1] neg_hi:[0,1]
	v_mov_b32_e32 v10, v13
	v_pk_mul_f32 v[8:9], v[8:9], v[10:11]
	v_add_u32_e32 v12, 0x2010, v74
	v_add_u32_e32 v10, 0x2018, v74
	ds_read2_b32 v[10:11], v10 offset1:1
	ds_read2_b32 v[12:13], v12 offset1:1
	v_add_u32_e32 v68, 0x2088, v74
	v_pk_fma_f32 v[8:9], v[60:61], v[8:9], v[62:63] op_sel_hi:[0,1,0]
	s_waitcnt lgkmcnt(1)
	v_mov_b32_e32 v15, v10
	s_waitcnt lgkmcnt(0)
	v_mov_b32_e32 v14, v12
	v_pk_add_f32 v[0:1], v[0:1], v[14:15] neg_lo:[0,1] neg_hi:[0,1]
	v_mov_b32_e32 v10, v13
	v_pk_mul_f32 v[0:1], v[0:1], v[10:11]
	v_add_u32_e32 v14, 0x2020, v74
	v_lshlrev_b32_e32 v10, 16, v2
	v_and_b32_e32 v11, 0xffff0000, v2
	v_add_u32_e32 v2, 0x2028, v74
	ds_read2_b32 v[12:13], v2 offset1:1
	ds_read2_b32 v[14:15], v14 offset1:1
	v_lshlrev_b32_e32 v2, 16, v3
	v_and_b32_e32 v3, 0xffff0000, v3
	v_pk_fma_f32 v[0:1], v[60:61], v[0:1], v[62:63] op_sel_hi:[0,1,0]
	s_waitcnt lgkmcnt(1)
	v_mov_b32_e32 v17, v12
	s_waitcnt lgkmcnt(0)
	v_mov_b32_e32 v16, v14
	v_pk_add_f32 v[10:11], v[10:11], v[16:17] neg_lo:[0,1] neg_hi:[0,1]
	v_mov_b32_e32 v12, v15
	v_pk_mul_f32 v[10:11], v[10:11], v[12:13]
	v_add_u32_e32 v14, 0x2030, v74
	v_add_u32_e32 v12, 0x2038, v74
	ds_read2_b32 v[12:13], v12 offset1:1
	ds_read2_b32 v[14:15], v14 offset1:1
	global_load_dwordx4 v[20:23], v[20:21], off
	ds_read2_b32 v[108:109], v68 offset1:1
	ds_read2_b32 v[110:111], v110 offset1:1
	v_lshlrev_b32_e32 v68, 16, v69
	v_and_b32_e32 v69, 0xffff0000, v69
	s_waitcnt lgkmcnt(2)
	v_mov_b32_e32 v16, v14
	s_waitcnt lgkmcnt(1)
	v_mov_b32_e32 v113, v108
	s_waitcnt lgkmcnt(0)
	v_mov_b32_e32 v112, v110
	v_pk_add_f32 v[72:73], v[72:73], v[112:113] neg_lo:[0,1] neg_hi:[0,1]
	v_mov_b32_e32 v108, v111
	v_pk_mul_f32 v[72:73], v[72:73], v[108:109]
	v_add_u32_e32 v110, 0x2090, v74
	v_add_u32_e32 v108, 0x2098, v74
	ds_read2_b32 v[108:109], v108 offset1:1
	ds_read2_b32 v[110:111], v110 offset1:1
	v_mov_b32_e32 v17, v12
	v_pk_add_f32 v[2:3], v[2:3], v[16:17] neg_lo:[0,1] neg_hi:[0,1]
	v_mov_b32_e32 v12, v15
	s_waitcnt lgkmcnt(1)
	v_mov_b32_e32 v113, v108
	s_waitcnt lgkmcnt(0)
	v_mov_b32_e32 v112, v110
	v_pk_add_f32 v[68:69], v[68:69], v[112:113] neg_lo:[0,1] neg_hi:[0,1]
	v_mov_b32_e32 v108, v111
	v_pk_mul_f32 v[68:69], v[68:69], v[108:109]
	v_add_u32_e32 v112, 0x20a0, v74
	v_pk_fma_f32 v[108:109], v[60:61], v[68:69], v[62:63] op_sel_hi:[0,1,0]
	v_lshlrev_b32_e32 v68, 16, v70
	v_and_b32_e32 v69, 0xffff0000, v70
	v_add_u32_e32 v70, 0x20a8, v74
	ds_read2_b32 v[110:111], v70 offset1:1
	ds_read2_b32 v[112:113], v112 offset1:1
	v_pk_mul_f32 v[2:3], v[2:3], v[12:13]
	v_add_u32_e32 v70, 0x20b8, v74
	v_pk_fma_f32 v[10:11], v[60:61], v[10:11], v[62:63] op_sel_hi:[0,1,0]
	s_waitcnt lgkmcnt(1)
; __device__ __forceinline__ unsigned pk2(float lo, float hi) { f32x2 v = {lo, hi}; bf16x2_t b = __builtin_convertvector(v, bf16x2_t); return __builtin_bit_cast(unsigned, b); }
; #define MFMA32(a, b, c) __builtin_amdgcn_mfma_f32_32x32x16_bf16((a), (b), (c), 0, 0, 0)
; __device__ __forceinline__ void unpack8(const u32x4 w, float* v) { v[0] = bflo(w.x); v[1] = bfhi(w.x); v[2] = bflo(w.y); v[3] = bfhi(w.y); v[4] = bflo(w.z); v[5] = bfhi(w.z); v[6] = bflo(w.w); v[7] = bfhi(w.w); }
; template <int tbA, int tbB> ...
;     ...
;         for (int k = 0; k < NSB; ++k) {
;             float v[8]; unpack8(raw[k], v);
; #pragma unroll
;             for (int jj = 0; jj < 8; ++jj) { const float mean = stat[(16 * k + 8 * hh + jj) * 2 + so], rstd = stat[(16 * k + 8 * hh + jj) * 2 + 1 + so]; v[jj] = (v[jj] - mean) * rstd * gg + bb; }
;             u32x4 af; af.x = pk2(v[0], v[1]); af.y = pk2(v[2], v[3]); af.z = pk2(v[4], v[5]); af.w = pk2(v[6], v[7]);
;             accB = MFMA32(__builtin_bit_cast(bf16x8, af), wB[k], accB);
;             if (k < NSA) accA = MFMA32(__builtin_bit_cast(bf16x8, af), wA[k < NSA ? k : 0], accA);
	v_mov_b32_e32 v115, v110
	s_waitcnt lgkmcnt(0)
	v_mov_b32_e32 v114, v112
	v_pk_add_f32 v[68:69], v[68:69], v[114:115] neg_lo:[0,1] neg_hi:[0,1]
	v_mov_b32_e32 v110, v113
	v_pk_mul_f32 v[68:69], v[68:69], v[110:111]
	v_add_u32_e32 v112, 0x20b0, v74
	v_pk_fma_f32 v[2:3], v[60:61], v[2:3], v[62:63] op_sel_hi:[0,1,0]
	v_pk_fma_f32 v[110:111], v[60:61], v[68:69], v[62:63] op_sel_hi:[0,1,0]
	v_lshlrev_b32_e32 v68, 16, v71
	v_and_b32_e32 v69, 0xffff0000, v71
	ds_read2_b32 v[70:71], v70 offset1:1
	ds_read2_b32 v[112:113], v112 offset1:1
	v_cvt_pk_bf16_f32 v16, v8, v9
	v_cvt_pk_bf16_f32 v17, v0, v1
	v_cvt_pk_bf16_f32 v18, v10, v11
	v_cvt_pk_bf16_f32 v19, v2, v3
	s_waitcnt lgkmcnt(0)
	v_mov_b32_e32 v114, v112
	v_mov_b32_e32 v115, v70
	v_mfma_f32_32x32x16_bf16 v[0:15], v[16:19], v[4:7], 0
	v_add_f32_e64 v68, v68, -v114
	v_add_f32_e64 v69, v69, -v115
	v_mov_b32_e32 v70, v113
	v_mul_f32_e64 v68, v68, v70
	v_mul_f32_e64 v69, v69, v71
	v_pk_fma_f32 v[72:73], v[60:61], v[72:73], v[62:63] op_sel_hi:[0,1,0]
	v_pk_fma_f32 v[112:113], v[60:61], v[68:69], v[62:63] op_sel_hi:[0,1,0]
	v_cvt_pk_bf16_f32 v68, v72, v73
	v_cvt_pk_bf16_f32 v69, v108, v109
	v_cvt_pk_bf16_f32 v70, v110, v111
	v_cvt_pk_bf16_f32 v71, v112, v113
	v_add_u32_e32 v72, 0x2100, v74
	s_waitcnt vmcnt(0)
	v_mfma_f32_32x32x16_bf16 v[16:31], v[16:19], v[20:23], 0
	v_mfma_f32_32x32x16_bf16 v[0:15], v[68:71], v[76:79], v[0:15]
	v_mfma_f32_32x32x16_bf16 v[16:31], v[68:71], v[96:99], v[16:31]
	v_add_u32_e32 v70, 0x2108, v74
	ds_read2_b32 v[70:71], v70 offset1:1
	ds_read2_b32 v[72:73], v72 offset1:1
	v_lshlrev_b32_e32 v68, 16, v80
	v_and_b32_e32 v69, 0xffff0000, v80
	s_waitcnt lgkmcnt(1)
	v_mov_b32_e32 v77, v70
	s_waitcnt lgkmcnt(0)
	v_mov_b32_e32 v76, v72
	v_pk_add_f32 v[68:69], v[68:69], v[76:77] neg_lo:[0,1] neg_hi:[0,1]
	v_add_u32_e32 v76, 0x2110, v74
	v_add_u32_e32 v72, 0x2118, v74
	v_mov_b32_e32 v70, v73
	ds_read2_b32 v[72:73], v72 offset1:1
	ds_read2_b32 v[76:77], v76 offset1:1
	v_pk_mul_f32 v[68:69], v[68:69], v[70:71]
	v_lshlrev_b32_e32 v70, 16, v81
	v_and_b32_e32 v71, 0xffff0000, v81
	s_waitcnt lgkmcnt(1)
	v_mov_b32_e32 v79, v72
	s_waitcnt lgkmcnt(0)
	v_mov_b32_e32 v78, v76
	v_pk_add_f32 v[70:71], v[70:71], v[78:79] neg_lo:[0,1] neg_hi:[0,1]
	v_add_u32_e32 v78, 0x2120, v74
	v_add_u32_e32 v76, 0x2128, v74
	v_mov_b32_e32 v72, v77
	ds_read2_b32 v[76:77], v76 offset1:1
	ds_read2_b32 v[78:79], v78 offset1:1
	v_pk_mul_f32 v[70:71], v[70:71], v[72:73]
	v_lshlrev_b32_e32 v72, 16, v82
	v_and_b32_e32 v73, 0xffff0000, v82
	s_waitcnt lgkmcnt(1)
	v_mov_b32_e32 v81, v76
	s_waitcnt lgkmcnt(0)
	v_mov_b32_e32 v80, v78
	v_pk_add_f32 v[72:73], v[72:73], v[80:81] neg_lo:[0,1] neg_hi:[0,1]
	v_add_u32_e32 v80, 0x2130, v74
	v_add_u32_e32 v78, 0x2138, v74
	v_mov_b32_e32 v76, v79
	ds_read2_b32 v[78:79], v78 offset1:1
	ds_read2_b32 v[80:81], v80 offset1:1
	v_pk_mul_f32 v[72:73], v[72:73], v[76:77]
	v_lshlrev_b32_e32 v76, 16, v83
	v_and_b32_e32 v77, 0xffff0000, v83
	s_waitcnt lgkmcnt(1)
	v_mov_b32_e32 v83, v78
	s_waitcnt lgkmcnt(0)
	v_mov_b32_e32 v82, v80
	v_pk_add_f32 v[76:77], v[76:77], v[82:83] neg_lo:[0,1] neg_hi:[0,1]
	v_mov_b32_e32 v78, v81
	v_pk_mul_f32 v[76:77], v[76:77], v[78:79]
	v_pk_fma_f32 v[68:69], v[60:61], v[68:69], v[62:63] op_sel_hi:[0,1,0]
	v_pk_fma_f32 v[70:71], v[60:61], v[70:71], v[62:63] op_sel_hi:[0,1,0]
	v_pk_fma_f32 v[72:73], v[60:61], v[72:73], v[62:63] op_sel_hi:[0,1,0]
	v_pk_fma_f32 v[76:77], v[60:61], v[76:77], v[62:63] op_sel_hi:[0,1,0]
	v_cvt_pk_bf16_f32 v68, v68, v69
	v_cvt_pk_bf16_f32 v69, v70, v71
	v_cvt_pk_bf16_f32 v70, v72, v73
	v_cvt_pk_bf16_f32 v71, v76, v77
	v_add_u32_e32 v72, 0x2180, v74
	s_nop 0
	v_mfma_f32_32x32x16_bf16 v[0:15], v[68:71], v[84:87], v[0:15]
	v_mfma_f32_32x32x16_bf16 v[16:31], v[68:71], v[100:103], v[16:31]
	v_add_u32_e32 v70, 0x2188, v74
	ds_read2_b32 v[70:71], v70 offset1:1
	ds_read2_b32 v[72:73], v72 offset1:1
	v_lshlrev_b32_e32 v68, 16, v88
	v_and_b32_e32 v69, 0xffff0000, v88
	s_waitcnt lgkmcnt(1)
	v_mov_b32_e32 v77, v70
	s_waitcnt lgkmcnt(0)
	v_mov_b32_e32 v76, v72
	v_pk_add_f32 v[68:69], v[68:69], v[76:77] neg_lo:[0,1] neg_hi:[0,1]
	v_add_u32_e32 v76, 0x2190, v74
	v_add_u32_e32 v72, 0x2198, v74
	v_mov_b32_e32 v70, v73
	ds_read2_b32 v[72:73], v72 offset1:1
	ds_read2_b32 v[76:77], v76 offset1:1
	v_pk_mul_f32 v[68:69], v[68:69], v[70:71]
	v_lshlrev_b32_e32 v70, 16, v89
	v_and_b32_e32 v71, 0xffff0000, v89
	s_waitcnt lgkmcnt(1)
	v_mov_b32_e32 v79, v72
	s_waitcnt lgkmcnt(0)
	v_mov_b32_e32 v78, v76
	v_pk_add_f32 v[70:71], v[70:71], v[78:79] neg_lo:[0,1] neg_hi:[0,1]
	v_add_u32_e32 v78, 0x21a0, v74
	v_add_u32_e32 v76, 0x21a8, v74
	v_mov_b32_e32 v72, v77
	ds_read2_b32 v[76:77], v76 offset1:1
	ds_read2_b32 v[78:79], v78 offset1:1
	v_pk_mul_f32 v[70:71], v[70:71], v[72:73]
	v_lshlrev_b32_e32 v72, 16, v90
	v_and_b32_e32 v73, 0xffff0000, v90
	s_waitcnt lgkmcnt(1)
	v_mov_b32_e32 v81, v76
	s_waitcnt lgkmcnt(0)
	v_mov_b32_e32 v80, v78
	v_pk_add_f32 v[72:73], v[72:73], v[80:81] neg_lo:[0,1] neg_hi:[0,1]
	v_add_u32_e32 v80, 0x21b0, v74
	v_add_u32_e32 v78, 0x21b8, v74
	v_mov_b32_e32 v76, v79
	ds_read2_b32 v[78:79], v78 offset1:1
	ds_read2_b32 v[80:81], v80 offset1:1
	v_pk_mul_f32 v[72:73], v[72:73], v[76:77]
	v_lshlrev_b32_e32 v76, 16, v91
	v_and_b32_e32 v77, 0xffff0000, v91
	s_waitcnt lgkmcnt(1)
	v_mov_b32_e32 v83, v78
	s_waitcnt lgkmcnt(0)
; __device__ __forceinline__ unsigned pk2(float lo, float hi) { f32x2 v = {lo, hi}; bf16x2_t b = __builtin_convertvector(v, bf16x2_t); return __builtin_bit_cast(unsigned, b); }
; #define MFMA32(a, b, c) __builtin_amdgcn_mfma_f32_32x32x16_bf16((a), (b), (c), 0, 0, 0)
; __device__ __forceinline__ void unpack8(const u32x4 w, float* v) { v[0] = bflo(w.x); v[1] = bfhi(w.x); v[2] = bflo(w.y); v[3] = bfhi(w.y); v[4] = bflo(w.z); v[5] = bfhi(w.z); v[6] = bflo(w.w); v[7] = bfhi(w.w); }
; template <int tbA, int tbB> ...
;     ...
;         for (int k = 0; k < NSB; ++k) {
;             float v[8]; unpack8(raw[k], v);
; #pragma unroll
;             for (int jj = 0; jj < 8; ++jj) { const float mean = stat[(16 * k + 8 * hh + jj) * 2 + so], rstd = stat[(16 * k + 8 * hh + jj) * 2 + 1 + so]; v[jj] = (v[jj] - mean) * rstd * gg + bb; }
;             u32x4 af; af.x = pk2(v[0], v[1]); af.y = pk2(v[2], v[3]); af.z = pk2(v[4], v[5]); af.w = pk2(v[6], v[7]);
;             accB = MFMA32(__builtin_bit_cast(bf16x8, af), wB[k], accB);
;             if (k < NSA) accA = MFMA32(__builtin_bit_cast(bf16x8, af), wA[k < NSA ? k : 0], accA);
;         }
; #pragma unroll
;         for (int which = 0; which < 2; ++which) {
;             const int tb = which ? tbB : tbA; const f32x16& acc = which ? accB : accA;
;             const float sbv = spb[g * 128 + tb * 32 + r];
	v_mov_b32_e32 v82, v80
	v_pk_add_f32 v[76:77], v[76:77], v[82:83] neg_lo:[0,1] neg_hi:[0,1]
	v_mov_b32_e32 v78, v81
	v_pk_mul_f32 v[76:77], v[76:77], v[78:79]
	v_pk_fma_f32 v[68:69], v[60:61], v[68:69], v[62:63] op_sel_hi:[0,1,0]
	v_pk_fma_f32 v[70:71], v[60:61], v[70:71], v[62:63] op_sel_hi:[0,1,0]
	v_pk_fma_f32 v[72:73], v[60:61], v[72:73], v[62:63] op_sel_hi:[0,1,0]
	v_pk_fma_f32 v[76:77], v[60:61], v[76:77], v[62:63] op_sel_hi:[0,1,0]
	v_cvt_pk_bf16_f32 v68, v68, v69
	v_cvt_pk_bf16_f32 v69, v70, v71
	v_cvt_pk_bf16_f32 v70, v72, v73
	v_cvt_pk_bf16_f32 v71, v76, v77
	v_add_u32_e32 v72, 0x2200, v74
	s_nop 0
	v_mfma_f32_32x32x16_bf16 v[0:15], v[68:71], v[92:95], v[0:15]
	v_mfma_f32_32x32x16_bf16 v[16:31], v[68:71], v[104:107], v[16:31]
	v_lshlrev_b32_e32 v68, 16, v44
	v_and_b32_e32 v69, 0xffff0000, v44
	v_add_u32_e32 v44, 0x2208, v74
	ds_read2_b32 v[70:71], v44 offset1:1
	ds_read2_b32 v[72:73], v72 offset1:1
	v_lshlrev_b32_e32 v44, 16, v45
	v_and_b32_e32 v45, 0xffff0000, v45
	s_waitcnt lgkmcnt(1)
	v_mov_b32_e32 v77, v70
	s_waitcnt lgkmcnt(0)
	v_mov_b32_e32 v76, v72
	v_pk_add_f32 v[68:69], v[68:69], v[76:77] neg_lo:[0,1] neg_hi:[0,1]
	v_mov_b32_e32 v70, v73
	v_pk_mul_f32 v[68:69], v[68:69], v[70:71]
	v_add_u32_e32 v72, 0x2210, v74
	v_add_u32_e32 v70, 0x2218, v74
	ds_read2_b32 v[70:71], v70 offset1:1
	ds_read2_b32 v[72:73], v72 offset1:1
	v_pk_fma_f32 v[68:69], v[60:61], v[68:69], v[62:63] op_sel_hi:[0,1,0]
	s_waitcnt lgkmcnt(1)
	v_mov_b32_e32 v77, v70
	s_waitcnt lgkmcnt(0)
	v_mov_b32_e32 v76, v72
	v_pk_add_f32 v[44:45], v[44:45], v[76:77] neg_lo:[0,1] neg_hi:[0,1]
	v_mov_b32_e32 v70, v73
	v_pk_mul_f32 v[44:45], v[44:45], v[70:71]
	v_add_u32_e32 v76, 0x2220, v74
	v_pk_fma_f32 v[70:71], v[60:61], v[44:45], v[62:63] op_sel_hi:[0,1,0]
	v_lshlrev_b32_e32 v44, 16, v46
	v_and_b32_e32 v45, 0xffff0000, v46
	v_add_u32_e32 v46, 0x2228, v74
	ds_read2_b32 v[72:73], v46 offset1:1
	ds_read2_b32 v[76:77], v76 offset1:1
	v_add_u32_e32 v46, 0x2238, v74
	s_waitcnt lgkmcnt(1)
	v_mov_b32_e32 v79, v72
	s_waitcnt lgkmcnt(0)
	v_mov_b32_e32 v78, v76
	v_pk_add_f32 v[44:45], v[44:45], v[78:79] neg_lo:[0,1] neg_hi:[0,1]
	v_mov_b32_e32 v72, v77
	v_pk_mul_f32 v[44:45], v[44:45], v[72:73]
	v_add_u32_e32 v76, 0x2230, v74
	v_pk_fma_f32 v[72:73], v[60:61], v[44:45], v[62:63] op_sel_hi:[0,1,0]
	v_lshlrev_b32_e32 v44, 16, v47
	v_and_b32_e32 v45, 0xffff0000, v47
	ds_read2_b32 v[46:47], v46 offset1:1
	ds_read2_b32 v[76:77], v76 offset1:1
	s_waitcnt lgkmcnt(1)
	v_mov_b32_e32 v79, v46
	s_waitcnt lgkmcnt(0)
	v_mov_b32_e32 v78, v76
	v_pk_add_f32 v[44:45], v[44:45], v[78:79] neg_lo:[0,1] neg_hi:[0,1]
	v_mov_b32_e32 v46, v77
	v_pk_mul_f32 v[44:45], v[44:45], v[46:47]
	v_cvt_pk_bf16_f32 v46, v72, v73
	v_pk_fma_f32 v[76:77], v[60:61], v[44:45], v[62:63] op_sel_hi:[0,1,0]
	v_cvt_pk_bf16_f32 v44, v68, v69
	v_cvt_pk_bf16_f32 v45, v70, v71
	v_cvt_pk_bf16_f32 v47, v76, v77
	s_nop 1
	v_mfma_f32_32x32x16_bf16 v[0:15], v[44:47], v[40:43], v[0:15]
	v_add_u32_e32 v44, 0x2280, v74
	v_lshlrev_b32_e32 v40, 16, v36
	v_and_b32_e32 v41, 0xffff0000, v36
	v_add_u32_e32 v36, 0x2288, v74
	ds_read2_b32 v[42:43], v36 offset1:1
	ds_read2_b32 v[44:45], v44 offset1:1
	v_lshlrev_b32_e32 v36, 16, v37
	v_and_b32_e32 v37, 0xffff0000, v37
	s_waitcnt lgkmcnt(1)
	v_mov_b32_e32 v47, v42
	s_waitcnt lgkmcnt(0)
	v_mov_b32_e32 v46, v44
	v_pk_add_f32 v[40:41], v[40:41], v[46:47] neg_lo:[0,1] neg_hi:[0,1]
	v_mov_b32_e32 v42, v45
	v_pk_mul_f32 v[40:41], v[40:41], v[42:43]
	v_add_u32_e32 v44, 0x2290, v74
	v_add_u32_e32 v42, 0x2298, v74
	ds_read2_b32 v[42:43], v42 offset1:1
	ds_read2_b32 v[44:45], v44 offset1:1
	v_pk_fma_f32 v[40:41], v[60:61], v[40:41], v[62:63] op_sel_hi:[0,1,0]
	s_waitcnt lgkmcnt(1)
	v_mov_b32_e32 v47, v42
	s_waitcnt lgkmcnt(0)
	v_mov_b32_e32 v46, v44
	v_pk_add_f32 v[36:37], v[36:37], v[46:47] neg_lo:[0,1] neg_hi:[0,1]
	v_mov_b32_e32 v42, v45
	v_pk_mul_f32 v[36:37], v[36:37], v[42:43]
	v_add_u32_e32 v46, 0x22a0, v74
	v_pk_fma_f32 v[42:43], v[60:61], v[36:37], v[62:63] op_sel_hi:[0,1,0]
	v_lshlrev_b32_e32 v36, 16, v38
	v_and_b32_e32 v37, 0xffff0000, v38
	v_add_u32_e32 v38, 0x22a8, v74
	ds_read2_b32 v[44:45], v38 offset1:1
	ds_read2_b32 v[46:47], v46 offset1:1
	v_add_u32_e32 v38, 0x22b8, v74
	s_waitcnt lgkmcnt(1)
	v_mov_b32_e32 v69, v44
	s_waitcnt lgkmcnt(0)
	v_mov_b32_e32 v68, v46
	v_pk_add_f32 v[36:37], v[36:37], v[68:69] neg_lo:[0,1] neg_hi:[0,1]
	v_mov_b32_e32 v44, v47
	v_pk_mul_f32 v[36:37], v[36:37], v[44:45]
	v_add_u32_e32 v46, 0x22b0, v74
	v_pk_fma_f32 v[44:45], v[60:61], v[36:37], v[62:63] op_sel_hi:[0,1,0]
	v_lshlrev_b32_e32 v36, 16, v39
	v_and_b32_e32 v37, 0xffff0000, v39
	ds_read2_b32 v[38:39], v38 offset1:1
	ds_read2_b32 v[46:47], v46 offset1:1
	s_waitcnt lgkmcnt(1)
	v_mov_b32_e32 v69, v38
	s_waitcnt lgkmcnt(0)
	v_mov_b32_e32 v68, v46
	v_pk_add_f32 v[36:37], v[36:37], v[68:69] neg_lo:[0,1] neg_hi:[0,1]
	v_mov_b32_e32 v38, v47
	v_pk_mul_f32 v[36:37], v[36:37], v[38:39]
	v_cvt_pk_bf16_f32 v38, v44, v45
	v_pk_fma_f32 v[46:47], v[60:61], v[36:37], v[62:63] op_sel_hi:[0,1,0]
	v_cvt_pk_bf16_f32 v36, v40, v41
	v_cvt_pk_bf16_f32 v37, v42, v43
	v_cvt_pk_bf16_f32 v39, v46, v47
	s_nop 1
	v_mfma_f32_32x32x16_bf16 v[0:15], v[36:39], v[32:35], v[0:15]
	global_load_dword v32, v[50:51], off offset:-128
	s_waitcnt vmcnt(0)
; #define LAS __attribute__((address_space(3)))
; __device__ __forceinline__ unsigned pk2(float lo, float hi) { f32x2 v = {lo, hi}; bf16x2_t b = __builtin_convertvector(v, bf16x2_t); return __builtin_bit_cast(unsigned, b); }
; __device__ __forceinline__ float bflo(unsigned u) { return __uint_as_float(u << 16); }
; __device__ __forceinline__ float bfhi(unsigned u) { return __uint_as_float(u & 0xffff0000u); }
; template <int tbA, int tbB> ...
;     ...
;         for (int which = 0; which < 2; ++which) {
;             const int tb = which ? tbB : tbA; const f32x16& acc = which ? accB : accA;
;             const float sbv = spb[g * 128 + tb * 32 + r];
; #pragma unroll
;             for (int q = 0; q < 4; ++q) {
;                 u32x2 w; w.x = pk2(acc[4 * q + 0] + sbv, acc[4 * q + 1] + sbv); w.y = pk2(acc[4 * q + 2] + sbv, acc[4 * q + 3] + sbv);
;                 *(LAS u32x2*)(stg + which * 2560 + r * 80 + (8 * q + 4 * hh) * 2) = w;
;             }
;         }
; #pragma unroll
;         for (int which = 0; which < 2; ++which) {
;             const int tb = which ? tbB : tbA;
; #pragma unroll
;             for (int i = 0; i < 2; ++i) {
;                 const int t = (lane >> 2) + 16 * i, ck = lane & 3;
;                 const size_t a = (size_t)(tok0 + tb * 32 + t) * DH + g * 128 + cb * 32 + ck * 8;
;                 const u32x4 uu = *(const u32x4*)(U + a), gc = *(const u32x4*)(GC + a);
;                 const u32x4 mv = *(const LAS u32x4*)(stg + which * 2560 + t * 80 + ck * 16);
;                 u32x4 o; o.x = pk2(bflo(uu.x) * bflo(mv.x) * bflo(gc.x), bfhi(uu.x) * bfhi(mv.x) * bfhi(gc.x)); o.y = pk2(bflo(uu.y) * bflo(mv.y) * bflo(gc.y), bfhi(uu.y) * bfhi(mv.y) * bfhi(gc.y));
;                 o.z = pk2(bflo(uu.z) * bflo(mv.z) * bflo(gc.z), bfhi(uu.z) * bfhi(mv.z) * bfhi(gc.z)); o.w = pk2(bflo(uu.w) * bflo(mv.w) * bflo(gc.w), bfhi(uu.w) * bfhi(mv.w) * bfhi(gc.w));
;                 *(u32x4*)(OC + a) = o;
;             }
	v_add_f32_e64 v16, v16, v32
	v_add_f32_e64 v17, v17, v32
	v_add_f32_e64 v18, v18, v32
	v_add_f32_e64 v19, v19, v32
	v_cvt_pk_bf16_f32 v16, v16, v17
	v_cvt_pk_bf16_f32 v17, v18, v19
	v_pk_add_f32 v[18:19], v[20:21], v[32:33] op_sel_hi:[1,0]
	v_pk_add_f32 v[20:21], v[22:23], v[32:33] op_sel_hi:[1,0]
	v_cvt_pk_bf16_f32 v18, v18, v19
	v_cvt_pk_bf16_f32 v19, v20, v21
	v_add_u32_e32 v22, 0x4000, v67
	ds_write2_b64 v22, v[16:17], v[18:19] offset1:2
	v_pk_add_f32 v[16:17], v[24:25], v[32:33] op_sel_hi:[1,0]
	v_pk_add_f32 v[18:19], v[26:27], v[32:33] op_sel_hi:[1,0]
	v_cvt_pk_bf16_f32 v16, v16, v17
	v_cvt_pk_bf16_f32 v17, v18, v19
	v_pk_add_f32 v[18:19], v[28:29], v[32:33] op_sel_hi:[1,0]
	v_pk_add_f32 v[20:21], v[30:31], v[32:33] op_sel_hi:[1,0]
	v_cvt_pk_bf16_f32 v18, v18, v19
	v_cvt_pk_bf16_f32 v19, v20, v21
	ds_write2_b64 v22, v[16:17], v[18:19] offset0:4 offset1:6
	global_load_dword v16, v[50:51], off
	v_add_u32_e32 v18, s8, v66
	v_add_u32_e32 v132, 0xfa008000, v18
	s_addk_i32 s8, 0x80
	v_lshl_add_u64 v[50:51], v[50:51], 0, s[62:63]
	s_cmpk_lg_i32 s8, 0x200
	s_waitcnt vmcnt(0)
	v_pk_add_f32 v[0:1], v[0:1], v[16:17] op_sel_hi:[1,0]
	v_pk_add_f32 v[2:3], v[2:3], v[16:17] op_sel_hi:[1,0]
	v_cvt_pk_bf16_f32 v0, v0, v1
	v_cvt_pk_bf16_f32 v1, v2, v3
	v_pk_add_f32 v[2:3], v[4:5], v[16:17] op_sel_hi:[1,0]
	v_pk_add_f32 v[4:5], v[6:7], v[16:17] op_sel_hi:[1,0]
	v_cvt_pk_bf16_f32 v2, v2, v3
	v_cvt_pk_bf16_f32 v3, v4, v5
	v_add_u32_e32 v6, 0x4800, v67
	ds_write2_b64 v6, v[0:1], v[2:3] offset0:64 offset1:66
	v_pk_add_f32 v[0:1], v[8:9], v[16:17] op_sel_hi:[1,0]
	v_pk_add_f32 v[2:3], v[10:11], v[16:17] op_sel_hi:[1,0]
	v_cvt_pk_bf16_f32 v0, v0, v1
	v_cvt_pk_bf16_f32 v1, v2, v3
	v_pk_add_f32 v[2:3], v[12:13], v[16:17] op_sel_hi:[1,0]
	v_pk_add_f32 v[4:5], v[14:15], v[16:17] op_sel_hi:[1,0]
	v_cvt_pk_bf16_f32 v2, v2, v3
	v_cvt_pk_bf16_f32 v3, v4, v5
	v_lshlrev_b64 v[12:13], 1, v[132:133]
	ds_write2_b64 v6, v[0:1], v[2:3] offset0:68 offset1:70
	v_lshl_add_u64 v[0:1], s[30:31], 0, v[12:13]
	global_load_dwordx4 v[0:3], v[0:1], off
	v_lshl_add_u64 v[4:5], s[34:35], 0, v[12:13]
	global_load_dwordx4 v[4:7], v[4:5], off
	ds_read_b128 v[8:11], v75 offset:16384
	v_add_u32_e32 v132, 0xfa00c000, v18
	s_waitcnt lgkmcnt(0)
	v_lshlrev_b32_e32 v16, 16, v8
	v_and_b32_e32 v17, 0xffff0000, v8
	v_lshlrev_b32_e32 v8, 16, v9
	v_and_b32_e32 v9, 0xffff0000, v9
	s_waitcnt vmcnt(1)
	v_lshlrev_b32_e32 v14, 16, v0
	v_and_b32_e32 v15, 0xffff0000, v0
	v_pk_mul_f32 v[14:15], v[14:15], v[16:17]
	s_waitcnt vmcnt(0)
	v_lshlrev_b32_e32 v16, 16, v4
	v_and_b32_e32 v17, 0xffff0000, v4
	v_pk_mul_f32 v[14:15], v[14:15], v[16:17]
	v_lshlrev_b32_e32 v4, 16, v5
	v_cvt_pk_bf16_f32 v0, v14, v15
	v_lshlrev_b32_e32 v14, 16, v1
	v_and_b32_e32 v15, 0xffff0000, v1
	v_pk_mul_f32 v[8:9], v[14:15], v[8:9]
	v_and_b32_e32 v5, 0xffff0000, v5
	v_pk_mul_f32 v[4:5], v[8:9], v[4:5]
	v_lshlrev_b32_e32 v8, 16, v10
	v_cvt_pk_bf16_f32 v1, v4, v5
	v_lshlrev_b32_e32 v4, 16, v2
	v_and_b32_e32 v5, 0xffff0000, v2
	v_and_b32_e32 v9, 0xffff0000, v10
	v_pk_mul_f32 v[4:5], v[4:5], v[8:9]
	v_lshlrev_b32_e32 v8, 16, v6
	v_and_b32_e32 v9, 0xffff0000, v6
	v_pk_mul_f32 v[4:5], v[4:5], v[8:9]
	v_lshlrev_b32_e32 v8, 16, v11
	v_cvt_pk_bf16_f32 v2, v4, v5
	v_lshlrev_b32_e32 v4, 16, v3
	v_and_b32_e32 v5, 0xffff0000, v3
	v_and_b32_e32 v9, 0xffff0000, v11
	v_pk_mul_f32 v[4:5], v[4:5], v[8:9]
	v_lshlrev_b32_e32 v6, 16, v7
	v_and_b32_e32 v7, 0xffff0000, v7
	v_pk_mul_f32 v[4:5], v[4:5], v[6:7]
	ds_read_b128 v[8:11], v75 offset:17664
	v_cvt_pk_bf16_f32 v3, v4, v5
	v_lshl_add_u64 v[4:5], s[36:37], 0, v[12:13]
	v_lshlrev_b64 v[12:13], 1, v[132:133]
	global_store_dwordx4 v[4:5], v[0:3], off
	v_lshl_add_u64 v[4:5], s[34:35], 0, v[12:13]
	global_load_dwordx4 v[4:7], v[4:5], off
	v_lshl_add_u64 v[0:1], s[30:31], 0, v[12:13]
	global_load_dwordx4 v[0:3], v[0:1], off
	s_waitcnt lgkmcnt(0)
	v_lshlrev_b32_e32 v16, 16, v8
	v_and_b32_e32 v17, 0xffff0000, v8
	v_lshlrev_b32_e32 v8, 16, v9
	v_and_b32_e32 v9, 0xffff0000, v9
	v_add_u32_e32 v132, 0xfa010000, v18
	s_waitcnt vmcnt(0)
; #define LAS __attribute__((address_space(3)))
; __device__ __forceinline__ unsigned pk2(float lo, float hi) { f32x2 v = {lo, hi}; bf16x2_t b = __builtin_convertvector(v, bf16x2_t); return __builtin_bit_cast(unsigned, b); }
; __device__ __forceinline__ float bflo(unsigned u) { return __uint_as_float(u << 16); }
; __device__ __forceinline__ float bfhi(unsigned u) { return __uint_as_float(u & 0xffff0000u); }
; template <int tbA, int tbB> ...
;     ...
;             for (int i = 0; i < 2; ++i) {
;                 const int t = (lane >> 2) + 16 * i, ck = lane & 3;
;                 const size_t a = (size_t)(tok0 + tb * 32 + t) * DH + g * 128 + cb * 32 + ck * 8;
;                 const u32x4 uu = *(const u32x4*)(U + a), gc = *(const u32x4*)(GC + a);
;                 const u32x4 mv = *(const LAS u32x4*)(stg + which * 2560 + t * 80 + ck * 16);
;                 u32x4 o; o.x = pk2(bflo(uu.x) * bflo(mv.x) * bflo(gc.x), bfhi(uu.x) * bfhi(mv.x) * bfhi(gc.x)); o.y = pk2(bflo(uu.y) * bflo(mv.y) * bflo(gc.y), bfhi(uu.y) * bfhi(mv.y) * bfhi(gc.y));
;                 o.z = pk2(bflo(uu.z) * bflo(mv.z) * bflo(gc.z), bfhi(uu.z) * bfhi(mv.z) * bfhi(gc.z)); o.w = pk2(bflo(uu.w) * bflo(mv.w) * bflo(gc.w), bfhi(uu.w) * bfhi(mv.w) * bfhi(gc.w));
;                 *(u32x4*)(OC + a) = o;
;             }
	v_lshlrev_b32_e32 v14, 16, v0
	v_and_b32_e32 v15, 0xffff0000, v0
	v_pk_mul_f32 v[14:15], v[14:15], v[16:17]
	v_lshlrev_b32_e32 v16, 16, v4
	v_and_b32_e32 v17, 0xffff0000, v4
	v_pk_mul_f32 v[14:15], v[14:15], v[16:17]
	v_lshlrev_b32_e32 v4, 16, v5
	v_cvt_pk_bf16_f32 v0, v14, v15
	v_lshlrev_b32_e32 v14, 16, v1
	v_and_b32_e32 v15, 0xffff0000, v1
	v_pk_mul_f32 v[8:9], v[14:15], v[8:9]
	v_and_b32_e32 v5, 0xffff0000, v5
	v_pk_mul_f32 v[4:5], v[8:9], v[4:5]
	v_lshlrev_b32_e32 v8, 16, v10
	v_cvt_pk_bf16_f32 v1, v4, v5
	v_lshlrev_b32_e32 v4, 16, v2
	v_and_b32_e32 v5, 0xffff0000, v2
	v_and_b32_e32 v9, 0xffff0000, v10
	v_pk_mul_f32 v[4:5], v[4:5], v[8:9]
	v_lshlrev_b32_e32 v8, 16, v6
	v_and_b32_e32 v9, 0xffff0000, v6
	v_pk_mul_f32 v[4:5], v[4:5], v[8:9]
	v_lshlrev_b32_e32 v8, 16, v11
	v_cvt_pk_bf16_f32 v2, v4, v5
	v_lshlrev_b32_e32 v4, 16, v3
	v_and_b32_e32 v5, 0xffff0000, v3
	v_and_b32_e32 v9, 0xffff0000, v11
	v_pk_mul_f32 v[4:5], v[4:5], v[8:9]
	v_lshlrev_b32_e32 v6, 16, v7
	v_and_b32_e32 v7, 0xffff0000, v7
	v_pk_mul_f32 v[4:5], v[4:5], v[6:7]
	ds_read_b128 v[8:11], v75 offset:18944
	v_cvt_pk_bf16_f32 v3, v4, v5
	v_lshl_add_u64 v[4:5], s[36:37], 0, v[12:13]
	v_lshlrev_b64 v[12:13], 1, v[132:133]
	global_store_dwordx4 v[4:5], v[0:3], off
	v_lshl_add_u64 v[4:5], s[34:35], 0, v[12:13]
	global_load_dwordx4 v[4:7], v[4:5], off
	v_lshl_add_u64 v[0:1], s[30:31], 0, v[12:13]
	global_load_dwordx4 v[0:3], v[0:1], off
	s_waitcnt lgkmcnt(0)
	v_lshlrev_b32_e32 v16, 16, v8
	v_and_b32_e32 v17, 0xffff0000, v8
	v_lshlrev_b32_e32 v8, 16, v9
	v_and_b32_e32 v9, 0xffff0000, v9
	v_add_u32_e32 v132, 0xfa014000, v18
	s_waitcnt vmcnt(0)
	v_lshlrev_b32_e32 v14, 16, v0
	v_and_b32_e32 v15, 0xffff0000, v0
	v_pk_mul_f32 v[14:15], v[14:15], v[16:17]
	v_lshlrev_b32_e32 v16, 16, v4
	v_and_b32_e32 v17, 0xffff0000, v4
	v_pk_mul_f32 v[14:15], v[14:15], v[16:17]
	v_lshlrev_b32_e32 v4, 16, v5
	v_cvt_pk_bf16_f32 v0, v14, v15
	v_lshlrev_b32_e32 v14, 16, v1
	v_and_b32_e32 v15, 0xffff0000, v1
	v_pk_mul_f32 v[8:9], v[14:15], v[8:9]
	v_and_b32_e32 v5, 0xffff0000, v5
	v_pk_mul_f32 v[4:5], v[8:9], v[4:5]
	v_lshlrev_b32_e32 v8, 16, v10
	v_cvt_pk_bf16_f32 v1, v4, v5
	v_lshlrev_b32_e32 v4, 16, v2
	v_and_b32_e32 v5, 0xffff0000, v2
	v_and_b32_e32 v9, 0xffff0000, v10
	v_pk_mul_f32 v[4:5], v[4:5], v[8:9]
	v_lshlrev_b32_e32 v8, 16, v6
	v_and_b32_e32 v9, 0xffff0000, v6
	v_pk_mul_f32 v[4:5], v[4:5], v[8:9]
	v_lshlrev_b32_e32 v8, 16, v11
	v_cvt_pk_bf16_f32 v2, v4, v5
	v_lshlrev_b32_e32 v4, 16, v3
	v_and_b32_e32 v5, 0xffff0000, v3
	v_and_b32_e32 v9, 0xffff0000, v11
	v_pk_mul_f32 v[4:5], v[4:5], v[8:9]
	v_lshlrev_b32_e32 v6, 16, v7
	v_and_b32_e32 v7, 0xffff0000, v7
	v_pk_mul_f32 v[4:5], v[4:5], v[6:7]
	ds_read_b128 v[8:11], v75 offset:20224
	v_cvt_pk_bf16_f32 v3, v4, v5
	v_lshl_add_u64 v[4:5], s[36:37], 0, v[12:13]
	v_lshlrev_b64 v[12:13], 1, v[132:133]
	global_store_dwordx4 v[4:5], v[0:3], off
	v_lshl_add_u64 v[4:5], s[34:35], 0, v[12:13]
	global_load_dwordx4 v[4:7], v[4:5], off
	v_lshl_add_u64 v[0:1], s[30:31], 0, v[12:13]
	global_load_dwordx4 v[0:3], v[0:1], off
	s_waitcnt lgkmcnt(0)
	v_lshlrev_b32_e32 v16, 16, v8
	v_and_b32_e32 v17, 0xffff0000, v8
	v_lshlrev_b32_e32 v8, 16, v9
	v_and_b32_e32 v9, 0xffff0000, v9
	s_waitcnt vmcnt(0)
	v_lshlrev_b32_e32 v14, 16, v0
	v_and_b32_e32 v15, 0xffff0000, v0
	v_pk_mul_f32 v[14:15], v[14:15], v[16:17]
	v_lshlrev_b32_e32 v16, 16, v4
	v_and_b32_e32 v17, 0xffff0000, v4
	v_pk_mul_f32 v[14:15], v[14:15], v[16:17]
	v_lshlrev_b32_e32 v4, 16, v5
	v_cvt_pk_bf16_f32 v0, v14, v15
	v_lshlrev_b32_e32 v14, 16, v1
	v_and_b32_e32 v15, 0xffff0000, v1
	v_pk_mul_f32 v[8:9], v[14:15], v[8:9]
	v_and_b32_e32 v5, 0xffff0000, v5
	v_pk_mul_f32 v[4:5], v[8:9], v[4:5]
	v_lshlrev_b32_e32 v8, 16, v10
	v_cvt_pk_bf16_f32 v1, v4, v5
	v_lshlrev_b32_e32 v4, 16, v2
	v_and_b32_e32 v5, 0xffff0000, v2
	v_and_b32_e32 v9, 0xffff0000, v10
	v_pk_mul_f32 v[4:5], v[4:5], v[8:9]
	v_lshlrev_b32_e32 v8, 16, v6
	v_and_b32_e32 v9, 0xffff0000, v6
	v_pk_mul_f32 v[4:5], v[4:5], v[8:9]
	v_lshlrev_b32_e32 v8, 16, v11
	v_cvt_pk_bf16_f32 v2, v4, v5
	v_lshlrev_b32_e32 v4, 16, v3
	v_and_b32_e32 v5, 0xffff0000, v3
	v_and_b32_e32 v9, 0xffff0000, v11
	v_pk_mul_f32 v[4:5], v[4:5], v[8:9]
	v_lshlrev_b32_e32 v6, 16, v7
	v_and_b32_e32 v7, 0xffff0000, v7
	v_pk_mul_f32 v[4:5], v[4:5], v[6:7]
	s_nop 0
	v_cvt_pk_bf16_f32 v3, v4, v5
	v_lshl_add_u64 v[4:5], s[36:37], 0, v[12:13]
	global_store_dwordx4 v[4:5], v[0:3], off
	s_cbranch_scc1 .LBB0_653
	s_mov_b64 s[8:9], 0

; __device__ __forceinline__ unsigned pk2(float lo, float hi) { f32x2 v = {lo, hi}; bf16x2_t b = __builtin_convertvector(v, bf16x2_t); return __builtin_bit_cast(unsigned, b); }
; #define MFMA32(a, b, c) __builtin_amdgcn_mfma_f32_32x32x16_bf16((a), (b), (c), 0, 0, 0)
; __device__ __forceinline__ void unpack8(const u32x4 w, float* v) { v[0] = bflo(w.x); v[1] = bfhi(w.x); v[2] = bflo(w.y); v[3] = bfhi(w.y); v[4] = bflo(w.z); v[5] = bfhi(w.z); v[6] = bflo(w.w); v[7] = bfhi(w.w); }
; template <int tbA, int tbB> ...
;     for (int gi = 0; gi < 4; ++gi) {
;         const int g = gh * 4 + gi;
;         const int ch = g * 128 + cb * 32 + r;
;         const float gg = lng[ch], bb = lnb[ch];
;         const bf16_t* ap = VCT + (size_t)ch * PT + tok0 + 8 * hh;
;         const bf16_t* wp = Wbf + (size_t)g * 16384 + 8 * hh;
;         constexpr int NSB = (tbB + 1) * 2, NSA = (tbA + 1) * 2;
;         int so = 0; asm volatile("" : "+v"(so));
;         u32x4 raw[NSB]; bf16x8 wB[NSB], wA[NSA];
; #pragma unroll
;         for (int k = 0; k < NSB; ++k) { raw[k] = *(const u32x4*)(ap + 16 * k); wB[k] = *(const bf16x8*)(wp + (size_t)(tbB * 32 + r) * 128 + 16 * k); }
; #pragma unroll
;         for (int k = 0; k < NSA; ++k) wA[k] = *(const bf16x8*)(wp + (size_t)(tbA * 32 + r) * 128 + 16 * k);
;         f32x16 accA, accB;
; #pragma unroll
;         for (int i = 0; i < 16; ++i) { accA[i] = 0.f; accB[i] = 0.f; }
; #pragma unroll
;         for (int k = 0; k < NSB; ++k) {
;             float v[8]; unpack8(raw[k], v);
; #pragma unroll
;             for (int jj = 0; jj < 8; ++jj) { const float mean = stat[(16 * k + 8 * hh + jj) * 2 + so], rstd = stat[(16 * k + 8 * hh + jj) * 2 + 1 + so]; v[jj] = (v[jj] - mean) * rstd * gg + bb; }
;             u32x4 af; af.x = pk2(v[0], v[1]); af.y = pk2(v[2], v[3]); af.z = pk2(v[4], v[5]); af.w = pk2(v[6], v[7]);
;             accB = MFMA32(__builtin_bit_cast(bf16x8, af), wB[k], accB);
;     ...
;                 const int t = (lane >> 2) + 16 * i, ck = lane & 3;
;                 const size_t a = (size_t)(tok0 + tb * 32 + t) * DH + g * 128 + cb * 32 + ck * 8;
;                 const u32x4 uu = *(const u32x4*)(U + a), gc = *(const u32x4*)(GC + a);
.LBB0_657:
	v_lshl_add_u64 v[8:9], v[68:69], 0, v[148:149]
	v_mov_b32_e32 v14, 0
	global_load_dword v74, v[72:73], off
	global_load_dword v76, v[70:71], off
	global_load_dwordx4 v[0:3], v[8:9], off offset:-128
	v_lshl_add_u64 v[10:11], v[64:65], 0, v[148:149]
	v_add_co_u32_e32 v12, vcc, s94, v10
	v_lshl_add_u32 v79, v14, 2, v158
	s_nop 0
	v_addc_co_u32_e32 v13, vcc, 0, v11, vcc
	v_add_co_u32_e32 v20, vcc, s95, v10
	global_load_dwordx4 v[4:7], v[12:13], off
	global_load_dwordx4 v[80:83], v[8:9], off offset:-96
	global_load_dwordx4 v[84:87], v[12:13], off offset:32
	global_load_dwordx4 v[88:91], v[8:9], off offset:-64
	global_load_dwordx4 v[92:95], v[12:13], off offset:64
	global_load_dwordx4 v[96:99], v[8:9], off offset:-32
	global_load_dwordx4 v[100:103], v[12:13], off offset:96
	global_load_dwordx4 v[60:63], v[8:9], off
	global_load_dwordx4 v[56:59], v[12:13], off offset:128
	global_load_dwordx4 v[52:55], v[8:9], off offset:32
	global_load_dwordx4 v[48:51], v[12:13], off offset:160
	global_load_dwordx4 v[44:47], v[8:9], off offset:64
	global_load_dwordx4 v[40:43], v[12:13], off offset:192
	global_load_dwordx4 v[36:39], v[8:9], off offset:96
	global_load_dwordx4 v[32:35], v[12:13], off offset:224
	v_addc_co_u32_e32 v21, vcc, 0, v11, vcc
	v_add_u32_e32 v12, 0x2000, v79
	global_load_dwordx4 v[104:107], v[20:21], off offset:32
	v_add_u32_e32 v112, 0x2080, v79
	v_lshl_add_u64 v[64:65], v[64:65], 0, s[58:59]
	v_lshl_add_u64 v[68:69], v[68:69], 0, s[60:61]
	v_lshl_add_u64 v[70:71], v[70:71], 0, s[62:63]
	v_lshl_add_u64 v[72:73], v[72:73], 0, s[62:63]
	v_add_u32_e32 v120, s8, v77
	v_add_u32_e32 v122, 0xfa000000, v120
	v_mov_b32_e32 v123, 0
	v_lshlrev_b64 v[122:123], 1, v[122:123]
	v_lshl_add_u64 v[124:125], s[30:31], 0, v[122:123]
	global_load_dword v126, v[124:125], off
	v_lshl_add_u64 v[124:125], s[34:35], 0, v[122:123]
	global_load_dword v126, v[124:125], off
	v_add_u32_e32 v122, 0xfa004000, v120
	v_mov_b32_e32 v123, 0
	v_lshlrev_b64 v[122:123], 1, v[122:123]
	v_lshl_add_u64 v[124:125], s[30:31], 0, v[122:123]
	global_load_dword v126, v[124:125], off
	v_lshl_add_u64 v[124:125], s[34:35], 0, v[122:123]
	global_load_dword v126, v[124:125], off
	v_add_u32_e32 v122, 0xfa018000, v120
	v_mov_b32_e32 v123, 0
	v_lshlrev_b64 v[122:123], 1, v[122:123]
	v_lshl_add_u64 v[124:125], s[30:31], 0, v[122:123]
	global_load_dword v126, v[124:125], off
	v_lshl_add_u64 v[124:125], s[34:35], 0, v[122:123]
	global_load_dword v126, v[124:125], off
	v_add_u32_e32 v122, 0xfa01c000, v120
	v_mov_b32_e32 v123, 0
	v_lshlrev_b64 v[122:123], 1, v[122:123]
	v_lshl_add_u64 v[124:125], s[30:31], 0, v[122:123]
	global_load_dword v126, v[124:125], off
	v_lshl_add_u64 v[124:125], s[34:35], 0, v[122:123]
	global_load_dword v126, v[124:125], off
	s_waitcnt vmcnt(22)
	v_lshlrev_b32_e32 v108, 16, v80
	v_and_b32_e32 v109, 0xffff0000, v80
	v_add_u32_e32 v80, 0x2088, v79
	v_lshlrev_b32_e32 v8, 16, v0
	v_and_b32_e32 v9, 0xffff0000, v0
	v_add_u32_e32 v0, 0x2008, v79
	ds_read2_b32 v[10:11], v0 offset1:1
	ds_read2_b32 v[12:13], v12 offset1:1
	v_lshlrev_b32_e32 v0, 16, v1
	v_and_b32_e32 v1, 0xffff0000, v1
	s_waitcnt lgkmcnt(1)
	v_mov_b32_e32 v15, v10
	s_waitcnt lgkmcnt(0)
	v_mov_b32_e32 v14, v12
	v_pk_add_f32 v[8:9], v[8:9], v[14:15] neg_lo:[0,1] neg_hi:[0,1]
	v_mov_b32_e32 v10, v13
	v_pk_mul_f32 v[8:9], v[8:9], v[10:11]
	v_add_u32_e32 v12, 0x2010, v79
	v_add_u32_e32 v10, 0x2018, v79
	ds_read2_b32 v[10:11], v10 offset1:1
	ds_read2_b32 v[12:13], v12 offset1:1
	v_pk_fma_f32 v[8:9], v[74:75], v[8:9], v[76:77] op_sel_hi:[0,1,0]
	s_waitcnt lgkmcnt(1)
	v_mov_b32_e32 v15, v10
	s_waitcnt lgkmcnt(0)
	v_mov_b32_e32 v14, v12
	v_pk_add_f32 v[0:1], v[0:1], v[14:15] neg_lo:[0,1] neg_hi:[0,1]
	v_mov_b32_e32 v10, v13
	v_pk_mul_f32 v[0:1], v[0:1], v[10:11]
	v_add_u32_e32 v14, 0x2020, v79
	v_lshlrev_b32_e32 v10, 16, v2
	v_and_b32_e32 v11, 0xffff0000, v2
	v_add_u32_e32 v2, 0x2028, v79
	ds_read2_b32 v[12:13], v2 offset1:1
	ds_read2_b32 v[14:15], v14 offset1:1
	v_lshlrev_b32_e32 v2, 16, v3
	v_and_b32_e32 v3, 0xffff0000, v3
	v_pk_fma_f32 v[0:1], v[74:75], v[0:1], v[76:77] op_sel_hi:[0,1,0]
	s_waitcnt lgkmcnt(1)
	v_mov_b32_e32 v17, v12
	s_waitcnt lgkmcnt(0)
	v_mov_b32_e32 v16, v14
	v_pk_add_f32 v[10:11], v[10:11], v[16:17] neg_lo:[0,1] neg_hi:[0,1]
	v_mov_b32_e32 v12, v15
	v_pk_mul_f32 v[10:11], v[10:11], v[12:13]
	v_add_u32_e32 v14, 0x2030, v79
	v_add_u32_e32 v12, 0x2038, v79
	ds_read2_b32 v[12:13], v12 offset1:1
	ds_read2_b32 v[14:15], v14 offset1:1
	global_load_dwordx4 v[20:23], v[20:21], off
	ds_read2_b32 v[110:111], v80 offset1:1
	ds_read2_b32 v[112:113], v112 offset1:1
	v_lshlrev_b32_e32 v80, 16, v81
	v_and_b32_e32 v81, 0xffff0000, v81
	s_waitcnt lgkmcnt(2)
	v_mov_b32_e32 v16, v14
	s_waitcnt lgkmcnt(1)
	v_mov_b32_e32 v115, v110
	s_waitcnt lgkmcnt(0)
	v_mov_b32_e32 v114, v112
	v_pk_add_f32 v[108:109], v[108:109], v[114:115] neg_lo:[0,1] neg_hi:[0,1]
	v_mov_b32_e32 v110, v113
	v_pk_mul_f32 v[108:109], v[108:109], v[110:111]
	v_add_u32_e32 v112, 0x2090, v79
	v_add_u32_e32 v110, 0x2098, v79
	ds_read2_b32 v[110:111], v110 offset1:1
	ds_read2_b32 v[112:113], v112 offset1:1
	v_mov_b32_e32 v17, v12
	v_pk_add_f32 v[2:3], v[2:3], v[16:17] neg_lo:[0,1] neg_hi:[0,1]
	v_mov_b32_e32 v12, v15
	s_waitcnt lgkmcnt(1)
	v_mov_b32_e32 v115, v110
	s_waitcnt lgkmcnt(0)
	v_mov_b32_e32 v114, v112
	v_pk_add_f32 v[80:81], v[80:81], v[114:115] neg_lo:[0,1] neg_hi:[0,1]
	v_mov_b32_e32 v110, v113
	v_pk_mul_f32 v[80:81], v[80:81], v[110:111]
	v_add_u32_e32 v114, 0x20a0, v79
	v_pk_fma_f32 v[110:111], v[74:75], v[80:81], v[76:77] op_sel_hi:[0,1,0]
	v_lshlrev_b32_e32 v80, 16, v82
	v_and_b32_e32 v81, 0xffff0000, v82
	v_add_u32_e32 v82, 0x20a8, v79
	ds_read2_b32 v[112:113], v82 offset1:1
	ds_read2_b32 v[114:115], v114 offset1:1
	v_pk_mul_f32 v[2:3], v[2:3], v[12:13]
	v_add_u32_e32 v82, 0x20b8, v79
	v_pk_fma_f32 v[10:11], v[74:75], v[10:11], v[76:77] op_sel_hi:[0,1,0]
	s_waitcnt lgkmcnt(1)
; __device__ __forceinline__ unsigned pk2(float lo, float hi) { f32x2 v = {lo, hi}; bf16x2_t b = __builtin_convertvector(v, bf16x2_t); return __builtin_bit_cast(unsigned, b); }
; #define MFMA32(a, b, c) __builtin_amdgcn_mfma_f32_32x32x16_bf16((a), (b), (c), 0, 0, 0)
; __device__ __forceinline__ void unpack8(const u32x4 w, float* v) { v[0] = bflo(w.x); v[1] = bfhi(w.x); v[2] = bflo(w.y); v[3] = bfhi(w.y); v[4] = bflo(w.z); v[5] = bfhi(w.z); v[6] = bflo(w.w); v[7] = bfhi(w.w); }
; template <int tbA, int tbB> ...
;     ...
;         for (int k = 0; k < NSB; ++k) {
;             float v[8]; unpack8(raw[k], v);
; #pragma unroll
;             for (int jj = 0; jj < 8; ++jj) { const float mean = stat[(16 * k + 8 * hh + jj) * 2 + so], rstd = stat[(16 * k + 8 * hh + jj) * 2 + 1 + so]; v[jj] = (v[jj] - mean) * rstd * gg + bb; }
;             u32x4 af; af.x = pk2(v[0], v[1]); af.y = pk2(v[2], v[3]); af.z = pk2(v[4], v[5]); af.w = pk2(v[6], v[7]);
;             accB = MFMA32(__builtin_bit_cast(bf16x8, af), wB[k], accB);
;             if (k < NSA) accA = MFMA32(__builtin_bit_cast(bf16x8, af), wA[k < NSA ? k : 0], accA);
	v_mov_b32_e32 v117, v112
	s_waitcnt lgkmcnt(0)
	v_mov_b32_e32 v116, v114
	v_pk_add_f32 v[80:81], v[80:81], v[116:117] neg_lo:[0,1] neg_hi:[0,1]
	v_mov_b32_e32 v112, v115
	v_pk_mul_f32 v[80:81], v[80:81], v[112:113]
	v_add_u32_e32 v114, 0x20b0, v79
	v_pk_fma_f32 v[2:3], v[74:75], v[2:3], v[76:77] op_sel_hi:[0,1,0]
	v_pk_fma_f32 v[112:113], v[74:75], v[80:81], v[76:77] op_sel_hi:[0,1,0]
	v_lshlrev_b32_e32 v80, 16, v83
	v_and_b32_e32 v81, 0xffff0000, v83
	ds_read2_b32 v[82:83], v82 offset1:1
	ds_read2_b32 v[114:115], v114 offset1:1
	v_cvt_pk_bf16_f32 v16, v8, v9
	v_cvt_pk_bf16_f32 v17, v0, v1
	v_cvt_pk_bf16_f32 v18, v10, v11
	v_cvt_pk_bf16_f32 v19, v2, v3
	s_waitcnt lgkmcnt(0)
	v_mov_b32_e32 v116, v114
	v_mov_b32_e32 v117, v82
	v_mfma_f32_32x32x16_bf16 v[0:15], v[16:19], v[4:7], 0
	v_add_f32_e64 v80, v80, -v116
	v_add_f32_e64 v81, v81, -v117
	v_mov_b32_e32 v82, v115
	v_mul_f32_e64 v80, v80, v82
	v_mul_f32_e64 v81, v81, v83
	v_pk_fma_f32 v[108:109], v[74:75], v[108:109], v[76:77] op_sel_hi:[0,1,0]
	v_pk_fma_f32 v[114:115], v[74:75], v[80:81], v[76:77] op_sel_hi:[0,1,0]
	v_cvt_pk_bf16_f32 v80, v108, v109
	v_cvt_pk_bf16_f32 v81, v110, v111
	v_cvt_pk_bf16_f32 v82, v112, v113
	v_cvt_pk_bf16_f32 v83, v114, v115
	s_waitcnt vmcnt(0)
	v_mfma_f32_32x32x16_bf16 v[16:31], v[16:19], v[20:23], 0
	v_mfma_f32_32x32x16_bf16 v[0:15], v[80:83], v[84:87], v[0:15]
	v_add_u32_e32 v84, 0x2100, v79
	v_mfma_f32_32x32x16_bf16 v[16:31], v[80:83], v[104:107], v[16:31]
	v_add_u32_e32 v82, 0x2108, v79
	ds_read2_b32 v[82:83], v82 offset1:1
	ds_read2_b32 v[84:85], v84 offset1:1
	v_lshlrev_b32_e32 v80, 16, v88
	v_and_b32_e32 v81, 0xffff0000, v88
	s_waitcnt lgkmcnt(1)
	v_mov_b32_e32 v87, v82
	s_waitcnt lgkmcnt(0)
	v_mov_b32_e32 v86, v84
	v_pk_add_f32 v[80:81], v[80:81], v[86:87] neg_lo:[0,1] neg_hi:[0,1]
	v_add_u32_e32 v86, 0x2110, v79
	v_add_u32_e32 v84, 0x2118, v79
	v_mov_b32_e32 v82, v85
	ds_read2_b32 v[84:85], v84 offset1:1
	ds_read2_b32 v[86:87], v86 offset1:1
	v_pk_mul_f32 v[80:81], v[80:81], v[82:83]
	v_lshlrev_b32_e32 v82, 16, v89
	v_and_b32_e32 v83, 0xffff0000, v89
	s_waitcnt lgkmcnt(1)
	v_mov_b32_e32 v89, v84
	s_waitcnt lgkmcnt(0)
	v_mov_b32_e32 v88, v86
	v_pk_add_f32 v[82:83], v[82:83], v[88:89] neg_lo:[0,1] neg_hi:[0,1]
	v_add_u32_e32 v88, 0x2120, v79
	v_add_u32_e32 v86, 0x2128, v79
	v_mov_b32_e32 v84, v87
	ds_read2_b32 v[86:87], v86 offset1:1
	ds_read2_b32 v[88:89], v88 offset1:1
	v_pk_mul_f32 v[82:83], v[82:83], v[84:85]
	v_lshlrev_b32_e32 v84, 16, v90
	v_and_b32_e32 v85, 0xffff0000, v90
	s_waitcnt lgkmcnt(1)
	v_mov_b32_e32 v105, v86
	s_waitcnt lgkmcnt(0)
	v_mov_b32_e32 v104, v88
	v_pk_add_f32 v[84:85], v[84:85], v[104:105] neg_lo:[0,1] neg_hi:[0,1]
	v_mov_b32_e32 v86, v89
	v_add_u32_e32 v90, 0x2130, v79
	v_add_u32_e32 v88, 0x2138, v79
	v_pk_mul_f32 v[84:85], v[84:85], v[86:87]
	v_lshlrev_b32_e32 v86, 16, v91
	v_and_b32_e32 v87, 0xffff0000, v91
	ds_read2_b32 v[88:89], v88 offset1:1
	ds_read2_b32 v[90:91], v90 offset1:1
	v_pk_fma_f32 v[80:81], v[74:75], v[80:81], v[76:77] op_sel_hi:[0,1,0]
	v_pk_fma_f32 v[82:83], v[74:75], v[82:83], v[76:77] op_sel_hi:[0,1,0]
	v_pk_fma_f32 v[84:85], v[74:75], v[84:85], v[76:77] op_sel_hi:[0,1,0]
	s_waitcnt lgkmcnt(1)
	v_mov_b32_e32 v105, v88
	s_waitcnt lgkmcnt(0)
	v_mov_b32_e32 v104, v90
	v_pk_add_f32 v[86:87], v[86:87], v[104:105] neg_lo:[0,1] neg_hi:[0,1]
	v_mov_b32_e32 v88, v91
	v_pk_mul_f32 v[86:87], v[86:87], v[88:89]
	v_cvt_pk_bf16_f32 v80, v80, v81
	v_pk_fma_f32 v[86:87], v[74:75], v[86:87], v[76:77] op_sel_hi:[0,1,0]
	v_cvt_pk_bf16_f32 v81, v82, v83
	v_cvt_pk_bf16_f32 v82, v84, v85
	v_cvt_pk_bf16_f32 v83, v86, v87
	v_add_u32_e32 v84, 0x2180, v79
	s_nop 0
	v_mfma_f32_32x32x16_bf16 v[0:15], v[80:83], v[92:95], v[0:15]
	v_add_u32_e32 v82, 0x2188, v79
	ds_read2_b32 v[82:83], v82 offset1:1
	ds_read2_b32 v[84:85], v84 offset1:1
	v_lshlrev_b32_e32 v80, 16, v96
	v_and_b32_e32 v81, 0xffff0000, v96
	s_waitcnt lgkmcnt(1)
	v_mov_b32_e32 v87, v82
	s_waitcnt lgkmcnt(0)
	v_mov_b32_e32 v86, v84
	v_pk_add_f32 v[80:81], v[80:81], v[86:87] neg_lo:[0,1] neg_hi:[0,1]
	v_add_u32_e32 v86, 0x2190, v79
	v_add_u32_e32 v84, 0x2198, v79
	v_mov_b32_e32 v82, v85
	ds_read2_b32 v[84:85], v84 offset1:1
	ds_read2_b32 v[86:87], v86 offset1:1
	v_pk_mul_f32 v[80:81], v[80:81], v[82:83]
	v_lshlrev_b32_e32 v82, 16, v97
	v_and_b32_e32 v83, 0xffff0000, v97
	s_waitcnt lgkmcnt(1)
	v_mov_b32_e32 v89, v84
	s_waitcnt lgkmcnt(0)
	v_mov_b32_e32 v88, v86
	v_pk_add_f32 v[82:83], v[82:83], v[88:89] neg_lo:[0,1] neg_hi:[0,1]
	v_add_u32_e32 v88, 0x21a0, v79
	v_add_u32_e32 v86, 0x21a8, v79
	v_mov_b32_e32 v84, v87
	ds_read2_b32 v[86:87], v86 offset1:1
	ds_read2_b32 v[88:89], v88 offset1:1
	v_pk_mul_f32 v[82:83], v[82:83], v[84:85]
	v_lshlrev_b32_e32 v84, 16, v98
	v_and_b32_e32 v85, 0xffff0000, v98
	s_waitcnt lgkmcnt(1)
	v_mov_b32_e32 v91, v86
	s_waitcnt lgkmcnt(0)
	v_mov_b32_e32 v90, v88
	v_pk_add_f32 v[84:85], v[84:85], v[90:91] neg_lo:[0,1] neg_hi:[0,1]
	v_add_u32_e32 v90, 0x21b0, v79
	v_add_u32_e32 v88, 0x21b8, v79
	v_mov_b32_e32 v86, v89
	ds_read2_b32 v[88:89], v88 offset1:1
	ds_read2_b32 v[90:91], v90 offset1:1
	v_pk_mul_f32 v[84:85], v[84:85], v[86:87]
	v_lshlrev_b32_e32 v86, 16, v99
	v_and_b32_e32 v87, 0xffff0000, v99
	s_waitcnt lgkmcnt(1)
	v_mov_b32_e32 v93, v88
	s_waitcnt lgkmcnt(0)
; __device__ __forceinline__ unsigned pk2(float lo, float hi) { f32x2 v = {lo, hi}; bf16x2_t b = __builtin_convertvector(v, bf16x2_t); return __builtin_bit_cast(unsigned, b); }
; #define MFMA32(a, b, c) __builtin_amdgcn_mfma_f32_32x32x16_bf16((a), (b), (c), 0, 0, 0)
; __device__ __forceinline__ void unpack8(const u32x4 w, float* v) { v[0] = bflo(w.x); v[1] = bfhi(w.x); v[2] = bflo(w.y); v[3] = bfhi(w.y); v[4] = bflo(w.z); v[5] = bfhi(w.z); v[6] = bflo(w.w); v[7] = bfhi(w.w); }
; template <int tbA, int tbB> ...
;     ...
;         for (int k = 0; k < NSB; ++k) {
;             float v[8]; unpack8(raw[k], v);
; #pragma unroll
;             for (int jj = 0; jj < 8; ++jj) { const float mean = stat[(16 * k + 8 * hh + jj) * 2 + so], rstd = stat[(16 * k + 8 * hh + jj) * 2 + 1 + so]; v[jj] = (v[jj] - mean) * rstd * gg + bb; }
;             u32x4 af; af.x = pk2(v[0], v[1]); af.y = pk2(v[2], v[3]); af.z = pk2(v[4], v[5]); af.w = pk2(v[6], v[7]);
;             accB = MFMA32(__builtin_bit_cast(bf16x8, af), wB[k], accB);
	v_mov_b32_e32 v92, v90
	v_pk_add_f32 v[86:87], v[86:87], v[92:93] neg_lo:[0,1] neg_hi:[0,1]
	v_mov_b32_e32 v88, v91
	v_pk_mul_f32 v[86:87], v[86:87], v[88:89]
	v_pk_fma_f32 v[80:81], v[74:75], v[80:81], v[76:77] op_sel_hi:[0,1,0]
	v_pk_fma_f32 v[82:83], v[74:75], v[82:83], v[76:77] op_sel_hi:[0,1,0]
	v_pk_fma_f32 v[84:85], v[74:75], v[84:85], v[76:77] op_sel_hi:[0,1,0]
	v_pk_fma_f32 v[86:87], v[74:75], v[86:87], v[76:77] op_sel_hi:[0,1,0]
	v_cvt_pk_bf16_f32 v80, v80, v81
	v_cvt_pk_bf16_f32 v81, v82, v83
	v_cvt_pk_bf16_f32 v82, v84, v85
	v_cvt_pk_bf16_f32 v83, v86, v87
	v_add_u32_e32 v84, 0x2200, v79
	s_nop 0
	v_mfma_f32_32x32x16_bf16 v[0:15], v[80:83], v[100:103], v[0:15]
	v_lshlrev_b32_e32 v80, 16, v60
	v_and_b32_e32 v81, 0xffff0000, v60
	v_add_u32_e32 v60, 0x2208, v79
	ds_read2_b32 v[82:83], v60 offset1:1
	ds_read2_b32 v[84:85], v84 offset1:1
	v_lshlrev_b32_e32 v60, 16, v61
	v_and_b32_e32 v61, 0xffff0000, v61
	s_waitcnt lgkmcnt(1)
	v_mov_b32_e32 v87, v82
	s_waitcnt lgkmcnt(0)
	v_mov_b32_e32 v86, v84
	v_pk_add_f32 v[80:81], v[80:81], v[86:87] neg_lo:[0,1] neg_hi:[0,1]
	v_mov_b32_e32 v82, v85
	v_pk_mul_f32 v[80:81], v[80:81], v[82:83]
	v_add_u32_e32 v84, 0x2210, v79
	v_add_u32_e32 v82, 0x2218, v79
	ds_read2_b32 v[82:83], v82 offset1:1
	ds_read2_b32 v[84:85], v84 offset1:1
	v_pk_fma_f32 v[80:81], v[74:75], v[80:81], v[76:77] op_sel_hi:[0,1,0]
	s_waitcnt lgkmcnt(1)
	v_mov_b32_e32 v87, v82
	s_waitcnt lgkmcnt(0)
	v_mov_b32_e32 v86, v84
	v_pk_add_f32 v[60:61], v[60:61], v[86:87] neg_lo:[0,1] neg_hi:[0,1]
	v_mov_b32_e32 v82, v85
	v_pk_mul_f32 v[60:61], v[60:61], v[82:83]
	v_add_u32_e32 v86, 0x2220, v79
	v_pk_fma_f32 v[82:83], v[74:75], v[60:61], v[76:77] op_sel_hi:[0,1,0]
	v_lshlrev_b32_e32 v60, 16, v62
	v_and_b32_e32 v61, 0xffff0000, v62
	v_add_u32_e32 v62, 0x2228, v79
	ds_read2_b32 v[84:85], v62 offset1:1
	ds_read2_b32 v[86:87], v86 offset1:1
	v_add_u32_e32 v62, 0x2238, v79
	s_waitcnt lgkmcnt(1)
	v_mov_b32_e32 v89, v84
	s_waitcnt lgkmcnt(0)
	v_mov_b32_e32 v88, v86
	v_pk_add_f32 v[60:61], v[60:61], v[88:89] neg_lo:[0,1] neg_hi:[0,1]
	v_mov_b32_e32 v84, v87
	v_pk_mul_f32 v[60:61], v[60:61], v[84:85]
	v_add_u32_e32 v86, 0x2230, v79
	v_pk_fma_f32 v[84:85], v[74:75], v[60:61], v[76:77] op_sel_hi:[0,1,0]
	v_lshlrev_b32_e32 v60, 16, v63
	v_and_b32_e32 v61, 0xffff0000, v63
	ds_read2_b32 v[62:63], v62 offset1:1
	ds_read2_b32 v[86:87], v86 offset1:1
	s_waitcnt lgkmcnt(1)
	v_mov_b32_e32 v89, v62
	s_waitcnt lgkmcnt(0)
	v_mov_b32_e32 v88, v86
	v_pk_add_f32 v[60:61], v[60:61], v[88:89] neg_lo:[0,1] neg_hi:[0,1]
	v_mov_b32_e32 v62, v87
	v_pk_mul_f32 v[60:61], v[60:61], v[62:63]
	v_cvt_pk_bf16_f32 v62, v84, v85
	v_pk_fma_f32 v[86:87], v[74:75], v[60:61], v[76:77] op_sel_hi:[0,1,0]
	v_cvt_pk_bf16_f32 v60, v80, v81
	v_cvt_pk_bf16_f32 v61, v82, v83
	v_cvt_pk_bf16_f32 v63, v86, v87
	s_nop 1
	v_mfma_f32_32x32x16_bf16 v[0:15], v[60:63], v[56:59], v[0:15]
	v_add_u32_e32 v60, 0x2280, v79
	v_lshlrev_b32_e32 v56, 16, v52
	v_and_b32_e32 v57, 0xffff0000, v52
	v_add_u32_e32 v52, 0x2288, v79
	ds_read2_b32 v[58:59], v52 offset1:1
	ds_read2_b32 v[60:61], v60 offset1:1
	v_lshlrev_b32_e32 v52, 16, v53
	v_and_b32_e32 v53, 0xffff0000, v53
	s_waitcnt lgkmcnt(1)
	v_mov_b32_e32 v63, v58
	s_waitcnt lgkmcnt(0)
	v_mov_b32_e32 v62, v60
	v_pk_add_f32 v[56:57], v[56:57], v[62:63] neg_lo:[0,1] neg_hi:[0,1]
	v_mov_b32_e32 v58, v61
	v_pk_mul_f32 v[56:57], v[56:57], v[58:59]
	v_add_u32_e32 v60, 0x2290, v79
	v_add_u32_e32 v58, 0x2298, v79
	ds_read2_b32 v[58:59], v58 offset1:1
	ds_read2_b32 v[60:61], v60 offset1:1
	v_pk_fma_f32 v[56:57], v[74:75], v[56:57], v[76:77] op_sel_hi:[0,1,0]
	s_waitcnt lgkmcnt(1)
	v_mov_b32_e32 v63, v58
	s_waitcnt lgkmcnt(0)
	v_mov_b32_e32 v62, v60
	v_pk_add_f32 v[52:53], v[52:53], v[62:63] neg_lo:[0,1] neg_hi:[0,1]
	v_mov_b32_e32 v58, v61
	v_pk_mul_f32 v[52:53], v[52:53], v[58:59]
	v_add_u32_e32 v62, 0x22a0, v79
	v_pk_fma_f32 v[58:59], v[74:75], v[52:53], v[76:77] op_sel_hi:[0,1,0]
	v_lshlrev_b32_e32 v52, 16, v54
	v_and_b32_e32 v53, 0xffff0000, v54
	v_add_u32_e32 v54, 0x22a8, v79
	ds_read2_b32 v[60:61], v54 offset1:1
	ds_read2_b32 v[62:63], v62 offset1:1
	v_add_u32_e32 v54, 0x22b8, v79
	s_waitcnt lgkmcnt(1)
	v_mov_b32_e32 v81, v60
	s_waitcnt lgkmcnt(0)
	v_mov_b32_e32 v80, v62
	v_pk_add_f32 v[52:53], v[52:53], v[80:81] neg_lo:[0,1] neg_hi:[0,1]
	v_mov_b32_e32 v60, v63
	v_pk_mul_f32 v[52:53], v[52:53], v[60:61]
	v_add_u32_e32 v62, 0x22b0, v79
	v_pk_fma_f32 v[60:61], v[74:75], v[52:53], v[76:77] op_sel_hi:[0,1,0]
	v_lshlrev_b32_e32 v52, 16, v55
	v_and_b32_e32 v53, 0xffff0000, v55
	ds_read2_b32 v[54:55], v54 offset1:1
	ds_read2_b32 v[62:63], v62 offset1:1
	s_waitcnt lgkmcnt(1)
	v_mov_b32_e32 v81, v54
	s_waitcnt lgkmcnt(0)
	v_mov_b32_e32 v80, v62
	v_pk_add_f32 v[52:53], v[52:53], v[80:81] neg_lo:[0,1] neg_hi:[0,1]
	v_mov_b32_e32 v54, v63
	v_pk_mul_f32 v[52:53], v[52:53], v[54:55]
	v_cvt_pk_bf16_f32 v54, v60, v61
	v_pk_fma_f32 v[62:63], v[74:75], v[52:53], v[76:77] op_sel_hi:[0,1,0]
	v_cvt_pk_bf16_f32 v52, v56, v57
	v_cvt_pk_bf16_f32 v53, v58, v59
	v_cvt_pk_bf16_f32 v55, v62, v63
	s_nop 1
	v_mfma_f32_32x32x16_bf16 v[0:15], v[52:55], v[48:51], v[0:15]
	v_add_u32_e32 v52, 0x2300, v79
	v_lshlrev_b32_e32 v48, 16, v44
	v_and_b32_e32 v49, 0xffff0000, v44
	v_add_u32_e32 v44, 0x2308, v79
	ds_read2_b32 v[50:51], v44 offset1:1
	ds_read2_b32 v[52:53], v52 offset1:1
	v_lshlrev_b32_e32 v44, 16, v45
	v_and_b32_e32 v45, 0xffff0000, v45
	s_waitcnt lgkmcnt(1)
	v_mov_b32_e32 v55, v50
	s_waitcnt lgkmcnt(0)
; #define LAS __attribute__((address_space(3)))
; __device__ __forceinline__ unsigned pk2(float lo, float hi) { f32x2 v = {lo, hi}; bf16x2_t b = __builtin_convertvector(v, bf16x2_t); return __builtin_bit_cast(unsigned, b); }
; #define MFMA32(a, b, c) __builtin_amdgcn_mfma_f32_32x32x16_bf16((a), (b), (c), 0, 0, 0)
; __device__ __forceinline__ void unpack8(const u32x4 w, float* v) { v[0] = bflo(w.x); v[1] = bfhi(w.x); v[2] = bflo(w.y); v[3] = bfhi(w.y); v[4] = bflo(w.z); v[5] = bfhi(w.z); v[6] = bflo(w.w); v[7] = bfhi(w.w); }
; template <int tbA, int tbB> ...
;     ...
;         for (int k = 0; k < NSB; ++k) {
;             float v[8]; unpack8(raw[k], v);
; #pragma unroll
;             for (int jj = 0; jj < 8; ++jj) { const float mean = stat[(16 * k + 8 * hh + jj) * 2 + so], rstd = stat[(16 * k + 8 * hh + jj) * 2 + 1 + so]; v[jj] = (v[jj] - mean) * rstd * gg + bb; }
;             u32x4 af; af.x = pk2(v[0], v[1]); af.y = pk2(v[2], v[3]); af.z = pk2(v[4], v[5]); af.w = pk2(v[6], v[7]);
;             accB = MFMA32(__builtin_bit_cast(bf16x8, af), wB[k], accB);
;             if (k < NSA) accA = MFMA32(__builtin_bit_cast(bf16x8, af), wA[k < NSA ? k : 0], accA);
;         }
; #pragma unroll
;         for (int which = 0; which < 2; ++which) {
;             const int tb = which ? tbB : tbA; const f32x16& acc = which ? accB : accA;
;             const float sbv = spb[g * 128 + tb * 32 + r];
; #pragma unroll
;             for (int q = 0; q < 4; ++q) {
;                 u32x2 w; w.x = pk2(acc[4 * q + 0] + sbv, acc[4 * q + 1] + sbv); w.y = pk2(acc[4 * q + 2] + sbv, acc[4 * q + 3] + sbv);
;                 *(LAS u32x2*)(stg + which * 2560 + r * 80 + (8 * q + 4 * hh) * 2) = w;
;             }
;         }
; #pragma unroll
	v_mov_b32_e32 v54, v52
	v_pk_add_f32 v[48:49], v[48:49], v[54:55] neg_lo:[0,1] neg_hi:[0,1]
	v_mov_b32_e32 v50, v53
	v_pk_mul_f32 v[48:49], v[48:49], v[50:51]
	v_add_u32_e32 v52, 0x2310, v79
	v_add_u32_e32 v50, 0x2318, v79
	ds_read2_b32 v[50:51], v50 offset1:1
	ds_read2_b32 v[52:53], v52 offset1:1
	v_pk_fma_f32 v[48:49], v[74:75], v[48:49], v[76:77] op_sel_hi:[0,1,0]
	s_waitcnt lgkmcnt(1)
	v_mov_b32_e32 v55, v50
	s_waitcnt lgkmcnt(0)
	v_mov_b32_e32 v54, v52
	v_pk_add_f32 v[44:45], v[44:45], v[54:55] neg_lo:[0,1] neg_hi:[0,1]
	v_mov_b32_e32 v50, v53
	v_pk_mul_f32 v[44:45], v[44:45], v[50:51]
	v_add_u32_e32 v54, 0x2320, v79
	v_pk_fma_f32 v[50:51], v[74:75], v[44:45], v[76:77] op_sel_hi:[0,1,0]
	v_lshlrev_b32_e32 v44, 16, v46
	v_and_b32_e32 v45, 0xffff0000, v46
	v_add_u32_e32 v46, 0x2328, v79
	ds_read2_b32 v[52:53], v46 offset1:1
	ds_read2_b32 v[54:55], v54 offset1:1
	v_add_u32_e32 v46, 0x2338, v79
	s_waitcnt lgkmcnt(1)
	v_mov_b32_e32 v57, v52
	s_waitcnt lgkmcnt(0)
	v_mov_b32_e32 v56, v54
	v_pk_add_f32 v[44:45], v[44:45], v[56:57] neg_lo:[0,1] neg_hi:[0,1]
	v_mov_b32_e32 v52, v55
	v_pk_mul_f32 v[44:45], v[44:45], v[52:53]
	v_add_u32_e32 v54, 0x2330, v79
	v_pk_fma_f32 v[52:53], v[74:75], v[44:45], v[76:77] op_sel_hi:[0,1,0]
	v_lshlrev_b32_e32 v44, 16, v47
	v_and_b32_e32 v45, 0xffff0000, v47
	ds_read2_b32 v[46:47], v46 offset1:1
	ds_read2_b32 v[54:55], v54 offset1:1
	s_waitcnt lgkmcnt(1)
	v_mov_b32_e32 v57, v46
	s_waitcnt lgkmcnt(0)
	v_mov_b32_e32 v56, v54
	v_pk_add_f32 v[44:45], v[44:45], v[56:57] neg_lo:[0,1] neg_hi:[0,1]
	v_mov_b32_e32 v46, v55
	v_pk_mul_f32 v[44:45], v[44:45], v[46:47]
	v_cvt_pk_bf16_f32 v46, v52, v53
	v_pk_fma_f32 v[54:55], v[74:75], v[44:45], v[76:77] op_sel_hi:[0,1,0]
	v_cvt_pk_bf16_f32 v44, v48, v49
	v_cvt_pk_bf16_f32 v45, v50, v51
	v_cvt_pk_bf16_f32 v47, v54, v55
	s_nop 1
	v_mfma_f32_32x32x16_bf16 v[0:15], v[44:47], v[40:43], v[0:15]
	v_add_u32_e32 v44, 0x2380, v79
	v_lshlrev_b32_e32 v40, 16, v36
	v_and_b32_e32 v41, 0xffff0000, v36
	v_add_u32_e32 v36, 0x2388, v79
	ds_read2_b32 v[42:43], v36 offset1:1
	ds_read2_b32 v[44:45], v44 offset1:1
	v_lshlrev_b32_e32 v36, 16, v37
	v_and_b32_e32 v37, 0xffff0000, v37
	s_waitcnt lgkmcnt(1)
	v_mov_b32_e32 v47, v42
	s_waitcnt lgkmcnt(0)
	v_mov_b32_e32 v46, v44
	v_pk_add_f32 v[40:41], v[40:41], v[46:47] neg_lo:[0,1] neg_hi:[0,1]
	v_mov_b32_e32 v42, v45
	v_pk_mul_f32 v[40:41], v[40:41], v[42:43]
	v_add_u32_e32 v44, 0x2390, v79
	v_add_u32_e32 v42, 0x2398, v79
	ds_read2_b32 v[42:43], v42 offset1:1
	ds_read2_b32 v[44:45], v44 offset1:1
	v_pk_fma_f32 v[40:41], v[74:75], v[40:41], v[76:77] op_sel_hi:[0,1,0]
	s_waitcnt lgkmcnt(1)
	v_mov_b32_e32 v47, v42
	s_waitcnt lgkmcnt(0)
	v_mov_b32_e32 v46, v44
	v_pk_add_f32 v[36:37], v[36:37], v[46:47] neg_lo:[0,1] neg_hi:[0,1]
	v_mov_b32_e32 v42, v45
	v_pk_mul_f32 v[36:37], v[36:37], v[42:43]
	v_add_u32_e32 v46, 0x23a0, v79
	v_pk_fma_f32 v[42:43], v[74:75], v[36:37], v[76:77] op_sel_hi:[0,1,0]
	v_lshlrev_b32_e32 v36, 16, v38
	v_and_b32_e32 v37, 0xffff0000, v38
	v_add_u32_e32 v38, 0x23a8, v79
	ds_read2_b32 v[44:45], v38 offset1:1
	ds_read2_b32 v[46:47], v46 offset1:1
	v_add_u32_e32 v38, 0x23b8, v79
	s_waitcnt lgkmcnt(1)
	v_mov_b32_e32 v49, v44
	s_waitcnt lgkmcnt(0)
	v_mov_b32_e32 v48, v46
	v_pk_add_f32 v[36:37], v[36:37], v[48:49] neg_lo:[0,1] neg_hi:[0,1]
	v_mov_b32_e32 v44, v47
	v_pk_mul_f32 v[36:37], v[36:37], v[44:45]
	v_add_u32_e32 v46, 0x23b0, v79
	v_pk_fma_f32 v[44:45], v[74:75], v[36:37], v[76:77] op_sel_hi:[0,1,0]
	v_lshlrev_b32_e32 v36, 16, v39
	v_and_b32_e32 v37, 0xffff0000, v39
	ds_read2_b32 v[38:39], v38 offset1:1
	ds_read2_b32 v[46:47], v46 offset1:1
	s_waitcnt lgkmcnt(1)
	v_mov_b32_e32 v49, v38
	s_waitcnt lgkmcnt(0)
	v_mov_b32_e32 v48, v46
	v_pk_add_f32 v[36:37], v[36:37], v[48:49] neg_lo:[0,1] neg_hi:[0,1]
	v_mov_b32_e32 v38, v47
	v_pk_mul_f32 v[36:37], v[36:37], v[38:39]
	v_cvt_pk_bf16_f32 v38, v44, v45
	v_pk_fma_f32 v[46:47], v[74:75], v[36:37], v[76:77] op_sel_hi:[0,1,0]
	v_cvt_pk_bf16_f32 v36, v40, v41
	v_cvt_pk_bf16_f32 v37, v42, v43
	v_cvt_pk_bf16_f32 v39, v46, v47
	s_nop 1
	v_mfma_f32_32x32x16_bf16 v[0:15], v[36:39], v[32:35], v[0:15]
	global_load_dword v32, v[66:67], off offset:-384
	s_waitcnt vmcnt(0)
	v_add_f32_e64 v16, v16, v32
	v_add_f32_e64 v17, v17, v32
	v_add_f32_e64 v18, v18, v32
	v_add_f32_e64 v19, v19, v32
	v_cvt_pk_bf16_f32 v16, v16, v17
	v_cvt_pk_bf16_f32 v17, v18, v19
	v_pk_add_f32 v[18:19], v[20:21], v[32:33] op_sel_hi:[1,0]
	v_pk_add_f32 v[20:21], v[22:23], v[32:33] op_sel_hi:[1,0]
	v_cvt_pk_bf16_f32 v18, v18, v19
	v_cvt_pk_bf16_f32 v19, v20, v21
	v_add_u32_e32 v22, 0x4000, v78
	ds_write2_b64 v22, v[16:17], v[18:19] offset1:2
	v_pk_add_f32 v[16:17], v[24:25], v[32:33] op_sel_hi:[1,0]
	v_pk_add_f32 v[18:19], v[26:27], v[32:33] op_sel_hi:[1,0]
	v_cvt_pk_bf16_f32 v16, v16, v17
	v_cvt_pk_bf16_f32 v17, v18, v19
	v_pk_add_f32 v[18:19], v[28:29], v[32:33] op_sel_hi:[1,0]
	v_pk_add_f32 v[20:21], v[30:31], v[32:33] op_sel_hi:[1,0]
	v_cvt_pk_bf16_f32 v18, v18, v19
	v_cvt_pk_bf16_f32 v19, v20, v21
	ds_write2_b64 v22, v[16:17], v[18:19] offset0:4 offset1:6
	global_load_dword v16, v[66:67], off
	v_add_u32_e32 v18, s8, v77
	v_add_u32_e32 v132, 0xfa000000, v18
	s_addk_i32 s8, 0x80
	v_lshl_add_u64 v[66:67], v[66:67], 0, s[62:63]
	s_cmpk_eq_i32 s8, 0x200
	s_waitcnt vmcnt(0)
; #define LAS __attribute__((address_space(3)))
; __device__ __forceinline__ unsigned pk2(float lo, float hi) { f32x2 v = {lo, hi}; bf16x2_t b = __builtin_convertvector(v, bf16x2_t); return __builtin_bit_cast(unsigned, b); }
; __device__ __forceinline__ float bflo(unsigned u) { return __uint_as_float(u << 16); }
; __device__ __forceinline__ float bfhi(unsigned u) { return __uint_as_float(u & 0xffff0000u); }
; template <int tbA, int tbB> ...
;     ...
;             const float sbv = spb[g * 128 + tb * 32 + r];
; #pragma unroll
;             for (int q = 0; q < 4; ++q) {
;                 u32x2 w; w.x = pk2(acc[4 * q + 0] + sbv, acc[4 * q + 1] + sbv); w.y = pk2(acc[4 * q + 2] + sbv, acc[4 * q + 3] + sbv);
;                 *(LAS u32x2*)(stg + which * 2560 + r * 80 + (8 * q + 4 * hh) * 2) = w;
;             }
;         }
; #pragma unroll
;         for (int which = 0; which < 2; ++which) {
;             const int tb = which ? tbB : tbA;
; #pragma unroll
;             for (int i = 0; i < 2; ++i) {
;                 const int t = (lane >> 2) + 16 * i, ck = lane & 3;
;                 const size_t a = (size_t)(tok0 + tb * 32 + t) * DH + g * 128 + cb * 32 + ck * 8;
;                 const u32x4 uu = *(const u32x4*)(U + a), gc = *(const u32x4*)(GC + a);
;                 const u32x4 mv = *(const LAS u32x4*)(stg + which * 2560 + t * 80 + ck * 16);
;                 u32x4 o; o.x = pk2(bflo(uu.x) * bflo(mv.x) * bflo(gc.x), bfhi(uu.x) * bfhi(mv.x) * bfhi(gc.x)); o.y = pk2(bflo(uu.y) * bflo(mv.y) * bflo(gc.y), bfhi(uu.y) * bfhi(mv.y) * bfhi(gc.y));
;                 o.z = pk2(bflo(uu.z) * bflo(mv.z) * bflo(gc.z), bfhi(uu.z) * bfhi(mv.z) * bfhi(gc.z)); o.w = pk2(bflo(uu.w) * bflo(mv.w) * bflo(gc.w), bfhi(uu.w) * bfhi(mv.w) * bfhi(gc.w));
;                 *(u32x4*)(OC + a) = o;
;             }
	v_pk_add_f32 v[0:1], v[0:1], v[16:17] op_sel_hi:[1,0]
	v_pk_add_f32 v[2:3], v[2:3], v[16:17] op_sel_hi:[1,0]
	v_cvt_pk_bf16_f32 v0, v0, v1
	v_cvt_pk_bf16_f32 v1, v2, v3
	v_pk_add_f32 v[2:3], v[4:5], v[16:17] op_sel_hi:[1,0]
	v_pk_add_f32 v[4:5], v[6:7], v[16:17] op_sel_hi:[1,0]
	v_cvt_pk_bf16_f32 v2, v2, v3
	v_cvt_pk_bf16_f32 v3, v4, v5
	v_add_u32_e32 v6, 0x4800, v78
	ds_write2_b64 v6, v[0:1], v[2:3] offset0:64 offset1:66
	v_pk_add_f32 v[0:1], v[8:9], v[16:17] op_sel_hi:[1,0]
	v_pk_add_f32 v[2:3], v[10:11], v[16:17] op_sel_hi:[1,0]
	v_cvt_pk_bf16_f32 v0, v0, v1
	v_cvt_pk_bf16_f32 v1, v2, v3
	v_pk_add_f32 v[2:3], v[12:13], v[16:17] op_sel_hi:[1,0]
	v_pk_add_f32 v[4:5], v[14:15], v[16:17] op_sel_hi:[1,0]
	v_cvt_pk_bf16_f32 v2, v2, v3
	v_cvt_pk_bf16_f32 v3, v4, v5
	v_lshlrev_b64 v[12:13], 1, v[132:133]
	ds_write2_b64 v6, v[0:1], v[2:3] offset0:68 offset1:70
	v_lshl_add_u64 v[0:1], s[30:31], 0, v[12:13]
	global_load_dwordx4 v[0:3], v[0:1], off
	v_lshl_add_u64 v[4:5], s[34:35], 0, v[12:13]
	global_load_dwordx4 v[4:7], v[4:5], off
	ds_read_b128 v[8:11], v75 offset:16384
	v_add_u32_e32 v132, 0xfa004000, v18
	s_waitcnt lgkmcnt(0)
	v_lshlrev_b32_e32 v16, 16, v8
	v_and_b32_e32 v17, 0xffff0000, v8
	v_lshlrev_b32_e32 v8, 16, v9
	v_and_b32_e32 v9, 0xffff0000, v9
	s_waitcnt vmcnt(1)
	v_lshlrev_b32_e32 v14, 16, v0
	v_and_b32_e32 v15, 0xffff0000, v0
	v_pk_mul_f32 v[14:15], v[14:15], v[16:17]
	s_waitcnt vmcnt(0)
	v_lshlrev_b32_e32 v16, 16, v4
	v_and_b32_e32 v17, 0xffff0000, v4
	v_pk_mul_f32 v[14:15], v[14:15], v[16:17]
	v_lshlrev_b32_e32 v4, 16, v5
	v_cvt_pk_bf16_f32 v0, v14, v15
	v_lshlrev_b32_e32 v14, 16, v1
	v_and_b32_e32 v15, 0xffff0000, v1
	v_pk_mul_f32 v[8:9], v[14:15], v[8:9]
	v_and_b32_e32 v5, 0xffff0000, v5
	v_pk_mul_f32 v[4:5], v[8:9], v[4:5]
	v_lshlrev_b32_e32 v8, 16, v10
	v_cvt_pk_bf16_f32 v1, v4, v5
	v_lshlrev_b32_e32 v4, 16, v2
	v_and_b32_e32 v5, 0xffff0000, v2
	v_and_b32_e32 v9, 0xffff0000, v10
	v_pk_mul_f32 v[4:5], v[4:5], v[8:9]
	v_lshlrev_b32_e32 v8, 16, v6
	v_and_b32_e32 v9, 0xffff0000, v6
	v_pk_mul_f32 v[4:5], v[4:5], v[8:9]
	v_lshlrev_b32_e32 v8, 16, v11
	v_cvt_pk_bf16_f32 v2, v4, v5
	v_lshlrev_b32_e32 v4, 16, v3
	v_and_b32_e32 v5, 0xffff0000, v3
	v_and_b32_e32 v9, 0xffff0000, v11
	v_pk_mul_f32 v[4:5], v[4:5], v[8:9]
	v_lshlrev_b32_e32 v6, 16, v7
	v_and_b32_e32 v7, 0xffff0000, v7
	v_pk_mul_f32 v[4:5], v[4:5], v[6:7]
	ds_read_b128 v[8:11], v75 offset:17664
	v_cvt_pk_bf16_f32 v3, v4, v5
	v_lshl_add_u64 v[4:5], s[36:37], 0, v[12:13]
	v_lshlrev_b64 v[12:13], 1, v[132:133]
	global_store_dwordx4 v[4:5], v[0:3], off
	v_lshl_add_u64 v[4:5], s[34:35], 0, v[12:13]
	global_load_dwordx4 v[4:7], v[4:5], off
	v_lshl_add_u64 v[0:1], s[30:31], 0, v[12:13]
	global_load_dwordx4 v[0:3], v[0:1], off
	s_waitcnt lgkmcnt(0)
	v_lshlrev_b32_e32 v16, 16, v8
	v_and_b32_e32 v17, 0xffff0000, v8
	v_lshlrev_b32_e32 v8, 16, v9
	v_and_b32_e32 v9, 0xffff0000, v9
	v_add_u32_e32 v132, 0xfa018000, v18
	s_waitcnt vmcnt(0)
	v_lshlrev_b32_e32 v14, 16, v0
	v_and_b32_e32 v15, 0xffff0000, v0
	v_pk_mul_f32 v[14:15], v[14:15], v[16:17]
	v_lshlrev_b32_e32 v16, 16, v4
	v_and_b32_e32 v17, 0xffff0000, v4
	v_pk_mul_f32 v[14:15], v[14:15], v[16:17]
	v_lshlrev_b32_e32 v4, 16, v5
	v_cvt_pk_bf16_f32 v0, v14, v15
	v_lshlrev_b32_e32 v14, 16, v1
	v_and_b32_e32 v15, 0xffff0000, v1
	v_pk_mul_f32 v[8:9], v[14:15], v[8:9]
	v_and_b32_e32 v5, 0xffff0000, v5
	v_pk_mul_f32 v[4:5], v[8:9], v[4:5]
	v_lshlrev_b32_e32 v8, 16, v10
	v_cvt_pk_bf16_f32 v1, v4, v5
	v_lshlrev_b32_e32 v4, 16, v2
	v_and_b32_e32 v5, 0xffff0000, v2
	v_and_b32_e32 v9, 0xffff0000, v10
	v_pk_mul_f32 v[4:5], v[4:5], v[8:9]
	v_lshlrev_b32_e32 v8, 16, v6
	v_and_b32_e32 v9, 0xffff0000, v6
	v_pk_mul_f32 v[4:5], v[4:5], v[8:9]
	v_lshlrev_b32_e32 v8, 16, v11
	v_cvt_pk_bf16_f32 v2, v4, v5
	v_lshlrev_b32_e32 v4, 16, v3
	v_and_b32_e32 v5, 0xffff0000, v3
	v_and_b32_e32 v9, 0xffff0000, v11
	v_pk_mul_f32 v[4:5], v[4:5], v[8:9]
	v_lshlrev_b32_e32 v6, 16, v7
	v_and_b32_e32 v7, 0xffff0000, v7
	v_pk_mul_f32 v[4:5], v[4:5], v[6:7]
	ds_read_b128 v[8:11], v75 offset:18944
	v_cvt_pk_bf16_f32 v3, v4, v5
	v_lshl_add_u64 v[4:5], s[36:37], 0, v[12:13]
	v_lshlrev_b64 v[12:13], 1, v[132:133]
	global_store_dwordx4 v[4:5], v[0:3], off
	v_lshl_add_u64 v[4:5], s[34:35], 0, v[12:13]
	global_load_dwordx4 v[4:7], v[4:5], off
	v_lshl_add_u64 v[0:1], s[30:31], 0, v[12:13]
	global_load_dwordx4 v[0:3], v[0:1], off
	s_waitcnt lgkmcnt(0)
; #define LAS __attribute__((address_space(3)))
; __device__ __forceinline__ unsigned pk2(float lo, float hi) { f32x2 v = {lo, hi}; bf16x2_t b = __builtin_convertvector(v, bf16x2_t); return __builtin_bit_cast(unsigned, b); }
; __device__ __forceinline__ float bflo(unsigned u) { return __uint_as_float(u << 16); }
; __device__ __forceinline__ float bfhi(unsigned u) { return __uint_as_float(u & 0xffff0000u); }
; template <int tbA, int tbB> ...
;     ...
;             for (int i = 0; i < 2; ++i) {
;                 const int t = (lane >> 2) + 16 * i, ck = lane & 3;
;                 const size_t a = (size_t)(tok0 + tb * 32 + t) * DH + g * 128 + cb * 32 + ck * 8;
;                 const u32x4 uu = *(const u32x4*)(U + a), gc = *(const u32x4*)(GC + a);
;                 const u32x4 mv = *(const LAS u32x4*)(stg + which * 2560 + t * 80 + ck * 16);
;                 u32x4 o; o.x = pk2(bflo(uu.x) * bflo(mv.x) * bflo(gc.x), bfhi(uu.x) * bfhi(mv.x) * bfhi(gc.x)); o.y = pk2(bflo(uu.y) * bflo(mv.y) * bflo(gc.y), bfhi(uu.y) * bfhi(mv.y) * bfhi(gc.y));
;                 o.z = pk2(bflo(uu.z) * bflo(mv.z) * bflo(gc.z), bfhi(uu.z) * bfhi(mv.z) * bfhi(gc.z)); o.w = pk2(bflo(uu.w) * bflo(mv.w) * bflo(gc.w), bfhi(uu.w) * bfhi(mv.w) * bfhi(gc.w));
;                 *(u32x4*)(OC + a) = o;
;             }
	v_lshlrev_b32_e32 v16, 16, v8
	v_and_b32_e32 v17, 0xffff0000, v8
	v_lshlrev_b32_e32 v8, 16, v9
	v_and_b32_e32 v9, 0xffff0000, v9
	v_add_u32_e32 v132, 0xfa01c000, v18
	s_waitcnt vmcnt(0)
	v_lshlrev_b32_e32 v14, 16, v0
	v_and_b32_e32 v15, 0xffff0000, v0
	v_pk_mul_f32 v[14:15], v[14:15], v[16:17]
	v_lshlrev_b32_e32 v16, 16, v4
	v_and_b32_e32 v17, 0xffff0000, v4
	v_pk_mul_f32 v[14:15], v[14:15], v[16:17]
	v_lshlrev_b32_e32 v4, 16, v5
	v_cvt_pk_bf16_f32 v0, v14, v15
	v_lshlrev_b32_e32 v14, 16, v1
	v_and_b32_e32 v15, 0xffff0000, v1
	v_pk_mul_f32 v[8:9], v[14:15], v[8:9]
	v_and_b32_e32 v5, 0xffff0000, v5
	v_pk_mul_f32 v[4:5], v[8:9], v[4:5]
	v_lshlrev_b32_e32 v8, 16, v10
	v_cvt_pk_bf16_f32 v1, v4, v5
	v_lshlrev_b32_e32 v4, 16, v2
	v_and_b32_e32 v5, 0xffff0000, v2
	v_and_b32_e32 v9, 0xffff0000, v10
	v_pk_mul_f32 v[4:5], v[4:5], v[8:9]
	v_lshlrev_b32_e32 v8, 16, v6
	v_and_b32_e32 v9, 0xffff0000, v6
	v_pk_mul_f32 v[4:5], v[4:5], v[8:9]
	v_lshlrev_b32_e32 v8, 16, v11
	v_cvt_pk_bf16_f32 v2, v4, v5
	v_lshlrev_b32_e32 v4, 16, v3
	v_and_b32_e32 v5, 0xffff0000, v3
	v_and_b32_e32 v9, 0xffff0000, v11
	v_pk_mul_f32 v[4:5], v[4:5], v[8:9]
	v_lshlrev_b32_e32 v6, 16, v7
	v_and_b32_e32 v7, 0xffff0000, v7
	v_pk_mul_f32 v[4:5], v[4:5], v[6:7]
	ds_read_b128 v[8:11], v75 offset:20224
	v_cvt_pk_bf16_f32 v3, v4, v5
	v_lshl_add_u64 v[4:5], s[36:37], 0, v[12:13]
	v_lshlrev_b64 v[12:13], 1, v[132:133]
	global_store_dwordx4 v[4:5], v[0:3], off
	v_lshl_add_u64 v[4:5], s[34:35], 0, v[12:13]
	global_load_dwordx4 v[4:7], v[4:5], off
	v_lshl_add_u64 v[0:1], s[30:31], 0, v[12:13]
	global_load_dwordx4 v[0:3], v[0:1], off
	s_waitcnt lgkmcnt(0)
	v_lshlrev_b32_e32 v16, 16, v8
	v_and_b32_e32 v17, 0xffff0000, v8
	v_lshlrev_b32_e32 v8, 16, v9
	v_and_b32_e32 v9, 0xffff0000, v9
	s_waitcnt vmcnt(0)
	v_lshlrev_b32_e32 v14, 16, v0
	v_and_b32_e32 v15, 0xffff0000, v0
	v_pk_mul_f32 v[14:15], v[14:15], v[16:17]
	v_lshlrev_b32_e32 v16, 16, v4
	v_and_b32_e32 v17, 0xffff0000, v4
	v_pk_mul_f32 v[14:15], v[14:15], v[16:17]
	v_lshlrev_b32_e32 v4, 16, v5
	v_cvt_pk_bf16_f32 v0, v14, v15
	v_lshlrev_b32_e32 v14, 16, v1
	v_and_b32_e32 v15, 0xffff0000, v1
	v_pk_mul_f32 v[8:9], v[14:15], v[8:9]
	v_and_b32_e32 v5, 0xffff0000, v5
	v_pk_mul_f32 v[4:5], v[8:9], v[4:5]
	v_lshlrev_b32_e32 v8, 16, v10
	v_cvt_pk_bf16_f32 v1, v4, v5
	v_lshlrev_b32_e32 v4, 16, v2
	v_and_b32_e32 v5, 0xffff0000, v2
	v_and_b32_e32 v9, 0xffff0000, v10
	v_pk_mul_f32 v[4:5], v[4:5], v[8:9]
	v_lshlrev_b32_e32 v8, 16, v6
	v_and_b32_e32 v9, 0xffff0000, v6
	v_pk_mul_f32 v[4:5], v[4:5], v[8:9]
	v_lshlrev_b32_e32 v8, 16, v11
	v_cvt_pk_bf16_f32 v2, v4, v5
	v_lshlrev_b32_e32 v4, 16, v3
	v_and_b32_e32 v5, 0xffff0000, v3
	v_and_b32_e32 v9, 0xffff0000, v11
	v_pk_mul_f32 v[4:5], v[4:5], v[8:9]
	v_lshlrev_b32_e32 v6, 16, v7
	v_and_b32_e32 v7, 0xffff0000, v7
	v_pk_mul_f32 v[4:5], v[4:5], v[6:7]
	s_nop 0
	v_cvt_pk_bf16_f32 v3, v4, v5
	v_lshl_add_u64 v[4:5], s[36:37], 0, v[12:13]
	global_store_dwordx4 v[4:5], v[0:3], off
	s_cbranch_scc0 .LBB0_657
